# weight conversion tail: the 16 LDS reads of an item issued together (distinct registers) instead of one LDS round trip each
# speedup vs baseline: 1.0007x; 1.0007x over previous
.LBB0_25:
	v_or_b32_e32 v60, s9, v78
	v_mad_u64_u32 v[58:59], s[36:37], v60, s0, v[58:59]
	v_add_u32_e32 v63, 0x840, v62
	s_lshl_b32 s11, s11, 5
	v_add_u32_e32 v62, 0x848, v62
	s_lshl_b32 s14, s9, 1
	s_and_b32 s9, 0xffff, s11
	s_lshl_b32 s11, s9, 1
	s_and_b32 s9, s9, 0x60
	s_and_b32 s11, s11, 0x1f00
	s_or_b32 s9, s11, s9
	s_waitcnt vmcnt(0)
	v_pk_mul_f32 v[58:59], v[236:237], v[4:5] op_sel_hi:[1,0]
	v_pk_mul_f32 v[60:61], v[238:239], v[4:5] op_sel_hi:[1,0]
	ds_write2_b32 v63, v58, v59 offset1:1
	ds_write2_b32 v62, v60, v61 offset1:1
	s_waitcnt lgkmcnt(0)
	ds_read2_b32 v[212:213], v79 offset1:33
	ds_read2_b32 v[214:215], v79 offset0:66 offset1:99
	ds_read2_b32 v[216:217], v79 offset0:132 offset1:165
	ds_read2_b32 v[218:219], v79 offset0:198 offset1:231
	ds_read2_b32 v[220:221], v79 offset0:8 offset1:41
	ds_read2_b32 v[222:223], v79 offset0:74 offset1:107
	ds_read2_b32 v[224:225], v79 offset0:140 offset1:173
	ds_read2_b32 v[226:227], v79 offset0:206 offset1:239
	ds_read2_b32 v[228:229], v79 offset0:16 offset1:49
	ds_read2_b32 v[230:231], v79 offset0:82 offset1:115
	ds_read2_b32 v[232:233], v79 offset0:148 offset1:181
	ds_read2_b32 v[234:235], v79 offset0:214 offset1:247
	ds_read2_b32 v[236:237], v79 offset0:24 offset1:57
	ds_read2_b32 v[238:239], v79 offset0:90 offset1:123
	ds_read2_b32 v[240:241], v79 offset0:156 offset1:189
	ds_read2_b32 v[242:243], v79 offset0:222 offset1:255
	s_waitcnt lgkmcnt(0)
	v_cvt_pk_bf16_f32 v58, v212, v213
	v_or_b32_e32 v4, s9, v65
	s_waitcnt lgkmcnt(0)
	v_cvt_pk_bf16_f32 v59, v214, v215
	v_lshl_add_u64 v[62:63], v[44:45], 0, s[14:15]
	v_lshlrev_b32_e32 v4, 11, v4
	s_waitcnt lgkmcnt(0)
	v_cvt_pk_bf16_f32 v60, v216, v217
	s_waitcnt lgkmcnt(0)
	v_cvt_pk_bf16_f32 v61, v218, v219
	v_lshl_add_u64 v[86:87], v[62:63], 0, v[4:5]
	global_store_dwordx4 v[86:87], v[58:61], off
	v_or_b32_e32 v4, s9, v67
	v_lshlrev_b32_e32 v4, 11, v4
	s_waitcnt lgkmcnt(0)
	v_cvt_pk_bf16_f32 v58, v220, v221
	s_waitcnt lgkmcnt(0)
	v_cvt_pk_bf16_f32 v59, v222, v223
	s_waitcnt lgkmcnt(0)
	v_cvt_pk_bf16_f32 v60, v224, v225
	s_waitcnt lgkmcnt(0)
	v_cvt_pk_bf16_f32 v61, v226, v227
	v_lshl_add_u64 v[86:87], v[62:63], 0, v[4:5]
	global_store_dwordx4 v[86:87], v[58:61], off
	v_or_b32_e32 v4, s9, v69
	v_lshlrev_b32_e32 v4, 11, v4
	s_waitcnt lgkmcnt(0)
	v_cvt_pk_bf16_f32 v58, v228, v229
	s_waitcnt lgkmcnt(0)
	v_cvt_pk_bf16_f32 v59, v230, v231
	s_waitcnt lgkmcnt(0)
	v_cvt_pk_bf16_f32 v60, v232, v233
	s_waitcnt lgkmcnt(0)
	v_cvt_pk_bf16_f32 v61, v234, v235
	v_lshl_add_u64 v[86:87], v[62:63], 0, v[4:5]
	v_or_b32_e32 v4, s9, v71
	global_store_dwordx4 v[86:87], v[58:61], off
	v_lshlrev_b32_e32 v4, 11, v4
	v_lshl_add_u64 v[62:63], v[62:63], 0, v[4:5]
	s_waitcnt lgkmcnt(0)
	v_cvt_pk_bf16_f32 v58, v236, v237
	s_waitcnt lgkmcnt(0)
	v_cvt_pk_bf16_f32 v59, v238, v239
	s_waitcnt lgkmcnt(0)
	v_cvt_pk_bf16_f32 v60, v240, v241
	s_waitcnt lgkmcnt(0)
	v_cvt_pk_bf16_f32 v61, v242, v243
	global_store_dwordx4 v[62:63], v[58:61], off
	s_waitcnt lgkmcnt(0)
	s_add_i32 s11, s3, 0xfffffa80
	s_cmpk_gt_u32 s11, 0x57f
	s_cbranch_scc0 .LBB0_44

.LBB0_27:
	s_load_dwordx2 s[36:37], s[16:17], 0x20
	s_lshl_b32 s4, s4, 1
	s_and_b32 s5, s4, 0xfc0
	s_lshl_b32 s4, s3, 5
	s_and_b32 s4, s4, 0x3e0
	s_lshl_b32 s9, s4, 2
	s_waitcnt lgkmcnt(0)
	s_add_u32 s36, s36, s9
	s_addc_u32 s37, s37, 0
	v_lshlrev_b32_e32 v4, 2, v2
	v_lshl_add_u64 v[62:63], s[36:37], 0, v[4:5]
	v_or_b32_e32 v4, s5, v65
	v_lshlrev_b32_e32 v4, 12, v4
	v_lshl_add_u64 v[58:59], v[62:63], 0, v[4:5]
	v_or_b32_e32 v4, s5, v67
	v_lshlrev_b32_e32 v4, 12, v4
	v_lshl_add_u64 v[84:85], v[62:63], 0, v[4:5]
	v_or_b32_e32 v4, s5, v69
	v_lshlrev_b32_e32 v4, 12, v4
	v_lshl_add_u64 v[96:97], v[62:63], 0, v[4:5]
	v_or_b32_e32 v4, s5, v71
	v_lshlrev_b32_e32 v4, 12, v4
	v_lshl_add_u64 v[98:99], v[62:63], 0, v[4:5]
	v_or_b32_e32 v4, s5, v73
	v_lshlrev_b32_e32 v4, 12, v4
	v_lshl_add_u64 v[104:105], v[62:63], 0, v[4:5]
	v_or_b32_e32 v4, s5, v75
	v_lshlrev_b32_e32 v4, 12, v4
	global_load_dwordx4 v[58:61], v[58:59], off
	s_nop 0
	global_load_dwordx4 v[84:87], v[84:85], off
	s_nop 0
	global_load_dwordx4 v[88:91], v[96:97], off
	global_load_dwordx4 v[92:95], v[98:99], off
	v_lshl_add_u64 v[106:107], v[62:63], 0, v[4:5]
	global_load_dwordx4 v[96:99], v[104:105], off
	global_load_dwordx4 v[100:103], v[106:107], off
	v_or_b32_e32 v4, s5, v77
	v_lshlrev_b32_e32 v4, 12, v4
	v_lshl_add_u64 v[104:105], v[62:63], 0, v[4:5]
	v_or_b32_e32 v4, s5, v78
	global_load_dwordx4 v[104:107], v[104:105], off
	v_lshlrev_b32_e32 v4, 12, v4
	v_lshl_add_u64 v[62:63], v[62:63], 0, v[4:5]
	global_load_dwordx4 v[108:111], v[62:63], off
	v_add_u32_e32 v4, v66, v81
	v_add_u32_e32 v62, v66, v76
	v_add_u32_e32 v63, 0x420, v4
	v_add_u32_e32 v83, 0x428, v4
	v_add_u32_e32 v112, 0x840, v4
	v_add_u32_e32 v113, 0x848, v4
	v_add_u32_e32 v114, 0xc60, v4
	v_add_u32_e32 v115, 0xc68, v4
	v_add_u32_e32 v116, 0x1080, v4
	v_add_u32_e32 v117, 0x1088, v4
	v_add_u32_e32 v118, 0x14a0, v4
	v_add_u32_e32 v119, 0x420, v62
	v_add_u32_e32 v120, 0x428, v62
	v_add_u32_e32 v121, 0x840, v62
	v_add_u32_e32 v122, 0x848, v62
	s_lshl_b32 s14, s5, 1
	s_waitcnt vmcnt(7)
	ds_write2_b32 v4, v58, v59 offset1:1
	ds_write2_b32 v4, v60, v61 offset0:2 offset1:3
	s_waitcnt vmcnt(6)
	ds_write2_b32 v63, v84, v85 offset1:1
	ds_write2_b32 v83, v86, v87 offset1:1
	s_waitcnt vmcnt(5)
	ds_write2_b32 v112, v88, v89 offset1:1
	ds_write2_b32 v113, v90, v91 offset1:1
	s_waitcnt vmcnt(4)
	ds_write2_b32 v114, v92, v93 offset1:1
	ds_write2_b32 v115, v94, v95 offset1:1
	s_waitcnt vmcnt(3)
	ds_write2_b32 v116, v96, v97 offset1:1
	ds_write2_b32 v117, v98, v99 offset1:1
	s_waitcnt vmcnt(2)
	ds_write2_b32 v118, v100, v101 offset1:1
	ds_write2_b32 v62, v102, v103 offset0:2 offset1:3
	s_waitcnt vmcnt(1)
	ds_write2_b32 v119, v104, v105 offset1:1
	ds_write2_b32 v120, v106, v107 offset1:1
	s_waitcnt vmcnt(0)
	ds_write2_b32 v121, v108, v109 offset1:1
	ds_write2_b32 v122, v110, v111 offset1:1
	s_waitcnt lgkmcnt(0)
	ds_read2_b32 v[212:213], v79 offset1:33
	ds_read2_b32 v[214:215], v79 offset0:66 offset1:99
	ds_read2_b32 v[216:217], v79 offset0:132 offset1:165
	ds_read2_b32 v[218:219], v79 offset0:198 offset1:231
	ds_read2_b32 v[220:221], v79 offset0:8 offset1:41
	ds_read2_b32 v[222:223], v79 offset0:74 offset1:107
	ds_read2_b32 v[224:225], v79 offset0:140 offset1:173
	ds_read2_b32 v[226:227], v79 offset0:206 offset1:239
	ds_read2_b32 v[228:229], v79 offset0:16 offset1:49
	ds_read2_b32 v[230:231], v79 offset0:82 offset1:115
	ds_read2_b32 v[232:233], v79 offset0:148 offset1:181
	ds_read2_b32 v[234:235], v79 offset0:214 offset1:247
	ds_read2_b32 v[236:237], v79 offset0:24 offset1:57
	ds_read2_b32 v[238:239], v79 offset0:90 offset1:123
	ds_read2_b32 v[240:241], v79 offset0:156 offset1:189
	ds_read2_b32 v[242:243], v79 offset0:222 offset1:255
	s_waitcnt lgkmcnt(0)
	v_cvt_pk_bf16_f32 v58, v212, v213
	v_or_b32_e32 v4, s4, v65
	s_waitcnt lgkmcnt(0)
	v_cvt_pk_bf16_f32 v59, v214, v215
	v_lshl_add_u64 v[84:85], v[46:47], 0, s[14:15]
	v_mul_u32_u24_e32 v4, 0x1600, v4
	s_waitcnt lgkmcnt(0)
	v_cvt_pk_bf16_f32 v60, v216, v217
	s_waitcnt lgkmcnt(0)
	v_cvt_pk_bf16_f32 v61, v218, v219
	v_lshl_add_u64 v[86:87], v[84:85], 0, v[4:5]
	global_store_dwordx4 v[86:87], v[58:61], off
	v_or_b32_e32 v4, s4, v67
	v_mul_u32_u24_e32 v4, 0x1600, v4
	s_waitcnt lgkmcnt(0)
	v_cvt_pk_bf16_f32 v58, v220, v221
	s_waitcnt lgkmcnt(0)
	v_cvt_pk_bf16_f32 v59, v222, v223
	s_waitcnt lgkmcnt(0)
	v_cvt_pk_bf16_f32 v60, v224, v225
	s_waitcnt lgkmcnt(0)
	v_cvt_pk_bf16_f32 v61, v226, v227
	v_lshl_add_u64 v[86:87], v[84:85], 0, v[4:5]
	global_store_dwordx4 v[86:87], v[58:61], off
	v_or_b32_e32 v4, s4, v69
	v_mul_u32_u24_e32 v4, 0x1600, v4
	s_waitcnt lgkmcnt(0)
	v_cvt_pk_bf16_f32 v58, v228, v229
	s_waitcnt lgkmcnt(0)
	v_cvt_pk_bf16_f32 v59, v230, v231
	s_waitcnt lgkmcnt(0)
	v_cvt_pk_bf16_f32 v60, v232, v233
	s_waitcnt lgkmcnt(0)
	v_cvt_pk_bf16_f32 v61, v234, v235
	v_lshl_add_u64 v[86:87], v[84:85], 0, v[4:5]
	global_store_dwordx4 v[86:87], v[58:61], off
	v_or_b32_e32 v4, s4, v71
	v_mul_u32_u24_e32 v4, 0x1600, v4
	s_waitcnt lgkmcnt(0)
	v_cvt_pk_bf16_f32 v58, v236, v237
	s_waitcnt lgkmcnt(0)
	v_cvt_pk_bf16_f32 v59, v238, v239
	s_waitcnt lgkmcnt(0)
	v_cvt_pk_bf16_f32 v60, v240, v241
	s_waitcnt lgkmcnt(0)
	v_cvt_pk_bf16_f32 v61, v242, v243
	v_lshl_add_u64 v[62:63], v[84:85], 0, v[4:5]
	global_store_dwordx4 v[62:63], v[58:61], off
	s_waitcnt lgkmcnt(0)

.LBB0_60:
	v_or_b32_e32 v60, s9, v78
	v_mad_u64_u32 v[58:59], s[4:5], v60, s0, v[58:59]
	s_lshl_b32 s4, s11, 5
	s_and_b32 s4, 0xffff, s4
	v_add_u32_e32 v63, 0x840, v62
	s_lshl_b32 s5, s4, 1
	v_add_u32_e32 v62, 0x848, v62
	s_and_b32 s4, s4, 0x60
	s_and_b32 s5, s5, 0x1f00
	s_or_b32 s4, s5, s4
	s_lshl_b32 s14, s9, 1
	s_waitcnt vmcnt(0)
	v_pk_mul_f32 v[58:59], v[236:237], v[4:5] op_sel_hi:[1,0]
	v_pk_mul_f32 v[60:61], v[238:239], v[4:5] op_sel_hi:[1,0]
	ds_write2_b32 v63, v58, v59 offset1:1
	ds_write2_b32 v62, v60, v61 offset1:1
	s_waitcnt lgkmcnt(0)
	v_or_b32_e32 v4, s4, v65
	ds_read2_b32 v[212:213], v79 offset1:33
	ds_read2_b32 v[214:215], v79 offset0:66 offset1:99
	ds_read2_b32 v[216:217], v79 offset0:132 offset1:165
	ds_read2_b32 v[218:219], v79 offset0:198 offset1:231
	ds_read2_b32 v[220:221], v79 offset0:8 offset1:41
	ds_read2_b32 v[222:223], v79 offset0:74 offset1:107
	ds_read2_b32 v[224:225], v79 offset0:140 offset1:173
	ds_read2_b32 v[226:227], v79 offset0:206 offset1:239
	ds_read2_b32 v[228:229], v79 offset0:16 offset1:49
	ds_read2_b32 v[230:231], v79 offset0:82 offset1:115
	ds_read2_b32 v[232:233], v79 offset0:148 offset1:181
	ds_read2_b32 v[234:235], v79 offset0:214 offset1:247
	ds_read2_b32 v[236:237], v79 offset0:24 offset1:57
	ds_read2_b32 v[238:239], v79 offset0:90 offset1:123
	ds_read2_b32 v[240:241], v79 offset0:156 offset1:189
	ds_read2_b32 v[242:243], v79 offset0:222 offset1:255
	v_lshl_add_u64 v[62:63], v[44:45], 0, s[14:15]
	v_lshlrev_b32_e32 v4, 11, v4
	s_waitcnt lgkmcnt(0)
	v_cvt_pk_bf16_f32 v58, v212, v213
	v_lshl_add_u64 v[86:87], v[62:63], 0, v[4:5]
	s_waitcnt lgkmcnt(0)
	v_cvt_pk_bf16_f32 v59, v214, v215
	v_add_co_u32_e32 v86, vcc, s1, v86
	v_or_b32_e32 v4, s4, v67
	s_waitcnt lgkmcnt(0)
	v_cvt_pk_bf16_f32 v60, v216, v217
	s_waitcnt lgkmcnt(0)
	v_cvt_pk_bf16_f32 v61, v218, v219
	v_addc_co_u32_e32 v87, vcc, 0, v87, vcc
	v_lshlrev_b32_e32 v4, 11, v4
	global_store_dwordx4 v[86:87], v[58:61], off
	v_lshl_add_u64 v[86:87], v[62:63], 0, v[4:5]
	v_add_co_u32_e32 v86, vcc, s1, v86
	s_waitcnt lgkmcnt(0)
	v_cvt_pk_bf16_f32 v58, v220, v221
	s_waitcnt lgkmcnt(0)
	v_cvt_pk_bf16_f32 v59, v222, v223
	v_or_b32_e32 v4, s4, v69
	s_waitcnt lgkmcnt(0)
	v_cvt_pk_bf16_f32 v60, v224, v225
	s_waitcnt lgkmcnt(0)
	v_cvt_pk_bf16_f32 v61, v226, v227
	v_addc_co_u32_e32 v87, vcc, 0, v87, vcc
	v_lshlrev_b32_e32 v4, 11, v4
	global_store_dwordx4 v[86:87], v[58:61], off
	v_lshl_add_u64 v[86:87], v[62:63], 0, v[4:5]
	v_or_b32_e32 v4, s4, v71
	s_waitcnt lgkmcnt(0)
	v_cvt_pk_bf16_f32 v58, v228, v229
	s_waitcnt lgkmcnt(0)
	v_cvt_pk_bf16_f32 v59, v230, v231
	v_add_co_u32_e32 v86, vcc, s1, v86
	v_lshlrev_b32_e32 v4, 11, v4
	s_waitcnt lgkmcnt(0)
	v_cvt_pk_bf16_f32 v60, v232, v233
	s_waitcnt lgkmcnt(0)
	v_cvt_pk_bf16_f32 v61, v234, v235
	v_addc_co_u32_e32 v87, vcc, 0, v87, vcc
	v_lshl_add_u64 v[62:63], v[62:63], 0, v[4:5]
	global_store_dwordx4 v[86:87], v[58:61], off
	v_add_co_u32_e32 v62, vcc, 0x40000, v62
	s_waitcnt lgkmcnt(0)
	v_cvt_pk_bf16_f32 v58, v236, v237
	s_waitcnt lgkmcnt(0)
	v_cvt_pk_bf16_f32 v59, v238, v239
	v_addc_co_u32_e32 v63, vcc, 0, v63, vcc
	s_waitcnt lgkmcnt(0)
	v_cvt_pk_bf16_f32 v60, v240, v241
	s_waitcnt lgkmcnt(0)
	v_cvt_pk_bf16_f32 v61, v242, v243
	global_store_dwordx4 v[62:63], v[58:61], off
	s_waitcnt lgkmcnt(0)
	s_add_i32 s4, s3, 0xfffff500
	s_cmpk_gt_u32 s4, 0x57f
	s_cbranch_scc0 .LBB0_27
	s_branch .LBB0_28

.LBB0_80:
	v_or_b32_e32 v4, s11, v78
	v_lshlrev_b32_e32 v62, 2, v4
	global_load_dword v62, v62, s[28:29]
	v_lshlrev_b32_e32 v4, 8, v4
	v_lshl_add_u64 v[58:59], v[58:59], 0, v[4:5]
	global_load_dwordx4 v[84:87], v[58:59], off
	v_add_u32_e32 v63, 0x840, v61
	v_add_u32_e32 v83, 0x848, v61
	s_and_b32 s33, 0xffff, s33
	s_lshl_b32 s14, s11, 1
	s_or_b32 s11, s33, 0x840
	s_waitcnt vmcnt(1)
	v_sub_f32_e32 v4, 1.0, v62
	v_mul_f32_e32 v4, v60, v4
	s_waitcnt vmcnt(0)
	v_pk_mul_f32 v[60:61], v[84:85], v[4:5] op_sel_hi:[1,0]
	v_pk_mul_f32 v[58:59], v[86:87], v[4:5] op_sel_hi:[1,0]
	ds_write2_b32 v63, v60, v61 offset1:1
	ds_write2_b32 v83, v58, v59 offset1:1
	s_waitcnt lgkmcnt(0)
	ds_read2_b32 v[212:213], v79 offset1:33
	ds_read2_b32 v[214:215], v79 offset0:66 offset1:99
	ds_read2_b32 v[216:217], v79 offset0:132 offset1:165
	ds_read2_b32 v[218:219], v79 offset0:198 offset1:231
	ds_read2_b32 v[220:221], v79 offset0:8 offset1:41
	ds_read2_b32 v[222:223], v79 offset0:74 offset1:107
	ds_read2_b32 v[224:225], v79 offset0:140 offset1:173
	ds_read2_b32 v[226:227], v79 offset0:206 offset1:239
	ds_read2_b32 v[228:229], v79 offset0:16 offset1:49
	ds_read2_b32 v[230:231], v79 offset0:82 offset1:115
	ds_read2_b32 v[232:233], v79 offset0:148 offset1:181
	ds_read2_b32 v[234:235], v79 offset0:214 offset1:247
	ds_read2_b32 v[236:237], v79 offset0:24 offset1:57
	ds_read2_b32 v[238:239], v79 offset0:90 offset1:123
	ds_read2_b32 v[240:241], v79 offset0:156 offset1:189
	ds_read2_b32 v[242:243], v79 offset0:222 offset1:255
	s_waitcnt lgkmcnt(0)
	v_cvt_pk_bf16_f32 v58, v212, v213
	v_or_b32_e32 v4, s11, v65
	s_waitcnt lgkmcnt(0)
	v_cvt_pk_bf16_f32 v59, v214, v215
	v_lshl_add_u64 v[84:85], v[48:49], 0, s[14:15]
	v_lshlrev_b32_e32 v4, 11, v4
	s_waitcnt lgkmcnt(0)
	v_cvt_pk_bf16_f32 v60, v216, v217
	s_waitcnt lgkmcnt(0)
	v_cvt_pk_bf16_f32 v61, v218, v219
	v_lshl_add_u64 v[86:87], v[84:85], 0, v[4:5]
	global_store_dwordx4 v[86:87], v[58:61], off
	v_or_b32_e32 v4, s11, v67
	v_lshlrev_b32_e32 v4, 11, v4
	s_waitcnt lgkmcnt(0)
	v_cvt_pk_bf16_f32 v58, v220, v221
	s_waitcnt lgkmcnt(0)
	v_cvt_pk_bf16_f32 v59, v222, v223
	s_waitcnt lgkmcnt(0)
	v_cvt_pk_bf16_f32 v60, v224, v225
	s_waitcnt lgkmcnt(0)
	v_cvt_pk_bf16_f32 v61, v226, v227
	v_lshl_add_u64 v[86:87], v[84:85], 0, v[4:5]
	global_store_dwordx4 v[86:87], v[58:61], off
	v_or_b32_e32 v4, s11, v69
	v_lshlrev_b32_e32 v4, 11, v4
	s_waitcnt lgkmcnt(0)
	v_cvt_pk_bf16_f32 v58, v228, v229
	s_waitcnt lgkmcnt(0)
	v_cvt_pk_bf16_f32 v59, v230, v231
	s_waitcnt lgkmcnt(0)
	v_cvt_pk_bf16_f32 v60, v232, v233
	s_waitcnt lgkmcnt(0)
	v_cvt_pk_bf16_f32 v61, v234, v235
	v_lshl_add_u64 v[86:87], v[84:85], 0, v[4:5]
	global_store_dwordx4 v[86:87], v[58:61], off
	v_or_b32_e32 v4, s11, v71
	v_lshlrev_b32_e32 v4, 11, v4
	s_waitcnt lgkmcnt(0)
	v_cvt_pk_bf16_f32 v58, v236, v237
	s_waitcnt lgkmcnt(0)
	v_cvt_pk_bf16_f32 v59, v238, v239
	s_waitcnt lgkmcnt(0)
	v_cvt_pk_bf16_f32 v60, v240, v241
	s_waitcnt lgkmcnt(0)
	v_cvt_pk_bf16_f32 v61, v242, v243
	v_lshl_add_u64 v[62:63], v[84:85], 0, v[4:5]
	global_store_dwordx4 v[62:63], v[58:61], off
	s_waitcnt lgkmcnt(0)

.LBB0_86:
	v_or_b32_e32 v60, s9, v78
	v_mad_u64_u32 v[58:59], s[36:37], v60, s2, v[58:59]
	global_load_dwordx4 v[58:61], v[58:59], off
	v_add_u32_e32 v63, 0x840, v62
	v_add_u32_e32 v62, 0x848, v62
	s_and_b32 s11, 0xffff, s11
	s_lshl_b32 s14, s9, 1
	v_lshl_add_u64 v[84:85], v[48:49], 0, s[14:15]
	s_waitcnt vmcnt(0)
	v_pk_mul_f32 v[58:59], v[58:59], v[4:5] op_sel_hi:[1,0]
	v_pk_mul_f32 v[60:61], v[60:61], v[4:5] op_sel_hi:[1,0]
	ds_write2_b32 v63, v58, v59 offset1:1
	ds_write2_b32 v62, v60, v61 offset1:1
	s_waitcnt lgkmcnt(0)
	ds_read2_b32 v[212:213], v79 offset1:33
	ds_read2_b32 v[214:215], v79 offset0:66 offset1:99
	ds_read2_b32 v[216:217], v79 offset0:132 offset1:165
	ds_read2_b32 v[218:219], v79 offset0:198 offset1:231
	ds_read2_b32 v[220:221], v79 offset0:8 offset1:41
	ds_read2_b32 v[222:223], v79 offset0:74 offset1:107
	ds_read2_b32 v[224:225], v79 offset0:140 offset1:173
	ds_read2_b32 v[226:227], v79 offset0:206 offset1:239
	ds_read2_b32 v[228:229], v79 offset0:16 offset1:49
	ds_read2_b32 v[230:231], v79 offset0:82 offset1:115
	ds_read2_b32 v[232:233], v79 offset0:148 offset1:181
	ds_read2_b32 v[234:235], v79 offset0:214 offset1:247
	ds_read2_b32 v[236:237], v79 offset0:24 offset1:57
	ds_read2_b32 v[238:239], v79 offset0:90 offset1:123
	ds_read2_b32 v[240:241], v79 offset0:156 offset1:189
	ds_read2_b32 v[242:243], v79 offset0:222 offset1:255
	s_waitcnt lgkmcnt(0)
	v_cvt_pk_bf16_f32 v58, v212, v213
	v_or_b32_e32 v4, s11, v65
	s_waitcnt lgkmcnt(0)
	v_cvt_pk_bf16_f32 v59, v214, v215
	v_lshlrev_b32_e32 v4, 11, v4
	s_waitcnt lgkmcnt(0)
	v_cvt_pk_bf16_f32 v60, v216, v217
	s_waitcnt lgkmcnt(0)
	v_cvt_pk_bf16_f32 v61, v218, v219
	v_lshl_add_u64 v[86:87], v[84:85], 0, v[4:5]
	global_store_dwordx4 v[86:87], v[58:61], off
	v_or_b32_e32 v4, s11, v67
	v_lshlrev_b32_e32 v4, 11, v4
	s_waitcnt lgkmcnt(0)
	v_cvt_pk_bf16_f32 v58, v220, v221
	s_waitcnt lgkmcnt(0)
	v_cvt_pk_bf16_f32 v59, v222, v223
	s_waitcnt lgkmcnt(0)
	v_cvt_pk_bf16_f32 v60, v224, v225
	s_waitcnt lgkmcnt(0)
	v_cvt_pk_bf16_f32 v61, v226, v227
	v_lshl_add_u64 v[86:87], v[84:85], 0, v[4:5]
	global_store_dwordx4 v[86:87], v[58:61], off
	v_or_b32_e32 v4, s11, v69
	v_lshlrev_b32_e32 v4, 11, v4
	s_waitcnt lgkmcnt(0)
	v_cvt_pk_bf16_f32 v58, v228, v229
	s_waitcnt lgkmcnt(0)
	v_cvt_pk_bf16_f32 v59, v230, v231
	s_waitcnt lgkmcnt(0)
	v_cvt_pk_bf16_f32 v60, v232, v233
	s_waitcnt lgkmcnt(0)
	v_cvt_pk_bf16_f32 v61, v234, v235
	v_lshl_add_u64 v[86:87], v[84:85], 0, v[4:5]
	global_store_dwordx4 v[86:87], v[58:61], off
	v_or_b32_e32 v4, s11, v71
	v_lshlrev_b32_e32 v4, 11, v4
	s_waitcnt lgkmcnt(0)
	v_cvt_pk_bf16_f32 v58, v236, v237
	s_waitcnt lgkmcnt(0)
	v_cvt_pk_bf16_f32 v59, v238, v239
	s_waitcnt lgkmcnt(0)
	v_cvt_pk_bf16_f32 v60, v240, v241
	s_waitcnt lgkmcnt(0)
	v_cvt_pk_bf16_f32 v61, v242, v243
	v_lshl_add_u64 v[62:63], v[84:85], 0, v[4:5]
	global_store_dwordx4 v[62:63], v[58:61], off
	s_waitcnt lgkmcnt(0)
	s_and_b32 s9, s3, 0xffffffe0
	s_cmpk_lt_i32 s9, 0x14a0
	s_mov_b64 s[46:47], -1
	s_cbranch_scc0 .LBB0_62

.LBB0_109:
	v_or_b32_e32 v4, s14, v78
	global_load_dword v62, v[60:61], off offset:224
	v_lshlrev_b32_e32 v4, 8, v4
	v_lshl_add_u64 v[58:59], v[58:59], 0, v[4:5]
	global_load_dwordx4 v[58:61], v[58:59], off
	v_add_u32_e32 v63, 0x840, v85
	v_add_u32_e32 v84, 0x848, v85
	s_and_b32 s11, 0xffff, s11
	s_bitset1_b32 s11, 11
	s_lshl_b32 s14, s14, 1
	s_waitcnt vmcnt(1)
	v_sub_f32_e32 v4, 1.0, v62
	v_mul_f32_e32 v4, v83, v4
	s_waitcnt vmcnt(0)
	v_pk_mul_f32 v[58:59], v[58:59], v[4:5] op_sel_hi:[1,0]
	v_pk_mul_f32 v[60:61], v[60:61], v[4:5] op_sel_hi:[1,0]
	ds_write2_b32 v63, v58, v59 offset1:1
	ds_write2_b32 v84, v60, v61 offset1:1
	s_waitcnt lgkmcnt(0)
	ds_read2_b32 v[212:213], v79 offset1:33
	ds_read2_b32 v[214:215], v79 offset0:66 offset1:99
	ds_read2_b32 v[216:217], v79 offset0:132 offset1:165
	ds_read2_b32 v[218:219], v79 offset0:198 offset1:231
	ds_read2_b32 v[220:221], v79 offset0:8 offset1:41
	ds_read2_b32 v[222:223], v79 offset0:74 offset1:107
	ds_read2_b32 v[224:225], v79 offset0:140 offset1:173
	ds_read2_b32 v[226:227], v79 offset0:206 offset1:239
	ds_read2_b32 v[228:229], v79 offset0:16 offset1:49
	ds_read2_b32 v[230:231], v79 offset0:82 offset1:115
	ds_read2_b32 v[232:233], v79 offset0:148 offset1:181
	ds_read2_b32 v[234:235], v79 offset0:214 offset1:247
	ds_read2_b32 v[236:237], v79 offset0:24 offset1:57
	ds_read2_b32 v[238:239], v79 offset0:90 offset1:123
	ds_read2_b32 v[240:241], v79 offset0:156 offset1:189
	ds_read2_b32 v[242:243], v79 offset0:222 offset1:255
	s_waitcnt lgkmcnt(0)
	v_cvt_pk_bf16_f32 v58, v212, v213
	v_or_b32_e32 v4, s11, v65
	s_waitcnt lgkmcnt(0)
	v_cvt_pk_bf16_f32 v59, v214, v215
	v_lshl_add_u64 v[84:85], v[48:49], 0, s[14:15]
	v_lshlrev_b32_e32 v4, 11, v4
	s_waitcnt lgkmcnt(0)
	v_cvt_pk_bf16_f32 v60, v216, v217
	s_waitcnt lgkmcnt(0)
	v_cvt_pk_bf16_f32 v61, v218, v219
	v_lshl_add_u64 v[86:87], v[84:85], 0, v[4:5]
	global_store_dwordx4 v[86:87], v[58:61], off
	v_or_b32_e32 v4, s11, v67
	v_lshlrev_b32_e32 v4, 11, v4
	s_waitcnt lgkmcnt(0)
	v_cvt_pk_bf16_f32 v58, v220, v221
	s_waitcnt lgkmcnt(0)
	v_cvt_pk_bf16_f32 v59, v222, v223
	s_waitcnt lgkmcnt(0)
	v_cvt_pk_bf16_f32 v60, v224, v225
	s_waitcnt lgkmcnt(0)
	v_cvt_pk_bf16_f32 v61, v226, v227
	v_lshl_add_u64 v[86:87], v[84:85], 0, v[4:5]
	global_store_dwordx4 v[86:87], v[58:61], off
	v_or_b32_e32 v4, s11, v69
	v_lshlrev_b32_e32 v4, 11, v4
	s_waitcnt lgkmcnt(0)
	v_cvt_pk_bf16_f32 v58, v228, v229
	s_waitcnt lgkmcnt(0)
	v_cvt_pk_bf16_f32 v59, v230, v231
	s_waitcnt lgkmcnt(0)
	v_cvt_pk_bf16_f32 v60, v232, v233
	s_waitcnt lgkmcnt(0)
	v_cvt_pk_bf16_f32 v61, v234, v235
	v_lshl_add_u64 v[86:87], v[84:85], 0, v[4:5]
	global_store_dwordx4 v[86:87], v[58:61], off
	v_or_b32_e32 v4, s11, v71
	v_lshlrev_b32_e32 v4, 11, v4
	s_waitcnt lgkmcnt(0)
	v_cvt_pk_bf16_f32 v58, v236, v237
	s_waitcnt lgkmcnt(0)
	v_cvt_pk_bf16_f32 v59, v238, v239
	s_waitcnt lgkmcnt(0)
	v_cvt_pk_bf16_f32 v60, v240, v241
	s_waitcnt lgkmcnt(0)
	v_cvt_pk_bf16_f32 v61, v242, v243
	v_lshl_add_u64 v[62:63], v[84:85], 0, v[4:5]
	global_store_dwordx4 v[62:63], v[58:61], off
	s_waitcnt lgkmcnt(0)

.LBB0_128:
	v_or_b32_e32 v4, s33, v78
	v_lshlrev_b32_e32 v62, 2, v4
	global_load_dword v62, v62, s[30:31]
	v_lshlrev_b32_e32 v4, 9, v4
	v_lshl_add_u64 v[58:59], v[58:59], 0, v[4:5]
	global_load_dwordx4 v[84:87], v[58:59], off
	v_add_u32_e32 v63, 0x840, v61
	v_add_u32_e32 v83, 0x848, v61
	s_lshl_b32 s36, s3, 5
	s_lshl_b32 s14, s33, 1
	s_or_b32 s33, s36, 0x880
	s_waitcnt vmcnt(1)
	v_sub_f32_e32 v4, 1.0, v62
	v_mul_f32_e32 v4, v60, v4
	s_waitcnt vmcnt(0)
	v_pk_mul_f32 v[60:61], v[84:85], v[4:5] op_sel_hi:[1,0]
	v_pk_mul_f32 v[58:59], v[86:87], v[4:5] op_sel_hi:[1,0]
	ds_write2_b32 v63, v60, v61 offset1:1
	ds_write2_b32 v83, v58, v59 offset1:1
	s_waitcnt lgkmcnt(0)
	ds_read2_b32 v[212:213], v79 offset1:33
	ds_read2_b32 v[214:215], v79 offset0:66 offset1:99
	ds_read2_b32 v[216:217], v79 offset0:132 offset1:165
	ds_read2_b32 v[218:219], v79 offset0:198 offset1:231
	ds_read2_b32 v[220:221], v79 offset0:8 offset1:41
	ds_read2_b32 v[222:223], v79 offset0:74 offset1:107
	ds_read2_b32 v[224:225], v79 offset0:140 offset1:173
	ds_read2_b32 v[226:227], v79 offset0:206 offset1:239
	ds_read2_b32 v[228:229], v79 offset0:16 offset1:49
	ds_read2_b32 v[230:231], v79 offset0:82 offset1:115
	ds_read2_b32 v[232:233], v79 offset0:148 offset1:181
	ds_read2_b32 v[234:235], v79 offset0:214 offset1:247
	ds_read2_b32 v[236:237], v79 offset0:24 offset1:57
	ds_read2_b32 v[238:239], v79 offset0:90 offset1:123
	ds_read2_b32 v[240:241], v79 offset0:156 offset1:189
	ds_read2_b32 v[242:243], v79 offset0:222 offset1:255
	v_lshl_add_u64 v[84:85], v[48:49], 0, s[14:15]
	s_and_b32 s14, s33, 0x8ff
	s_waitcnt lgkmcnt(0)
	v_cvt_pk_bf16_f32 v58, v212, v213
	v_or_b32_e32 v4, s14, v65
	s_waitcnt lgkmcnt(0)
	v_cvt_pk_bf16_f32 v59, v214, v215
	v_lshlrev_b32_e32 v4, 11, v4
	s_waitcnt lgkmcnt(0)
	v_cvt_pk_bf16_f32 v60, v216, v217
	s_waitcnt lgkmcnt(0)
	v_cvt_pk_bf16_f32 v61, v218, v219
	v_lshl_add_u64 v[86:87], v[84:85], 0, v[4:5]
	global_store_dwordx4 v[86:87], v[58:61], off
	v_or_b32_e32 v4, s14, v67
	v_lshlrev_b32_e32 v4, 11, v4
	s_waitcnt lgkmcnt(0)
	v_cvt_pk_bf16_f32 v58, v220, v221
	s_waitcnt lgkmcnt(0)
	v_cvt_pk_bf16_f32 v59, v222, v223
	s_waitcnt lgkmcnt(0)
	v_cvt_pk_bf16_f32 v60, v224, v225
	s_waitcnt lgkmcnt(0)
	v_cvt_pk_bf16_f32 v61, v226, v227
	v_lshl_add_u64 v[86:87], v[84:85], 0, v[4:5]
	global_store_dwordx4 v[86:87], v[58:61], off
	v_or_b32_e32 v4, s14, v69
	v_lshlrev_b32_e32 v4, 11, v4
	s_waitcnt lgkmcnt(0)
	v_cvt_pk_bf16_f32 v58, v228, v229
	s_waitcnt lgkmcnt(0)
	v_cvt_pk_bf16_f32 v59, v230, v231
	s_waitcnt lgkmcnt(0)
	v_cvt_pk_bf16_f32 v60, v232, v233
	s_waitcnt lgkmcnt(0)
	v_cvt_pk_bf16_f32 v61, v234, v235
	v_lshl_add_u64 v[86:87], v[84:85], 0, v[4:5]
	global_store_dwordx4 v[86:87], v[58:61], off
	v_or_b32_e32 v4, s14, v71
	v_lshlrev_b32_e32 v4, 11, v4
	s_waitcnt lgkmcnt(0)
	v_cvt_pk_bf16_f32 v58, v236, v237
	s_waitcnt lgkmcnt(0)
	v_cvt_pk_bf16_f32 v59, v238, v239
	s_waitcnt lgkmcnt(0)
	v_cvt_pk_bf16_f32 v60, v240, v241
	s_waitcnt lgkmcnt(0)
	v_cvt_pk_bf16_f32 v61, v242, v243
	v_lshl_add_u64 v[62:63], v[84:85], 0, v[4:5]
	global_store_dwordx4 v[62:63], v[58:61], off
	s_waitcnt lgkmcnt(0)
	s_cmpk_lt_i32 s9, 0x1520
	s_mov_b64 s[46:47], -1
	s_cbranch_scc0 .LBB0_131

.LBB0_152:
	v_or_b32_e32 v4, s33, v78
	v_lshlrev_b32_e32 v62, 2, v4
	v_lshlrev_b32_e32 v4, 8, v4
	global_load_dword v62, v62, s[28:29]
	v_lshl_add_u64 v[58:59], v[58:59], 0, v[4:5]
	global_load_dwordx4 v[84:87], v[58:59], off
	v_add_u32_e32 v63, 0x840, v61
	v_add_u32_e32 v83, 0x848, v61
	s_and_b32 s36, 0xffff, s36
	s_lshl_b32 s14, s33, 1
	s_waitcnt vmcnt(1)
	v_mul_f32_e32 v4, v60, v62
	s_waitcnt vmcnt(0)
	v_pk_mul_f32 v[60:61], v[84:85], v[4:5] op_sel_hi:[1,0]
	v_pk_mul_f32 v[58:59], v[86:87], v[4:5] op_sel_hi:[1,0]
	ds_write2_b32 v63, v60, v61 offset1:1
	ds_write2_b32 v83, v58, v59 offset1:1
	s_waitcnt lgkmcnt(0)
	ds_read2_b32 v[212:213], v79 offset1:33
	ds_read2_b32 v[214:215], v79 offset0:66 offset1:99
	ds_read2_b32 v[216:217], v79 offset0:132 offset1:165
	ds_read2_b32 v[218:219], v79 offset0:198 offset1:231
	ds_read2_b32 v[220:221], v79 offset0:8 offset1:41
	ds_read2_b32 v[222:223], v79 offset0:74 offset1:107
	ds_read2_b32 v[224:225], v79 offset0:140 offset1:173
	ds_read2_b32 v[226:227], v79 offset0:206 offset1:239
	ds_read2_b32 v[228:229], v79 offset0:16 offset1:49
	ds_read2_b32 v[230:231], v79 offset0:82 offset1:115
	ds_read2_b32 v[232:233], v79 offset0:148 offset1:181
	ds_read2_b32 v[234:235], v79 offset0:214 offset1:247
	ds_read2_b32 v[236:237], v79 offset0:24 offset1:57
	ds_read2_b32 v[238:239], v79 offset0:90 offset1:123
	ds_read2_b32 v[240:241], v79 offset0:156 offset1:189
	ds_read2_b32 v[242:243], v79 offset0:222 offset1:255
	v_lshl_add_u64 v[84:85], v[48:49], 0, s[14:15]
	s_or_b32 s14, s36, 0x940
	s_waitcnt lgkmcnt(0)
	v_cvt_pk_bf16_f32 v58, v212, v213
	v_or_b32_e32 v4, s14, v65
	s_waitcnt lgkmcnt(0)
	v_cvt_pk_bf16_f32 v59, v214, v215
	v_lshlrev_b32_e32 v4, 11, v4
	s_waitcnt lgkmcnt(0)
	v_cvt_pk_bf16_f32 v60, v216, v217
	s_waitcnt lgkmcnt(0)
	v_cvt_pk_bf16_f32 v61, v218, v219
	v_lshl_add_u64 v[86:87], v[84:85], 0, v[4:5]
	global_store_dwordx4 v[86:87], v[58:61], off
	v_or_b32_e32 v4, s14, v67
	v_lshlrev_b32_e32 v4, 11, v4
	s_waitcnt lgkmcnt(0)
	v_cvt_pk_bf16_f32 v58, v220, v221
	s_waitcnt lgkmcnt(0)
	v_cvt_pk_bf16_f32 v59, v222, v223
	s_waitcnt lgkmcnt(0)
	v_cvt_pk_bf16_f32 v60, v224, v225
	s_waitcnt lgkmcnt(0)
	v_cvt_pk_bf16_f32 v61, v226, v227
	v_lshl_add_u64 v[86:87], v[84:85], 0, v[4:5]
	global_store_dwordx4 v[86:87], v[58:61], off
	v_or_b32_e32 v4, s14, v69
	v_lshlrev_b32_e32 v4, 11, v4
	s_waitcnt lgkmcnt(0)
	v_cvt_pk_bf16_f32 v58, v228, v229
	s_waitcnt lgkmcnt(0)
	v_cvt_pk_bf16_f32 v59, v230, v231
	s_waitcnt lgkmcnt(0)
	v_cvt_pk_bf16_f32 v60, v232, v233
	s_waitcnt lgkmcnt(0)
	v_cvt_pk_bf16_f32 v61, v234, v235
	v_lshl_add_u64 v[86:87], v[84:85], 0, v[4:5]
	global_store_dwordx4 v[86:87], v[58:61], off
	v_or_b32_e32 v4, s14, v71
	v_lshlrev_b32_e32 v4, 11, v4
	s_waitcnt lgkmcnt(0)
	v_cvt_pk_bf16_f32 v58, v236, v237
	s_waitcnt lgkmcnt(0)
	v_cvt_pk_bf16_f32 v59, v238, v239
	s_waitcnt lgkmcnt(0)
	v_cvt_pk_bf16_f32 v60, v240, v241
	s_waitcnt lgkmcnt(0)
	v_cvt_pk_bf16_f32 v61, v242, v243
	v_lshl_add_u64 v[62:63], v[84:85], 0, v[4:5]
	global_store_dwordx4 v[62:63], v[58:61], off
	s_waitcnt lgkmcnt(0)

.LBB0_174:
	v_or_b32_e32 v4, s9, v78
	v_lshlrev_b32_e32 v4, 8, v4
	global_load_dword v62, v[60:61], off offset:224
	v_lshl_add_u64 v[58:59], v[58:59], 0, v[4:5]
	global_load_dwordx4 v[58:61], v[58:59], off
	v_add_u32_e32 v63, 0x840, v83
	v_add_u32_e32 v83, 0x848, v83
	s_and_b32 s33, 0xffff, s33
	s_lshl_b32 s14, s9, 1
	s_or_b32 s9, s33, 0x900
	s_waitcnt vmcnt(1)
	v_mul_f32_e32 v4, v85, v62
	v_lshl_add_u64 v[84:85], v[48:49], 0, s[14:15]
	s_waitcnt vmcnt(0)
	v_pk_mul_f32 v[58:59], v[58:59], v[4:5] op_sel_hi:[1,0]
	v_pk_mul_f32 v[60:61], v[60:61], v[4:5] op_sel_hi:[1,0]
	ds_write2_b32 v63, v58, v59 offset1:1
	ds_write2_b32 v83, v60, v61 offset1:1
	s_waitcnt lgkmcnt(0)
	ds_read2_b32 v[212:213], v79 offset1:33
	ds_read2_b32 v[214:215], v79 offset0:66 offset1:99
	ds_read2_b32 v[216:217], v79 offset0:132 offset1:165
	ds_read2_b32 v[218:219], v79 offset0:198 offset1:231
	ds_read2_b32 v[220:221], v79 offset0:8 offset1:41
	ds_read2_b32 v[222:223], v79 offset0:74 offset1:107
	ds_read2_b32 v[224:225], v79 offset0:140 offset1:173
	ds_read2_b32 v[226:227], v79 offset0:206 offset1:239
	ds_read2_b32 v[228:229], v79 offset0:16 offset1:49
	ds_read2_b32 v[230:231], v79 offset0:82 offset1:115
	ds_read2_b32 v[232:233], v79 offset0:148 offset1:181
	ds_read2_b32 v[234:235], v79 offset0:214 offset1:247
	ds_read2_b32 v[236:237], v79 offset0:24 offset1:57
	ds_read2_b32 v[238:239], v79 offset0:90 offset1:123
	ds_read2_b32 v[240:241], v79 offset0:156 offset1:189
	ds_read2_b32 v[242:243], v79 offset0:222 offset1:255
	s_waitcnt lgkmcnt(0)
	v_cvt_pk_bf16_f32 v58, v212, v213
	v_or_b32_e32 v4, s9, v65
	s_waitcnt lgkmcnt(0)
	v_cvt_pk_bf16_f32 v59, v214, v215
	v_lshlrev_b32_e32 v4, 11, v4
	s_waitcnt lgkmcnt(0)
	v_cvt_pk_bf16_f32 v60, v216, v217
	s_waitcnt lgkmcnt(0)
	v_cvt_pk_bf16_f32 v61, v218, v219
	v_lshl_add_u64 v[86:87], v[84:85], 0, v[4:5]
	global_store_dwordx4 v[86:87], v[58:61], off
	v_or_b32_e32 v4, s9, v67
	v_lshlrev_b32_e32 v4, 11, v4
	s_waitcnt lgkmcnt(0)
	v_cvt_pk_bf16_f32 v58, v220, v221
	s_waitcnt lgkmcnt(0)
	v_cvt_pk_bf16_f32 v59, v222, v223
	s_waitcnt lgkmcnt(0)
	v_cvt_pk_bf16_f32 v60, v224, v225
	s_waitcnt lgkmcnt(0)
	v_cvt_pk_bf16_f32 v61, v226, v227
	v_lshl_add_u64 v[86:87], v[84:85], 0, v[4:5]
	global_store_dwordx4 v[86:87], v[58:61], off
	v_or_b32_e32 v4, s9, v69
	v_lshlrev_b32_e32 v4, 11, v4
	s_waitcnt lgkmcnt(0)
	v_cvt_pk_bf16_f32 v58, v228, v229
	s_waitcnt lgkmcnt(0)
	v_cvt_pk_bf16_f32 v59, v230, v231
	s_waitcnt lgkmcnt(0)
	v_cvt_pk_bf16_f32 v60, v232, v233
	s_waitcnt lgkmcnt(0)
	v_cvt_pk_bf16_f32 v61, v234, v235
	v_lshl_add_u64 v[86:87], v[84:85], 0, v[4:5]
	global_store_dwordx4 v[86:87], v[58:61], off
	v_or_b32_e32 v4, s9, v71
	v_lshlrev_b32_e32 v4, 11, v4
	s_waitcnt lgkmcnt(0)
	v_cvt_pk_bf16_f32 v58, v236, v237
	s_waitcnt lgkmcnt(0)
	v_cvt_pk_bf16_f32 v59, v238, v239
	s_waitcnt lgkmcnt(0)
	v_cvt_pk_bf16_f32 v60, v240, v241
	s_waitcnt lgkmcnt(0)
	v_cvt_pk_bf16_f32 v61, v242, v243
	v_lshl_add_u64 v[62:63], v[84:85], 0, v[4:5]
	global_store_dwordx4 v[62:63], v[58:61], off
	s_waitcnt lgkmcnt(0)

.LBB0_191:
	s_cmpk_eq_i32 s9, 0x1588
	s_cbranch_scc0 .LBB0_193
	s_load_dwordx2 s[4:5], s[16:17], 0xc8
	s_lshl_b32 s11, s3, 5
	s_addk_i32 s11, 0x4f00
	s_and_b32 s11, s11, 0xffe0
	s_lshl_b32 s14, s11, 2
	s_waitcnt lgkmcnt(0)
	s_add_u32 s4, s4, s14
	s_addc_u32 s5, s5, 0
	v_lshlrev_b32_e32 v4, 2, v2
	v_lshl_add_u64 v[62:63], s[4:5], 0, v[4:5]
	v_lshl_add_u64 v[58:59], v[62:63], 0, v[12:13]
	global_load_dwordx4 v[58:61], v[58:59], off
	v_lshl_add_u64 v[84:85], v[62:63], 0, v[14:15]
	global_load_dwordx4 v[84:87], v[84:85], off
	v_lshl_add_u64 v[88:89], v[62:63], 0, v[16:17]
	global_load_dwordx4 v[88:91], v[88:89], off
	v_lshl_add_u64 v[92:93], v[62:63], 0, v[18:19]
	global_load_dwordx4 v[92:95], v[92:93], off
	v_lshl_add_u64 v[96:97], v[62:63], 0, v[20:21]
	global_load_dwordx4 v[96:99], v[96:97], off
	v_lshl_add_u64 v[100:101], v[62:63], 0, v[22:23]
	global_load_dwordx4 v[100:103], v[100:101], off
	v_lshl_add_u64 v[104:105], v[62:63], 0, v[24:25]
	global_load_dwordx4 v[104:107], v[104:105], off
	v_lshl_add_u64 v[62:63], v[62:63], 0, v[26:27]
	global_load_dwordx4 v[108:111], v[62:63], off
	v_add_u32_e32 v4, v66, v81
	v_add_u32_e32 v62, v66, v76
	v_add_u32_e32 v63, 0x420, v4
	v_add_u32_e32 v83, 0x428, v4
	v_add_u32_e32 v112, 0x840, v4
	v_add_u32_e32 v113, 0x848, v4
	v_add_u32_e32 v114, 0xc60, v4
	v_add_u32_e32 v115, 0xc68, v4
	v_add_u32_e32 v116, 0x1080, v4
	v_add_u32_e32 v117, 0x1088, v4
	v_add_u32_e32 v118, 0x14a0, v4
	v_add_u32_e32 v119, 0x420, v62
	v_add_u32_e32 v120, 0x428, v62
	v_add_u32_e32 v121, 0x840, v62
	v_add_u32_e32 v122, 0x848, v62
	s_waitcnt vmcnt(7)
	ds_write2_b32 v4, v58, v59 offset1:1
	ds_write2_b32 v4, v60, v61 offset0:2 offset1:3
	s_waitcnt vmcnt(6)
	ds_write2_b32 v63, v84, v85 offset1:1
	ds_write2_b32 v83, v86, v87 offset1:1
	s_waitcnt vmcnt(5)
	ds_write2_b32 v112, v88, v89 offset1:1
	ds_write2_b32 v113, v90, v91 offset1:1
	s_waitcnt vmcnt(4)
	ds_write2_b32 v114, v92, v93 offset1:1
	ds_write2_b32 v115, v94, v95 offset1:1
	s_waitcnt vmcnt(3)
	ds_write2_b32 v116, v96, v97 offset1:1
	ds_write2_b32 v117, v98, v99 offset1:1
	s_waitcnt vmcnt(2)
	ds_write2_b32 v118, v100, v101 offset1:1
	ds_write2_b32 v62, v102, v103 offset0:2 offset1:3
	s_waitcnt vmcnt(1)
	ds_write2_b32 v119, v104, v105 offset1:1
	ds_write2_b32 v120, v106, v107 offset1:1
	s_waitcnt vmcnt(0)
	ds_write2_b32 v121, v108, v109 offset1:1
	ds_write2_b32 v122, v110, v111 offset1:1
	s_waitcnt lgkmcnt(0)
	ds_read2_b32 v[212:213], v79 offset1:33
	ds_read2_b32 v[214:215], v79 offset0:66 offset1:99
	ds_read2_b32 v[216:217], v79 offset0:132 offset1:165
	ds_read2_b32 v[218:219], v79 offset0:198 offset1:231
	ds_read2_b32 v[220:221], v79 offset0:8 offset1:41
	ds_read2_b32 v[222:223], v79 offset0:74 offset1:107
	ds_read2_b32 v[224:225], v79 offset0:140 offset1:173
	ds_read2_b32 v[226:227], v79 offset0:206 offset1:239
	ds_read2_b32 v[228:229], v79 offset0:16 offset1:49
	ds_read2_b32 v[230:231], v79 offset0:82 offset1:115
	ds_read2_b32 v[232:233], v79 offset0:148 offset1:181
	ds_read2_b32 v[234:235], v79 offset0:214 offset1:247
	ds_read2_b32 v[236:237], v79 offset0:24 offset1:57
	ds_read2_b32 v[238:239], v79 offset0:90 offset1:123
	ds_read2_b32 v[240:241], v79 offset0:156 offset1:189
	ds_read2_b32 v[242:243], v79 offset0:222 offset1:255
	s_waitcnt lgkmcnt(0)
	v_cvt_pk_bf16_f32 v58, v212, v213
	v_or_b32_e32 v4, s11, v65
	s_waitcnt lgkmcnt(0)
	v_cvt_pk_bf16_f32 v59, v214, v215
	v_lshlrev_b32_e32 v4, 7, v4
	s_waitcnt lgkmcnt(0)
	v_cvt_pk_bf16_f32 v60, v216, v217
	s_waitcnt lgkmcnt(0)
	v_cvt_pk_bf16_f32 v61, v218, v219
	v_lshl_add_u64 v[84:85], v[50:51], 0, v[4:5]
	global_store_dwordx4 v[84:85], v[58:61], off
	v_or_b32_e32 v4, s11, v67
	v_lshlrev_b32_e32 v4, 7, v4
	s_waitcnt lgkmcnt(0)
	v_cvt_pk_bf16_f32 v58, v220, v221
	s_waitcnt lgkmcnt(0)
	v_cvt_pk_bf16_f32 v59, v222, v223
	s_waitcnt lgkmcnt(0)
	v_cvt_pk_bf16_f32 v60, v224, v225
	s_waitcnt lgkmcnt(0)
	v_cvt_pk_bf16_f32 v61, v226, v227
	v_lshl_add_u64 v[84:85], v[50:51], 0, v[4:5]
	global_store_dwordx4 v[84:85], v[58:61], off
	v_or_b32_e32 v4, s11, v69
	v_lshlrev_b32_e32 v4, 7, v4
	s_waitcnt lgkmcnt(0)
	v_cvt_pk_bf16_f32 v58, v228, v229
	s_waitcnt lgkmcnt(0)
	v_cvt_pk_bf16_f32 v59, v230, v231
	s_waitcnt lgkmcnt(0)
	v_cvt_pk_bf16_f32 v60, v232, v233
	s_waitcnt lgkmcnt(0)
	v_cvt_pk_bf16_f32 v61, v234, v235
	v_lshl_add_u64 v[84:85], v[50:51], 0, v[4:5]
	global_store_dwordx4 v[84:85], v[58:61], off
	v_or_b32_e32 v4, s11, v71
	v_lshlrev_b32_e32 v4, 7, v4
	s_waitcnt lgkmcnt(0)
	v_cvt_pk_bf16_f32 v58, v236, v237
	s_waitcnt lgkmcnt(0)
	v_cvt_pk_bf16_f32 v59, v238, v239
	s_waitcnt lgkmcnt(0)
	v_cvt_pk_bf16_f32 v60, v240, v241
	s_waitcnt lgkmcnt(0)
	v_cvt_pk_bf16_f32 v61, v242, v243
	v_lshl_add_u64 v[62:63], v[50:51], 0, v[4:5]
	global_store_dwordx4 v[62:63], v[58:61], off
	s_waitcnt lgkmcnt(0)

.LBB0_198:
	v_or_b32_e32 v4, s9, v78
	v_lshlrev_b32_e32 v62, 2, v4
	v_lshlrev_b32_e32 v4, 9, v4
	global_load_dword v62, v62, s[30:31]
	v_lshl_add_u64 v[58:59], v[58:59], 0, v[4:5]
	global_load_dwordx4 v[84:87], v[58:59], off
	v_add_u32_e32 v63, 0x840, v61
	v_add_u32_e32 v83, 0x848, v61
	s_lshl_b32 s4, s3, 5
	s_or_b32 s4, s4, 0x980
	s_and_b32 s4, s4, 0x9ff
	s_lshl_b32 s14, s9, 1
	s_waitcnt vmcnt(1)
	v_mul_f32_e32 v4, v60, v62
	s_waitcnt vmcnt(0)
	v_pk_mul_f32 v[60:61], v[84:85], v[4:5] op_sel_hi:[1,0]
	v_pk_mul_f32 v[58:59], v[86:87], v[4:5] op_sel_hi:[1,0]
	ds_write2_b32 v63, v60, v61 offset1:1
	ds_write2_b32 v83, v58, v59 offset1:1
	s_waitcnt lgkmcnt(0)
	ds_read2_b32 v[212:213], v79 offset1:33
	ds_read2_b32 v[214:215], v79 offset0:66 offset1:99
	ds_read2_b32 v[216:217], v79 offset0:132 offset1:165
	ds_read2_b32 v[218:219], v79 offset0:198 offset1:231
	ds_read2_b32 v[220:221], v79 offset0:8 offset1:41
	ds_read2_b32 v[222:223], v79 offset0:74 offset1:107
	ds_read2_b32 v[224:225], v79 offset0:140 offset1:173
	ds_read2_b32 v[226:227], v79 offset0:206 offset1:239
	ds_read2_b32 v[228:229], v79 offset0:16 offset1:49
	ds_read2_b32 v[230:231], v79 offset0:82 offset1:115
	ds_read2_b32 v[232:233], v79 offset0:148 offset1:181
	ds_read2_b32 v[234:235], v79 offset0:214 offset1:247
	ds_read2_b32 v[236:237], v79 offset0:24 offset1:57
	ds_read2_b32 v[238:239], v79 offset0:90 offset1:123
	ds_read2_b32 v[240:241], v79 offset0:156 offset1:189
	ds_read2_b32 v[242:243], v79 offset0:222 offset1:255
	s_waitcnt lgkmcnt(0)
	v_cvt_pk_bf16_f32 v58, v212, v213
	v_or_b32_e32 v4, s4, v65
	s_waitcnt lgkmcnt(0)
	v_cvt_pk_bf16_f32 v59, v214, v215
	v_lshl_add_u64 v[84:85], v[48:49], 0, s[14:15]
	v_lshlrev_b32_e32 v4, 11, v4
	s_waitcnt lgkmcnt(0)
	v_cvt_pk_bf16_f32 v60, v216, v217
	s_waitcnt lgkmcnt(0)
	v_cvt_pk_bf16_f32 v61, v218, v219
	v_lshl_add_u64 v[86:87], v[84:85], 0, v[4:5]
	global_store_dwordx4 v[86:87], v[58:61], off
	v_or_b32_e32 v4, s4, v67
	v_lshlrev_b32_e32 v4, 11, v4
	s_waitcnt lgkmcnt(0)
	v_cvt_pk_bf16_f32 v58, v220, v221
	s_waitcnt lgkmcnt(0)
	v_cvt_pk_bf16_f32 v59, v222, v223
	s_waitcnt lgkmcnt(0)
	v_cvt_pk_bf16_f32 v60, v224, v225
	s_waitcnt lgkmcnt(0)
	v_cvt_pk_bf16_f32 v61, v226, v227
	v_lshl_add_u64 v[86:87], v[84:85], 0, v[4:5]
	global_store_dwordx4 v[86:87], v[58:61], off
	v_or_b32_e32 v4, s4, v69
	v_lshlrev_b32_e32 v4, 11, v4
	s_waitcnt lgkmcnt(0)
	v_cvt_pk_bf16_f32 v58, v228, v229
	s_waitcnt lgkmcnt(0)
	v_cvt_pk_bf16_f32 v59, v230, v231
	s_waitcnt lgkmcnt(0)
	v_cvt_pk_bf16_f32 v60, v232, v233
	s_waitcnt lgkmcnt(0)
	v_cvt_pk_bf16_f32 v61, v234, v235
	v_lshl_add_u64 v[86:87], v[84:85], 0, v[4:5]
	global_store_dwordx4 v[86:87], v[58:61], off
	v_or_b32_e32 v4, s4, v71
	v_lshlrev_b32_e32 v4, 11, v4
	s_waitcnt lgkmcnt(0)
	v_cvt_pk_bf16_f32 v58, v236, v237
	s_waitcnt lgkmcnt(0)
	v_cvt_pk_bf16_f32 v59, v238, v239
	s_waitcnt lgkmcnt(0)
	v_cvt_pk_bf16_f32 v60, v240, v241
	s_waitcnt lgkmcnt(0)
	v_cvt_pk_bf16_f32 v61, v242, v243
	v_lshl_add_u64 v[62:63], v[84:85], 0, v[4:5]
	global_store_dwordx4 v[62:63], v[58:61], off
	s_waitcnt lgkmcnt(0)
	s_and_b32 s9, s3, -8
	s_cmpk_lt_i32 s9, 0x1588
	s_mov_b64 s[4:5], -1
	s_cbranch_scc0 .LBB0_191

.LBB0_200:
	s_cmpk_lg_i32 s9, 0x1580
	s_cbranch_scc1 .LBB0_202
	s_load_dwordx2 s[4:5], s[16:17], 0xb0
	s_lshl_b32 s9, s3, 5
	s_addk_i32 s9, 0x5000
	s_and_b32 s9, s9, 0xffe0
	s_lshl_b32 s11, s9, 2
	s_waitcnt lgkmcnt(0)
	s_add_u32 s4, s4, s11
	s_addc_u32 s5, s5, 0
	v_lshlrev_b32_e32 v4, 2, v2
	v_lshl_add_u64 v[62:63], s[4:5], 0, v[4:5]
	v_lshl_add_u64 v[58:59], v[62:63], 0, v[12:13]
	global_load_dwordx4 v[58:61], v[58:59], off
	v_lshl_add_u64 v[84:85], v[62:63], 0, v[14:15]
	global_load_dwordx4 v[84:87], v[84:85], off
	v_lshl_add_u64 v[88:89], v[62:63], 0, v[16:17]
	global_load_dwordx4 v[88:91], v[88:89], off
	v_lshl_add_u64 v[92:93], v[62:63], 0, v[18:19]
	global_load_dwordx4 v[92:95], v[92:93], off
	v_lshl_add_u64 v[96:97], v[62:63], 0, v[20:21]
	global_load_dwordx4 v[96:99], v[96:97], off
	v_lshl_add_u64 v[100:101], v[62:63], 0, v[22:23]
	global_load_dwordx4 v[100:103], v[100:101], off
	v_lshl_add_u64 v[104:105], v[62:63], 0, v[24:25]
	global_load_dwordx4 v[104:107], v[104:105], off
	v_lshl_add_u64 v[62:63], v[62:63], 0, v[26:27]
	global_load_dwordx4 v[108:111], v[62:63], off
	v_add_u32_e32 v4, v66, v81
	v_add_u32_e32 v62, v66, v76
	v_add_u32_e32 v63, 0x420, v4
	v_add_u32_e32 v83, 0x428, v4
	v_add_u32_e32 v112, 0x840, v4
	v_add_u32_e32 v113, 0x848, v4
	v_add_u32_e32 v114, 0xc60, v4
	v_add_u32_e32 v115, 0xc68, v4
	v_add_u32_e32 v116, 0x1080, v4
	v_add_u32_e32 v117, 0x1088, v4
	v_add_u32_e32 v118, 0x14a0, v4
	v_add_u32_e32 v119, 0x420, v62
	v_add_u32_e32 v120, 0x428, v62
	v_add_u32_e32 v121, 0x840, v62
	v_add_u32_e32 v122, 0x848, v62
	s_waitcnt vmcnt(7)
	ds_write2_b32 v4, v58, v59 offset1:1
	ds_write2_b32 v4, v60, v61 offset0:2 offset1:3
	s_waitcnt vmcnt(6)
	ds_write2_b32 v63, v84, v85 offset1:1
	ds_write2_b32 v83, v86, v87 offset1:1
	s_waitcnt vmcnt(5)
	ds_write2_b32 v112, v88, v89 offset1:1
	ds_write2_b32 v113, v90, v91 offset1:1
	s_waitcnt vmcnt(4)
	ds_write2_b32 v114, v92, v93 offset1:1
	ds_write2_b32 v115, v94, v95 offset1:1
	s_waitcnt vmcnt(3)
	ds_write2_b32 v116, v96, v97 offset1:1
	ds_write2_b32 v117, v98, v99 offset1:1
	s_waitcnt vmcnt(2)
	ds_write2_b32 v118, v100, v101 offset1:1
	ds_write2_b32 v62, v102, v103 offset0:2 offset1:3
	s_waitcnt vmcnt(1)
	ds_write2_b32 v119, v104, v105 offset1:1
	ds_write2_b32 v120, v106, v107 offset1:1
	s_waitcnt vmcnt(0)
	ds_write2_b32 v121, v108, v109 offset1:1
	ds_write2_b32 v122, v110, v111 offset1:1
	s_waitcnt lgkmcnt(0)
	ds_read2_b32 v[212:213], v79 offset1:33
	ds_read2_b32 v[214:215], v79 offset0:66 offset1:99
	ds_read2_b32 v[216:217], v79 offset0:132 offset1:165
	ds_read2_b32 v[218:219], v79 offset0:198 offset1:231
	ds_read2_b32 v[220:221], v79 offset0:8 offset1:41
	ds_read2_b32 v[222:223], v79 offset0:74 offset1:107
	ds_read2_b32 v[224:225], v79 offset0:140 offset1:173
	ds_read2_b32 v[226:227], v79 offset0:206 offset1:239
	ds_read2_b32 v[228:229], v79 offset0:16 offset1:49
	ds_read2_b32 v[230:231], v79 offset0:82 offset1:115
	ds_read2_b32 v[232:233], v79 offset0:148 offset1:181
	ds_read2_b32 v[234:235], v79 offset0:214 offset1:247
	ds_read2_b32 v[236:237], v79 offset0:24 offset1:57
	ds_read2_b32 v[238:239], v79 offset0:90 offset1:123
	ds_read2_b32 v[240:241], v79 offset0:156 offset1:189
	ds_read2_b32 v[242:243], v79 offset0:222 offset1:255
	s_waitcnt lgkmcnt(0)
	v_cvt_pk_bf16_f32 v58, v212, v213
	v_or_b32_e32 v4, s9, v65
	s_waitcnt lgkmcnt(0)
	v_cvt_pk_bf16_f32 v59, v214, v215
	v_lshlrev_b32_e32 v4, 7, v4
	s_waitcnt lgkmcnt(0)
	v_cvt_pk_bf16_f32 v60, v216, v217
	s_waitcnt lgkmcnt(0)
	v_cvt_pk_bf16_f32 v61, v218, v219
	v_lshl_add_u64 v[84:85], v[52:53], 0, v[4:5]
	global_store_dwordx4 v[84:85], v[58:61], off
	v_or_b32_e32 v4, s9, v67
	v_lshlrev_b32_e32 v4, 7, v4
	s_waitcnt lgkmcnt(0)
	v_cvt_pk_bf16_f32 v58, v220, v221
	s_waitcnt lgkmcnt(0)
	v_cvt_pk_bf16_f32 v59, v222, v223
	s_waitcnt lgkmcnt(0)
	v_cvt_pk_bf16_f32 v60, v224, v225
	s_waitcnt lgkmcnt(0)
	v_cvt_pk_bf16_f32 v61, v226, v227
	v_lshl_add_u64 v[84:85], v[52:53], 0, v[4:5]
	global_store_dwordx4 v[84:85], v[58:61], off
	v_or_b32_e32 v4, s9, v69
	v_lshlrev_b32_e32 v4, 7, v4
	s_waitcnt lgkmcnt(0)
	v_cvt_pk_bf16_f32 v58, v228, v229
	s_waitcnt lgkmcnt(0)
	v_cvt_pk_bf16_f32 v59, v230, v231
	s_waitcnt lgkmcnt(0)
	v_cvt_pk_bf16_f32 v60, v232, v233
	s_waitcnt lgkmcnt(0)
	v_cvt_pk_bf16_f32 v61, v234, v235
	v_lshl_add_u64 v[84:85], v[52:53], 0, v[4:5]
	global_store_dwordx4 v[84:85], v[58:61], off
	v_or_b32_e32 v4, s9, v71
	v_lshlrev_b32_e32 v4, 7, v4
	s_waitcnt lgkmcnt(0)
	v_cvt_pk_bf16_f32 v58, v236, v237
	s_waitcnt lgkmcnt(0)
	v_cvt_pk_bf16_f32 v59, v238, v239
	s_waitcnt lgkmcnt(0)
	v_cvt_pk_bf16_f32 v60, v240, v241
	s_waitcnt lgkmcnt(0)
	v_cvt_pk_bf16_f32 v61, v242, v243
	v_lshl_add_u64 v[62:63], v[52:53], 0, v[4:5]
	global_store_dwordx4 v[62:63], v[58:61], off
	s_waitcnt lgkmcnt(0)
.LBB0_202:
	s_and_b32 s4, s3, -16
	s_cmpk_lg_i32 s4, 0x1590
	s_cbranch_scc1 .LBB0_205
	s_add_i32 s4, s3, 0xea70
	s_and_b32 s5, s4, 0xffff
	s_add_i32 s9, s3, 0xea68
	s_load_dwordx2 s[36:37], s[16:17], 0xd8
	s_cmp_lt_u32 s5, 8
	s_cselect_b32 s4, s4, s9
	s_cmp_gt_u32 s5, 7
	s_cselect_b32 s5, 64, 0
	s_lshl_b32 s4, s4, 5
	s_and_b32 s4, s4, 0xffe0
	s_lshl_b32 s9, s4, 2
	s_waitcnt lgkmcnt(0)
	s_add_u32 s36, s36, s9
	s_addc_u32 s37, s37, 0
	v_lshlrev_b32_e32 v4, 2, v2
	v_lshl_add_u64 v[62:63], s[36:37], 0, v[4:5]
	v_or_b32_e32 v4, s5, v65
	v_lshlrev_b32_e32 v4, 10, v4
	v_lshl_add_u64 v[58:59], v[62:63], 0, v[4:5]
	v_or_b32_e32 v4, s5, v67
	v_lshlrev_b32_e32 v4, 10, v4
	v_lshl_add_u64 v[84:85], v[62:63], 0, v[4:5]
	v_or_b32_e32 v4, s5, v69
	v_lshlrev_b32_e32 v4, 10, v4
	v_lshl_add_u64 v[96:97], v[62:63], 0, v[4:5]
	v_or_b32_e32 v4, s5, v71
	v_lshlrev_b32_e32 v4, 10, v4
	v_lshl_add_u64 v[98:99], v[62:63], 0, v[4:5]
	v_or_b32_e32 v4, s5, v73
	v_lshlrev_b32_e32 v4, 10, v4
	v_lshl_add_u64 v[104:105], v[62:63], 0, v[4:5]
	v_or_b32_e32 v4, s5, v75
	v_lshlrev_b32_e32 v4, 10, v4
	global_load_dwordx4 v[58:61], v[58:59], off
	s_nop 0
	global_load_dwordx4 v[84:87], v[84:85], off
	s_nop 0
	global_load_dwordx4 v[88:91], v[96:97], off
	global_load_dwordx4 v[92:95], v[98:99], off
	v_lshl_add_u64 v[106:107], v[62:63], 0, v[4:5]
	global_load_dwordx4 v[96:99], v[104:105], off
	global_load_dwordx4 v[100:103], v[106:107], off
	v_or_b32_e32 v4, s5, v77
	v_lshlrev_b32_e32 v4, 10, v4
	v_lshl_add_u64 v[104:105], v[62:63], 0, v[4:5]
	v_or_b32_e32 v4, s5, v78
	global_load_dwordx4 v[104:107], v[104:105], off
	v_lshlrev_b32_e32 v4, 10, v4
	v_lshl_add_u64 v[62:63], v[62:63], 0, v[4:5]
	global_load_dwordx4 v[108:111], v[62:63], off
	v_add_u32_e32 v4, v66, v81
	v_add_u32_e32 v62, v66, v76
	v_add_u32_e32 v63, 0x420, v4
	v_add_u32_e32 v83, 0x428, v4
	v_add_u32_e32 v112, 0x840, v4
	v_add_u32_e32 v113, 0x848, v4
	v_add_u32_e32 v114, 0xc60, v4
	v_add_u32_e32 v115, 0xc68, v4
	v_add_u32_e32 v116, 0x1080, v4
	v_add_u32_e32 v117, 0x1088, v4
	v_add_u32_e32 v118, 0x14a0, v4
	v_add_u32_e32 v119, 0x420, v62
	v_add_u32_e32 v120, 0x428, v62
	v_add_u32_e32 v121, 0x840, v62
	v_add_u32_e32 v122, 0x848, v62
	s_lshl_b32 s14, s5, 1
	s_waitcnt vmcnt(7)
	ds_write2_b32 v4, v58, v59 offset1:1
	ds_write2_b32 v4, v60, v61 offset0:2 offset1:3
	s_waitcnt vmcnt(6)
	ds_write2_b32 v63, v84, v85 offset1:1
	ds_write2_b32 v83, v86, v87 offset1:1
	s_waitcnt vmcnt(5)
	ds_write2_b32 v112, v88, v89 offset1:1
	ds_write2_b32 v113, v90, v91 offset1:1
	s_waitcnt vmcnt(4)
	ds_write2_b32 v114, v92, v93 offset1:1
	ds_write2_b32 v115, v94, v95 offset1:1
	s_waitcnt vmcnt(3)
	ds_write2_b32 v116, v96, v97 offset1:1
	ds_write2_b32 v117, v98, v99 offset1:1
	s_waitcnt vmcnt(2)
	ds_write2_b32 v118, v100, v101 offset1:1
	ds_write2_b32 v62, v102, v103 offset0:2 offset1:3
	s_waitcnt vmcnt(1)
	ds_write2_b32 v119, v104, v105 offset1:1
	ds_write2_b32 v120, v106, v107 offset1:1
	s_waitcnt vmcnt(0)
	ds_write2_b32 v121, v108, v109 offset1:1
	ds_write2_b32 v122, v110, v111 offset1:1
	s_waitcnt lgkmcnt(0)
	ds_read2_b32 v[212:213], v79 offset1:33
	ds_read2_b32 v[214:215], v79 offset0:66 offset1:99
	ds_read2_b32 v[216:217], v79 offset0:132 offset1:165
	ds_read2_b32 v[218:219], v79 offset0:198 offset1:231
	ds_read2_b32 v[220:221], v79 offset0:8 offset1:41
	ds_read2_b32 v[222:223], v79 offset0:74 offset1:107
	ds_read2_b32 v[224:225], v79 offset0:140 offset1:173
	ds_read2_b32 v[226:227], v79 offset0:206 offset1:239
	ds_read2_b32 v[228:229], v79 offset0:16 offset1:49
	ds_read2_b32 v[230:231], v79 offset0:82 offset1:115
	ds_read2_b32 v[232:233], v79 offset0:148 offset1:181
	ds_read2_b32 v[234:235], v79 offset0:214 offset1:247
	ds_read2_b32 v[236:237], v79 offset0:24 offset1:57
	ds_read2_b32 v[238:239], v79 offset0:90 offset1:123
	ds_read2_b32 v[240:241], v79 offset0:156 offset1:189
	ds_read2_b32 v[242:243], v79 offset0:222 offset1:255
	s_waitcnt lgkmcnt(0)
	v_cvt_pk_bf16_f32 v58, v212, v213
	v_or_b32_e32 v4, s4, v65
	s_waitcnt lgkmcnt(0)
	v_cvt_pk_bf16_f32 v59, v214, v215
	v_lshl_add_u64 v[84:85], v[54:55], 0, s[14:15]
	v_lshlrev_b32_e32 v4, 8, v4
	s_waitcnt lgkmcnt(0)
	v_cvt_pk_bf16_f32 v60, v216, v217
	s_waitcnt lgkmcnt(0)
	v_cvt_pk_bf16_f32 v61, v218, v219
	v_lshl_add_u64 v[86:87], v[84:85], 0, v[4:5]
	global_store_dwordx4 v[86:87], v[58:61], off
	v_or_b32_e32 v4, s4, v67
	v_lshlrev_b32_e32 v4, 8, v4
	s_waitcnt lgkmcnt(0)
	v_cvt_pk_bf16_f32 v58, v220, v221
	s_waitcnt lgkmcnt(0)
	v_cvt_pk_bf16_f32 v59, v222, v223
	s_waitcnt lgkmcnt(0)
	v_cvt_pk_bf16_f32 v60, v224, v225
	s_waitcnt lgkmcnt(0)
	v_cvt_pk_bf16_f32 v61, v226, v227
	v_lshl_add_u64 v[86:87], v[84:85], 0, v[4:5]
	global_store_dwordx4 v[86:87], v[58:61], off
	v_or_b32_e32 v4, s4, v69
	v_lshlrev_b32_e32 v4, 8, v4
	s_waitcnt lgkmcnt(0)
	v_cvt_pk_bf16_f32 v58, v228, v229
	s_waitcnt lgkmcnt(0)
	v_cvt_pk_bf16_f32 v59, v230, v231
	s_waitcnt lgkmcnt(0)
	v_cvt_pk_bf16_f32 v60, v232, v233
	s_waitcnt lgkmcnt(0)
	v_cvt_pk_bf16_f32 v61, v234, v235
	v_lshl_add_u64 v[86:87], v[84:85], 0, v[4:5]
	global_store_dwordx4 v[86:87], v[58:61], off
	v_or_b32_e32 v4, s4, v71
	v_lshlrev_b32_e32 v4, 8, v4
	s_waitcnt lgkmcnt(0)
	v_cvt_pk_bf16_f32 v58, v236, v237
	s_waitcnt lgkmcnt(0)
	v_cvt_pk_bf16_f32 v59, v238, v239
	s_waitcnt lgkmcnt(0)
	v_cvt_pk_bf16_f32 v60, v240, v241
	s_waitcnt lgkmcnt(0)
	v_cvt_pk_bf16_f32 v61, v242, v243
	v_lshl_add_u64 v[62:63], v[84:85], 0, v[4:5]
	global_store_dwordx4 v[62:63], v[58:61], off
	s_waitcnt lgkmcnt(0)
	s_and_b32 s9, s3, -2
	s_cmpk_lt_i32 s9, 0x15a4
	s_mov_b64 s[4:5], -1
	s_cbranch_scc0 .LBB0_206

.LBB0_206:
	s_cmpk_lt_i32 s9, 0x15a6
	s_cbranch_scc1 .LBB0_210
	s_cmpk_eq_i32 s9, 0x15a6
	s_cbranch_scc0 .LBB0_209
	s_load_dwordx2 s[4:5], s[16:17], 0x80
	s_lshl_b32 s11, s3, 5
	s_addk_i32 s11, 0x4b40
	s_and_b32 s11, s11, 0xffe0
	s_lshl_b32 s14, s11, 2
	s_waitcnt lgkmcnt(0)
	s_add_u32 s4, s4, s14
	s_addc_u32 s5, s5, 0
	v_lshlrev_b32_e32 v4, 2, v2
	v_lshl_add_u64 v[58:59], s[4:5], 0, v[4:5]
	v_lshl_add_u64 v[62:63], v[58:59], 0, s[34:35]
	v_lshl_add_u64 v[58:59], v[62:63], 0, v[28:29]
	global_load_dwordx4 v[58:61], v[58:59], off
	v_lshl_add_u64 v[84:85], v[62:63], 0, v[30:31]
	global_load_dwordx4 v[84:87], v[84:85], off
	v_lshl_add_u64 v[88:89], v[62:63], 0, v[32:33]
	global_load_dwordx4 v[88:91], v[88:89], off
	v_lshl_add_u64 v[92:93], v[62:63], 0, v[34:35]
	global_load_dwordx4 v[92:95], v[92:93], off
	v_lshl_add_u64 v[96:97], v[62:63], 0, v[36:37]
	global_load_dwordx4 v[96:99], v[96:97], off
	v_lshl_add_u64 v[100:101], v[62:63], 0, v[38:39]
	global_load_dwordx4 v[100:103], v[100:101], off
	v_lshl_add_u64 v[104:105], v[62:63], 0, v[40:41]
	global_load_dwordx4 v[104:107], v[104:105], off
	v_lshl_add_u64 v[62:63], v[62:63], 0, v[42:43]
	global_load_dwordx4 v[108:111], v[62:63], off
	v_add_u32_e32 v4, v66, v81
	v_add_u32_e32 v62, v66, v76
	v_add_u32_e32 v63, 0x420, v4
	v_add_u32_e32 v83, 0x428, v4
	v_add_u32_e32 v112, 0x840, v4
	v_add_u32_e32 v113, 0x848, v4
	v_add_u32_e32 v114, 0xc60, v4
	v_add_u32_e32 v115, 0xc68, v4
	v_add_u32_e32 v116, 0x1080, v4
	v_add_u32_e32 v117, 0x1088, v4
	v_add_u32_e32 v118, 0x14a0, v4
	v_add_u32_e32 v119, 0x420, v62
	v_add_u32_e32 v120, 0x428, v62
	v_add_u32_e32 v121, 0x840, v62
	v_add_u32_e32 v122, 0x848, v62
	s_addk_i32 s11, 0xc0
	s_waitcnt vmcnt(7)
	ds_write2_b32 v4, v58, v59 offset1:1
	ds_write2_b32 v4, v60, v61 offset0:2 offset1:3
	s_waitcnt vmcnt(6)
	ds_write2_b32 v63, v84, v85 offset1:1
	ds_write2_b32 v83, v86, v87 offset1:1
	s_waitcnt vmcnt(5)
	ds_write2_b32 v112, v88, v89 offset1:1
	ds_write2_b32 v113, v90, v91 offset1:1
	s_waitcnt vmcnt(4)
	ds_write2_b32 v114, v92, v93 offset1:1
	ds_write2_b32 v115, v94, v95 offset1:1
	s_waitcnt vmcnt(3)
	ds_write2_b32 v116, v96, v97 offset1:1
	ds_write2_b32 v117, v98, v99 offset1:1
	s_waitcnt vmcnt(2)
	ds_write2_b32 v118, v100, v101 offset1:1
	ds_write2_b32 v62, v102, v103 offset0:2 offset1:3
	s_waitcnt vmcnt(1)
	ds_write2_b32 v119, v104, v105 offset1:1
	ds_write2_b32 v120, v106, v107 offset1:1
	s_waitcnt vmcnt(0)
	ds_write2_b32 v121, v108, v109 offset1:1
	ds_write2_b32 v122, v110, v111 offset1:1
	s_waitcnt lgkmcnt(0)
	ds_read2_b32 v[212:213], v79 offset1:33
	ds_read2_b32 v[214:215], v79 offset0:66 offset1:99
	ds_read2_b32 v[216:217], v79 offset0:132 offset1:165
	ds_read2_b32 v[218:219], v79 offset0:198 offset1:231
	ds_read2_b32 v[220:221], v79 offset0:8 offset1:41
	ds_read2_b32 v[222:223], v79 offset0:74 offset1:107
	ds_read2_b32 v[224:225], v79 offset0:140 offset1:173
	ds_read2_b32 v[226:227], v79 offset0:206 offset1:239
	ds_read2_b32 v[228:229], v79 offset0:16 offset1:49
	ds_read2_b32 v[230:231], v79 offset0:82 offset1:115
	ds_read2_b32 v[232:233], v79 offset0:148 offset1:181
	ds_read2_b32 v[234:235], v79 offset0:214 offset1:247
	ds_read2_b32 v[236:237], v79 offset0:24 offset1:57
	ds_read2_b32 v[238:239], v79 offset0:90 offset1:123
	ds_read2_b32 v[240:241], v79 offset0:156 offset1:189
	ds_read2_b32 v[242:243], v79 offset0:222 offset1:255
	s_waitcnt lgkmcnt(0)
	v_cvt_pk_bf16_f32 v58, v212, v213
	v_or_b32_e32 v4, s11, v65
	s_waitcnt lgkmcnt(0)
	v_cvt_pk_bf16_f32 v59, v214, v215
	v_lshlrev_b32_e32 v4, 7, v4
	s_waitcnt lgkmcnt(0)
	v_cvt_pk_bf16_f32 v60, v216, v217
	s_waitcnt lgkmcnt(0)
	v_cvt_pk_bf16_f32 v61, v218, v219
	v_lshl_add_u64 v[84:85], v[56:57], 0, v[4:5]
	global_store_dwordx4 v[84:85], v[58:61], off
	v_or_b32_e32 v4, s11, v67
	v_lshlrev_b32_e32 v4, 7, v4
	s_waitcnt lgkmcnt(0)
	v_cvt_pk_bf16_f32 v58, v220, v221
	s_waitcnt lgkmcnt(0)
	v_cvt_pk_bf16_f32 v59, v222, v223
	s_waitcnt lgkmcnt(0)
	v_cvt_pk_bf16_f32 v60, v224, v225
	s_waitcnt lgkmcnt(0)
	v_cvt_pk_bf16_f32 v61, v226, v227
	v_lshl_add_u64 v[84:85], v[56:57], 0, v[4:5]
	global_store_dwordx4 v[84:85], v[58:61], off
	v_or_b32_e32 v4, s11, v69
	v_lshlrev_b32_e32 v4, 7, v4
	s_waitcnt lgkmcnt(0)
	v_cvt_pk_bf16_f32 v58, v228, v229
	s_waitcnt lgkmcnt(0)
	v_cvt_pk_bf16_f32 v59, v230, v231
	s_waitcnt lgkmcnt(0)
	v_cvt_pk_bf16_f32 v60, v232, v233
	s_waitcnt lgkmcnt(0)
	v_cvt_pk_bf16_f32 v61, v234, v235
	v_lshl_add_u64 v[84:85], v[56:57], 0, v[4:5]
	global_store_dwordx4 v[84:85], v[58:61], off
	v_or_b32_e32 v4, s11, v71
	v_lshlrev_b32_e32 v4, 7, v4
	s_waitcnt lgkmcnt(0)
	v_cvt_pk_bf16_f32 v58, v236, v237
	s_waitcnt lgkmcnt(0)
	v_cvt_pk_bf16_f32 v59, v238, v239
	s_waitcnt lgkmcnt(0)
	v_cvt_pk_bf16_f32 v60, v240, v241
	s_waitcnt lgkmcnt(0)
	v_cvt_pk_bf16_f32 v61, v242, v243
	v_lshl_add_u64 v[62:63], v[56:57], 0, v[4:5]
	global_store_dwordx4 v[62:63], v[58:61], off
	s_waitcnt lgkmcnt(0)

.LBB0_210:
	s_andn2_b64 vcc, exec, s[4:5]
	s_cbranch_vccnz .LBB0_213
	s_cmpk_eq_i32 s9, 0x15a4
	s_cbranch_scc0 .LBB0_213
	s_load_dwordx2 s[4:5], s[16:17], 0x80
	s_lshl_b32 s11, s3, 5
	s_addk_i32 s11, 0x4b80
	s_and_b32 s11, s11, 0xffe0
	s_lshl_b32 s14, s11, 2
	s_waitcnt lgkmcnt(0)
	s_add_u32 s4, s4, s14
	s_addc_u32 s5, s5, 0
	v_lshlrev_b32_e32 v4, 2, v2
	v_lshl_add_u64 v[58:59], s[4:5], 0, v[4:5]
	v_lshl_add_u64 v[62:63], v[58:59], 0, s[38:39]
	v_lshl_add_u64 v[58:59], v[62:63], 0, v[28:29]
	global_load_dwordx4 v[58:61], v[58:59], off
	v_lshl_add_u64 v[84:85], v[62:63], 0, v[30:31]
	global_load_dwordx4 v[84:87], v[84:85], off
	v_lshl_add_u64 v[88:89], v[62:63], 0, v[32:33]
	global_load_dwordx4 v[88:91], v[88:89], off
	v_lshl_add_u64 v[92:93], v[62:63], 0, v[34:35]
	global_load_dwordx4 v[92:95], v[92:93], off
	v_lshl_add_u64 v[96:97], v[62:63], 0, v[36:37]
	global_load_dwordx4 v[96:99], v[96:97], off
	v_lshl_add_u64 v[100:101], v[62:63], 0, v[38:39]
	global_load_dwordx4 v[100:103], v[100:101], off
	v_lshl_add_u64 v[104:105], v[62:63], 0, v[40:41]
	global_load_dwordx4 v[104:107], v[104:105], off
	v_lshl_add_u64 v[62:63], v[62:63], 0, v[42:43]
	global_load_dwordx4 v[108:111], v[62:63], off
	v_add_u32_e32 v4, v66, v81
	v_add_u32_e32 v62, v66, v76
	v_add_u32_e32 v63, 0x420, v4
	v_add_u32_e32 v83, 0x428, v4
	v_add_u32_e32 v112, 0x840, v4
	v_add_u32_e32 v113, 0x848, v4
	v_add_u32_e32 v114, 0xc60, v4
	v_add_u32_e32 v115, 0xc68, v4
	v_add_u32_e32 v116, 0x1080, v4
	v_add_u32_e32 v117, 0x1088, v4
	v_add_u32_e32 v118, 0x14a0, v4
	v_add_u32_e32 v119, 0x420, v62
	v_add_u32_e32 v120, 0x428, v62
	v_add_u32_e32 v121, 0x840, v62
	v_add_u32_e32 v122, 0x848, v62
	s_addk_i32 s11, 0x80
	s_waitcnt vmcnt(7)
	ds_write2_b32 v4, v58, v59 offset1:1
	ds_write2_b32 v4, v60, v61 offset0:2 offset1:3
	s_waitcnt vmcnt(6)
	ds_write2_b32 v63, v84, v85 offset1:1
	ds_write2_b32 v83, v86, v87 offset1:1
	s_waitcnt vmcnt(5)
	ds_write2_b32 v112, v88, v89 offset1:1
	ds_write2_b32 v113, v90, v91 offset1:1
	s_waitcnt vmcnt(4)
	ds_write2_b32 v114, v92, v93 offset1:1
	ds_write2_b32 v115, v94, v95 offset1:1
	s_waitcnt vmcnt(3)
	ds_write2_b32 v116, v96, v97 offset1:1
	ds_write2_b32 v117, v98, v99 offset1:1
	s_waitcnt vmcnt(2)
	ds_write2_b32 v118, v100, v101 offset1:1
	ds_write2_b32 v62, v102, v103 offset0:2 offset1:3
	s_waitcnt vmcnt(1)
	ds_write2_b32 v119, v104, v105 offset1:1
	ds_write2_b32 v120, v106, v107 offset1:1
	s_waitcnt vmcnt(0)
	ds_write2_b32 v121, v108, v109 offset1:1
	ds_write2_b32 v122, v110, v111 offset1:1
	s_waitcnt lgkmcnt(0)
	ds_read2_b32 v[212:213], v79 offset1:33
	ds_read2_b32 v[214:215], v79 offset0:66 offset1:99
	ds_read2_b32 v[216:217], v79 offset0:132 offset1:165
	ds_read2_b32 v[218:219], v79 offset0:198 offset1:231
	ds_read2_b32 v[220:221], v79 offset0:8 offset1:41
	ds_read2_b32 v[222:223], v79 offset0:74 offset1:107
	ds_read2_b32 v[224:225], v79 offset0:140 offset1:173
	ds_read2_b32 v[226:227], v79 offset0:206 offset1:239
	ds_read2_b32 v[228:229], v79 offset0:16 offset1:49
	ds_read2_b32 v[230:231], v79 offset0:82 offset1:115
	ds_read2_b32 v[232:233], v79 offset0:148 offset1:181
	ds_read2_b32 v[234:235], v79 offset0:214 offset1:247
	ds_read2_b32 v[236:237], v79 offset0:24 offset1:57
	ds_read2_b32 v[238:239], v79 offset0:90 offset1:123
	ds_read2_b32 v[240:241], v79 offset0:156 offset1:189
	ds_read2_b32 v[242:243], v79 offset0:222 offset1:255
	s_waitcnt lgkmcnt(0)
	v_cvt_pk_bf16_f32 v58, v212, v213
	v_or_b32_e32 v4, s11, v65
	s_waitcnt lgkmcnt(0)
	v_cvt_pk_bf16_f32 v59, v214, v215
	v_lshlrev_b32_e32 v4, 7, v4
	s_waitcnt lgkmcnt(0)
	v_cvt_pk_bf16_f32 v60, v216, v217
	s_waitcnt lgkmcnt(0)
	v_cvt_pk_bf16_f32 v61, v218, v219
	v_lshl_add_u64 v[84:85], v[56:57], 0, v[4:5]
	global_store_dwordx4 v[84:85], v[58:61], off
	v_or_b32_e32 v4, s11, v67
	v_lshlrev_b32_e32 v4, 7, v4
	s_waitcnt lgkmcnt(0)
	v_cvt_pk_bf16_f32 v58, v220, v221
	s_waitcnt lgkmcnt(0)
	v_cvt_pk_bf16_f32 v59, v222, v223
	s_waitcnt lgkmcnt(0)
	v_cvt_pk_bf16_f32 v60, v224, v225
	s_waitcnt lgkmcnt(0)
	v_cvt_pk_bf16_f32 v61, v226, v227
	v_lshl_add_u64 v[84:85], v[56:57], 0, v[4:5]
	global_store_dwordx4 v[84:85], v[58:61], off
	v_or_b32_e32 v4, s11, v69
	v_lshlrev_b32_e32 v4, 7, v4
	s_waitcnt lgkmcnt(0)
	v_cvt_pk_bf16_f32 v58, v228, v229
	s_waitcnt lgkmcnt(0)
	v_cvt_pk_bf16_f32 v59, v230, v231
	s_waitcnt lgkmcnt(0)
	v_cvt_pk_bf16_f32 v60, v232, v233
	s_waitcnt lgkmcnt(0)
	v_cvt_pk_bf16_f32 v61, v234, v235
	v_lshl_add_u64 v[84:85], v[56:57], 0, v[4:5]
	global_store_dwordx4 v[84:85], v[58:61], off
	v_or_b32_e32 v4, s11, v71
	v_lshlrev_b32_e32 v4, 7, v4
	s_waitcnt lgkmcnt(0)
	v_cvt_pk_bf16_f32 v58, v236, v237
	s_waitcnt lgkmcnt(0)
	v_cvt_pk_bf16_f32 v59, v238, v239
	s_waitcnt lgkmcnt(0)
	v_cvt_pk_bf16_f32 v60, v240, v241
	s_waitcnt lgkmcnt(0)
	v_cvt_pk_bf16_f32 v61, v242, v243
	v_lshl_add_u64 v[62:63], v[56:57], 0, v[4:5]
	global_store_dwordx4 v[62:63], v[58:61], off
	s_waitcnt lgkmcnt(0)

.LBB0_214:
	s_cmpk_lt_i32 s9, 0x15a2
	s_mov_b64 s[4:5], -1
	s_cbranch_scc1 .LBB0_218
	s_cmpk_eq_i32 s9, 0x15a2
	s_cbranch_scc0 .LBB0_217
	s_load_dwordx2 s[4:5], s[16:17], 0x80
	s_lshl_b32 s11, s3, 5
	s_addk_i32 s11, 0x4bc0
	s_and_b32 s11, s11, 0xffe0
	s_lshl_b32 s14, s11, 2
	s_waitcnt lgkmcnt(0)
	s_add_u32 s4, s4, s14
	s_addc_u32 s5, s5, 0
	v_lshlrev_b32_e32 v4, 2, v2
	v_lshl_add_u64 v[58:59], s[4:5], 0, v[4:5]
	v_lshl_add_u64 v[62:63], v[58:59], 0, s[44:45]
	v_lshl_add_u64 v[58:59], v[62:63], 0, v[28:29]
	global_load_dwordx4 v[58:61], v[58:59], off
	v_lshl_add_u64 v[84:85], v[62:63], 0, v[30:31]
	global_load_dwordx4 v[84:87], v[84:85], off
	v_lshl_add_u64 v[88:89], v[62:63], 0, v[32:33]
	global_load_dwordx4 v[88:91], v[88:89], off
	v_lshl_add_u64 v[92:93], v[62:63], 0, v[34:35]
	global_load_dwordx4 v[92:95], v[92:93], off
	v_lshl_add_u64 v[96:97], v[62:63], 0, v[36:37]
	global_load_dwordx4 v[96:99], v[96:97], off
	v_lshl_add_u64 v[100:101], v[62:63], 0, v[38:39]
	global_load_dwordx4 v[100:103], v[100:101], off
	v_lshl_add_u64 v[104:105], v[62:63], 0, v[40:41]
	global_load_dwordx4 v[104:107], v[104:105], off
	v_lshl_add_u64 v[62:63], v[62:63], 0, v[42:43]
	global_load_dwordx4 v[108:111], v[62:63], off
	v_add_u32_e32 v4, v66, v81
	v_add_u32_e32 v62, v66, v76
	v_add_u32_e32 v63, 0x420, v4
	v_add_u32_e32 v83, 0x428, v4
	v_add_u32_e32 v112, 0x840, v4
	v_add_u32_e32 v113, 0x848, v4
	v_add_u32_e32 v114, 0xc60, v4
	v_add_u32_e32 v115, 0xc68, v4
	v_add_u32_e32 v116, 0x1080, v4
	v_add_u32_e32 v117, 0x1088, v4
	v_add_u32_e32 v118, 0x14a0, v4
	v_add_u32_e32 v119, 0x420, v62
	v_add_u32_e32 v120, 0x428, v62
	v_add_u32_e32 v121, 0x840, v62
	v_add_u32_e32 v122, 0x848, v62
	s_add_i32 s11, s11, 64
	s_waitcnt vmcnt(7)
	ds_write2_b32 v4, v58, v59 offset1:1
	ds_write2_b32 v4, v60, v61 offset0:2 offset1:3
	s_waitcnt vmcnt(6)
	ds_write2_b32 v63, v84, v85 offset1:1
	ds_write2_b32 v83, v86, v87 offset1:1
	s_waitcnt vmcnt(5)
	ds_write2_b32 v112, v88, v89 offset1:1
	ds_write2_b32 v113, v90, v91 offset1:1
	s_waitcnt vmcnt(4)
	ds_write2_b32 v114, v92, v93 offset1:1
	ds_write2_b32 v115, v94, v95 offset1:1
	s_waitcnt vmcnt(3)
	ds_write2_b32 v116, v96, v97 offset1:1
	ds_write2_b32 v117, v98, v99 offset1:1
	s_waitcnt vmcnt(2)
	ds_write2_b32 v118, v100, v101 offset1:1
	ds_write2_b32 v62, v102, v103 offset0:2 offset1:3
	s_waitcnt vmcnt(1)
	ds_write2_b32 v119, v104, v105 offset1:1
	ds_write2_b32 v120, v106, v107 offset1:1
	s_waitcnt vmcnt(0)
	ds_write2_b32 v121, v108, v109 offset1:1
	ds_write2_b32 v122, v110, v111 offset1:1
	s_waitcnt lgkmcnt(0)
	ds_read2_b32 v[212:213], v79 offset1:33
	ds_read2_b32 v[214:215], v79 offset0:66 offset1:99
	ds_read2_b32 v[216:217], v79 offset0:132 offset1:165
	ds_read2_b32 v[218:219], v79 offset0:198 offset1:231
	ds_read2_b32 v[220:221], v79 offset0:8 offset1:41
	ds_read2_b32 v[222:223], v79 offset0:74 offset1:107
	ds_read2_b32 v[224:225], v79 offset0:140 offset1:173
	ds_read2_b32 v[226:227], v79 offset0:206 offset1:239
	ds_read2_b32 v[228:229], v79 offset0:16 offset1:49
	ds_read2_b32 v[230:231], v79 offset0:82 offset1:115
	ds_read2_b32 v[232:233], v79 offset0:148 offset1:181
	ds_read2_b32 v[234:235], v79 offset0:214 offset1:247
	ds_read2_b32 v[236:237], v79 offset0:24 offset1:57
	ds_read2_b32 v[238:239], v79 offset0:90 offset1:123
	ds_read2_b32 v[240:241], v79 offset0:156 offset1:189
	ds_read2_b32 v[242:243], v79 offset0:222 offset1:255
	s_waitcnt lgkmcnt(0)
	v_cvt_pk_bf16_f32 v58, v212, v213
	v_or_b32_e32 v4, s11, v65
	s_waitcnt lgkmcnt(0)
	v_cvt_pk_bf16_f32 v59, v214, v215
	v_lshlrev_b32_e32 v4, 7, v4
	s_waitcnt lgkmcnt(0)
	v_cvt_pk_bf16_f32 v60, v216, v217
	s_waitcnt lgkmcnt(0)
	v_cvt_pk_bf16_f32 v61, v218, v219
	v_lshl_add_u64 v[84:85], v[56:57], 0, v[4:5]
	global_store_dwordx4 v[84:85], v[58:61], off
	v_or_b32_e32 v4, s11, v67
	v_lshlrev_b32_e32 v4, 7, v4
	s_waitcnt lgkmcnt(0)
	v_cvt_pk_bf16_f32 v58, v220, v221
	s_waitcnt lgkmcnt(0)
	v_cvt_pk_bf16_f32 v59, v222, v223
	s_waitcnt lgkmcnt(0)
	v_cvt_pk_bf16_f32 v60, v224, v225
	s_waitcnt lgkmcnt(0)
	v_cvt_pk_bf16_f32 v61, v226, v227
	v_lshl_add_u64 v[84:85], v[56:57], 0, v[4:5]
	global_store_dwordx4 v[84:85], v[58:61], off
	v_or_b32_e32 v4, s11, v69
	v_lshlrev_b32_e32 v4, 7, v4
	s_waitcnt lgkmcnt(0)
	v_cvt_pk_bf16_f32 v58, v228, v229
	s_waitcnt lgkmcnt(0)
	v_cvt_pk_bf16_f32 v59, v230, v231
	s_waitcnt lgkmcnt(0)
	v_cvt_pk_bf16_f32 v60, v232, v233
	s_waitcnt lgkmcnt(0)
	v_cvt_pk_bf16_f32 v61, v234, v235
	v_lshl_add_u64 v[84:85], v[56:57], 0, v[4:5]
	global_store_dwordx4 v[84:85], v[58:61], off
	v_or_b32_e32 v4, s11, v71
	v_lshlrev_b32_e32 v4, 7, v4
	s_waitcnt lgkmcnt(0)
	v_cvt_pk_bf16_f32 v58, v236, v237
	s_waitcnt lgkmcnt(0)
	v_cvt_pk_bf16_f32 v59, v238, v239
	s_waitcnt lgkmcnt(0)
	v_cvt_pk_bf16_f32 v60, v240, v241
	s_waitcnt lgkmcnt(0)
	v_cvt_pk_bf16_f32 v61, v242, v243
	v_lshl_add_u64 v[62:63], v[56:57], 0, v[4:5]
	global_store_dwordx4 v[62:63], v[58:61], off
	s_waitcnt lgkmcnt(0)

.LBB0_218:
	s_andn2_b64 vcc, exec, s[4:5]
	s_cbranch_vccnz .LBB0_7
	s_cmpk_lg_i32 s9, 0x15a0
	s_cbranch_scc1 .LBB0_7
	s_load_dwordx2 s[4:5], s[16:17], 0x80
	s_lshl_b32 s9, s3, 5
	s_addk_i32 s9, 0x4c00
	s_and_b32 s9, s9, 0xffe0
	s_lshl_b32 s11, s9, 2
	s_waitcnt lgkmcnt(0)
	s_add_u32 s4, s4, s11
	s_addc_u32 s5, s5, 0
	v_lshlrev_b32_e32 v4, 2, v2
	v_lshl_add_u64 v[62:63], s[4:5], 0, v[4:5]
	v_lshl_add_u64 v[58:59], v[62:63], 0, v[28:29]
	global_load_dwordx4 v[58:61], v[58:59], off
	v_lshl_add_u64 v[84:85], v[62:63], 0, v[30:31]
	global_load_dwordx4 v[84:87], v[84:85], off
	v_lshl_add_u64 v[88:89], v[62:63], 0, v[32:33]
	global_load_dwordx4 v[88:91], v[88:89], off
	v_lshl_add_u64 v[92:93], v[62:63], 0, v[34:35]
	global_load_dwordx4 v[92:95], v[92:93], off
	v_lshl_add_u64 v[96:97], v[62:63], 0, v[36:37]
	global_load_dwordx4 v[96:99], v[96:97], off
	v_lshl_add_u64 v[100:101], v[62:63], 0, v[38:39]
	global_load_dwordx4 v[100:103], v[100:101], off
	v_lshl_add_u64 v[104:105], v[62:63], 0, v[40:41]
	global_load_dwordx4 v[104:107], v[104:105], off
	v_lshl_add_u64 v[62:63], v[62:63], 0, v[42:43]
	global_load_dwordx4 v[108:111], v[62:63], off
	v_add_u32_e32 v4, v66, v81
	v_add_u32_e32 v62, v66, v76
	v_add_u32_e32 v63, 0x420, v4
	v_add_u32_e32 v83, 0x428, v4
	v_add_u32_e32 v112, 0x840, v4
	v_add_u32_e32 v113, 0x848, v4
	v_add_u32_e32 v114, 0xc60, v4
	v_add_u32_e32 v115, 0xc68, v4
	v_add_u32_e32 v116, 0x1080, v4
	v_add_u32_e32 v117, 0x1088, v4
	v_add_u32_e32 v118, 0x14a0, v4
	v_add_u32_e32 v119, 0x420, v62
	v_add_u32_e32 v120, 0x428, v62
	v_add_u32_e32 v121, 0x840, v62
	v_add_u32_e32 v122, 0x848, v62
	s_waitcnt vmcnt(7)
	ds_write2_b32 v4, v58, v59 offset1:1
	ds_write2_b32 v4, v60, v61 offset0:2 offset1:3
	s_waitcnt vmcnt(6)
	ds_write2_b32 v63, v84, v85 offset1:1
	ds_write2_b32 v83, v86, v87 offset1:1
	s_waitcnt vmcnt(5)
	ds_write2_b32 v112, v88, v89 offset1:1
	ds_write2_b32 v113, v90, v91 offset1:1
	s_waitcnt vmcnt(4)
	ds_write2_b32 v114, v92, v93 offset1:1
	ds_write2_b32 v115, v94, v95 offset1:1
	s_waitcnt vmcnt(3)
	ds_write2_b32 v116, v96, v97 offset1:1
	ds_write2_b32 v117, v98, v99 offset1:1
	s_waitcnt vmcnt(2)
	ds_write2_b32 v118, v100, v101 offset1:1
	ds_write2_b32 v62, v102, v103 offset0:2 offset1:3
	s_waitcnt vmcnt(1)
	ds_write2_b32 v119, v104, v105 offset1:1
	ds_write2_b32 v120, v106, v107 offset1:1
	s_waitcnt vmcnt(0)
	ds_write2_b32 v121, v108, v109 offset1:1
	ds_write2_b32 v122, v110, v111 offset1:1
	s_waitcnt lgkmcnt(0)
	ds_read2_b32 v[212:213], v79 offset1:33
	ds_read2_b32 v[214:215], v79 offset0:66 offset1:99
	ds_read2_b32 v[216:217], v79 offset0:132 offset1:165
	ds_read2_b32 v[218:219], v79 offset0:198 offset1:231
	ds_read2_b32 v[220:221], v79 offset0:8 offset1:41
	ds_read2_b32 v[222:223], v79 offset0:74 offset1:107
	ds_read2_b32 v[224:225], v79 offset0:140 offset1:173
	ds_read2_b32 v[226:227], v79 offset0:206 offset1:239
	ds_read2_b32 v[228:229], v79 offset0:16 offset1:49
	ds_read2_b32 v[230:231], v79 offset0:82 offset1:115
	ds_read2_b32 v[232:233], v79 offset0:148 offset1:181
	ds_read2_b32 v[234:235], v79 offset0:214 offset1:247
	ds_read2_b32 v[236:237], v79 offset0:24 offset1:57
	ds_read2_b32 v[238:239], v79 offset0:90 offset1:123
	ds_read2_b32 v[240:241], v79 offset0:156 offset1:189
	ds_read2_b32 v[242:243], v79 offset0:222 offset1:255
	s_waitcnt lgkmcnt(0)
	v_cvt_pk_bf16_f32 v58, v212, v213
	v_or_b32_e32 v4, s9, v65
	s_waitcnt lgkmcnt(0)
	v_cvt_pk_bf16_f32 v59, v214, v215
	v_lshlrev_b32_e32 v4, 7, v4
	s_waitcnt lgkmcnt(0)
	v_cvt_pk_bf16_f32 v60, v216, v217
	s_waitcnt lgkmcnt(0)
	v_cvt_pk_bf16_f32 v61, v218, v219
	v_lshl_add_u64 v[84:85], v[56:57], 0, v[4:5]
	global_store_dwordx4 v[84:85], v[58:61], off
	v_or_b32_e32 v4, s9, v67
	v_lshlrev_b32_e32 v4, 7, v4
	s_waitcnt lgkmcnt(0)
	v_cvt_pk_bf16_f32 v58, v220, v221
	s_waitcnt lgkmcnt(0)
	v_cvt_pk_bf16_f32 v59, v222, v223
	s_waitcnt lgkmcnt(0)
	v_cvt_pk_bf16_f32 v60, v224, v225
	s_waitcnt lgkmcnt(0)
	v_cvt_pk_bf16_f32 v61, v226, v227
	v_lshl_add_u64 v[84:85], v[56:57], 0, v[4:5]
	global_store_dwordx4 v[84:85], v[58:61], off
	v_or_b32_e32 v4, s9, v69
	v_lshlrev_b32_e32 v4, 7, v4
	s_waitcnt lgkmcnt(0)
	v_cvt_pk_bf16_f32 v58, v228, v229
	s_waitcnt lgkmcnt(0)
	v_cvt_pk_bf16_f32 v59, v230, v231
	s_waitcnt lgkmcnt(0)
	v_cvt_pk_bf16_f32 v60, v232, v233
	s_waitcnt lgkmcnt(0)
	v_cvt_pk_bf16_f32 v61, v234, v235
	v_lshl_add_u64 v[84:85], v[56:57], 0, v[4:5]
	global_store_dwordx4 v[84:85], v[58:61], off
	v_or_b32_e32 v4, s9, v71
	v_lshlrev_b32_e32 v4, 7, v4
	s_waitcnt lgkmcnt(0)
	v_cvt_pk_bf16_f32 v58, v236, v237
	s_waitcnt lgkmcnt(0)
	v_cvt_pk_bf16_f32 v59, v238, v239
	s_waitcnt lgkmcnt(0)
	v_cvt_pk_bf16_f32 v60, v240, v241
	s_waitcnt lgkmcnt(0)
	v_cvt_pk_bf16_f32 v61, v242, v243
	v_lshl_add_u64 v[62:63], v[56:57], 0, v[4:5]
	global_store_dwordx4 v[62:63], v[58:61], off
	s_waitcnt lgkmcnt(0)
	s_branch .LBB0_7

.LBB0_885:
	s_cmpk_eq_i32 s31, 0xa00
	s_cbranch_scc0 .LBB0_887
	s_load_dwordx2 s[34:35], s[44:45], 0x118
	s_add_i32 s6, s22, 0xfffffc00
	s_and_b32 s7, s6, 0x1ffc0
	s_lshl_b32 s6, s2, 5
	s_and_b32 s6, s6, 0x3e0
	s_lshl_b32 s10, s6, 2
	s_waitcnt lgkmcnt(0)
	s_add_u32 s34, s34, s10
	v_or_b32_e32 v18, s7, v9
	s_addc_u32 s35, s35, 0
	v_lshlrev_b32_e32 v32, 12, v18
	v_or_b32_e32 v18, s7, v19
	v_lshl_add_u64 v[16:17], s[34:35], 0, v[0:1]
	v_mov_b32_e32 v33, v1
	v_lshlrev_b32_e32 v34, 12, v18
	v_mov_b32_e32 v35, v1
	v_lshl_add_u64 v[32:33], v[16:17], 0, v[32:33]
	v_lshl_add_u64 v[36:37], v[16:17], 0, v[34:35]
	v_or_b32_e32 v18, s7, v21
	global_load_dwordx4 v[32:35], v[32:33], off
	s_nop 0
	global_load_dwordx4 v[40:43], v[36:37], off
	v_lshlrev_b32_e32 v36, 12, v18
	v_or_b32_e32 v18, s7, v22
	v_mov_b32_e32 v37, v1
	v_lshlrev_b32_e32 v44, 12, v18
	v_mov_b32_e32 v45, v1
	v_lshl_add_u64 v[36:37], v[16:17], 0, v[36:37]
	v_lshl_add_u64 v[48:49], v[16:17], 0, v[44:45]
	v_or_b32_e32 v18, s7, v23
	global_load_dwordx4 v[44:47], v[36:37], off
	s_nop 0
	global_load_dwordx4 v[48:51], v[48:49], off
	v_lshlrev_b32_e32 v36, 12, v18
	v_or_b32_e32 v18, s7, v24
	v_mov_b32_e32 v37, v1
	v_lshlrev_b32_e32 v52, 12, v18
	v_mov_b32_e32 v53, v1
	v_lshl_add_u64 v[36:37], v[16:17], 0, v[36:37]
	v_lshl_add_u64 v[56:57], v[16:17], 0, v[52:53]
	global_load_dwordx4 v[52:55], v[36:37], off
	s_nop 0
	global_load_dwordx4 v[56:59], v[56:57], off
	v_or_b32_e32 v18, s7, v25
	v_lshlrev_b32_e32 v36, 12, v18
	v_mov_b32_e32 v37, v1
	v_lshl_add_u64 v[36:37], v[16:17], 0, v[36:37]
	v_or_b32_e32 v18, s7, v26
	global_load_dwordx4 v[60:63], v[36:37], off
	v_lshlrev_b32_e32 v36, 12, v18
	v_mov_b32_e32 v37, v1
	v_lshl_add_u64 v[16:17], v[16:17], 0, v[36:37]
	global_load_dwordx4 v[68:71], v[16:17], off
	v_add_u32_e32 v16, 0x420, v29
	v_add_u32_e32 v17, 0x428, v29
	v_add_u32_e32 v18, 0x840, v29
	v_add_u32_e32 v20, 0x848, v29
	v_add_u32_e32 v36, 0xc60, v29
	v_add_u32_e32 v37, 0xc68, v29
	v_add_u32_e32 v65, 0x1080, v29
	v_add_u32_e32 v72, 0x1088, v29
	v_add_u32_e32 v73, 0x14a0, v29
	v_add_u32_e32 v74, 0x14a8, v29
	v_add_u32_e32 v75, 0x18c0, v29
	v_add_u32_e32 v76, 0x18c8, v29
	v_add_u32_e32 v77, 0x1ce0, v29
	v_add_u32_e32 v78, 0x1ce8, v29
	s_lshl_b32 s10, s7, 1
	s_waitcnt vmcnt(7)
	ds_write2_b32 v29, v32, v33 offset1:1
	ds_write2_b32 v29, v34, v35 offset0:2 offset1:3
	s_waitcnt vmcnt(6)
	ds_write2_b32 v16, v40, v41 offset1:1
	ds_write2_b32 v17, v42, v43 offset1:1
	s_waitcnt vmcnt(5)
	ds_write2_b32 v18, v44, v45 offset1:1
	ds_write2_b32 v20, v46, v47 offset1:1
	s_waitcnt vmcnt(4)
	ds_write2_b32 v36, v48, v49 offset1:1
	ds_write2_b32 v37, v50, v51 offset1:1
	s_waitcnt vmcnt(3)
	ds_write2_b32 v65, v52, v53 offset1:1
	ds_write2_b32 v72, v54, v55 offset1:1
	s_waitcnt vmcnt(2)
	ds_write2_b32 v73, v56, v57 offset1:1
	ds_write2_b32 v74, v58, v59 offset1:1
	s_waitcnt vmcnt(1)
	ds_write2_b32 v75, v60, v61 offset1:1
	ds_write2_b32 v76, v62, v63 offset1:1
	s_waitcnt vmcnt(0)
	ds_write2_b32 v77, v68, v69 offset1:1
	ds_write2_b32 v78, v70, v71 offset1:1
	s_waitcnt lgkmcnt(0)
	ds_read2_b32 v[212:213], v27 offset1:33
	ds_read2_b32 v[214:215], v27 offset0:66 offset1:99
	ds_read2_b32 v[216:217], v27 offset0:132 offset1:165
	ds_read2_b32 v[218:219], v27 offset0:198 offset1:231
	ds_read2_b32 v[220:221], v27 offset0:8 offset1:41
	ds_read2_b32 v[222:223], v27 offset0:74 offset1:107
	ds_read2_b32 v[224:225], v27 offset0:140 offset1:173
	ds_read2_b32 v[226:227], v27 offset0:206 offset1:239
	ds_read2_b32 v[228:229], v27 offset0:16 offset1:49
	ds_read2_b32 v[230:231], v27 offset0:82 offset1:115
	ds_read2_b32 v[232:233], v27 offset0:148 offset1:181
	ds_read2_b32 v[234:235], v27 offset0:214 offset1:247
	ds_read2_b32 v[236:237], v27 offset0:24 offset1:57
	ds_read2_b32 v[238:239], v27 offset0:90 offset1:123
	ds_read2_b32 v[240:241], v27 offset0:156 offset1:189
	ds_read2_b32 v[242:243], v27 offset0:222 offset1:255
	s_waitcnt lgkmcnt(0)
	v_cvt_pk_bf16_f32 v32, v212, v213
	s_waitcnt lgkmcnt(0)
	v_cvt_pk_bf16_f32 v33, v214, v215
	v_or_b32_e32 v18, s6, v9
	s_waitcnt lgkmcnt(0)
	v_cvt_pk_bf16_f32 v34, v216, v217
	v_mov_b32_e32 v37, v1
	v_lshlrev_b32_e32 v36, 11, v18
	v_lshl_add_u64 v[40:41], v[4:5], 0, s[10:11]
	s_waitcnt lgkmcnt(0)
	v_cvt_pk_bf16_f32 v35, v218, v219
	v_lshl_add_u64 v[36:37], v[40:41], 0, v[36:37]
	global_store_dwordx4 v[36:37], v[32:35], off
	v_or_b32_e32 v18, s6, v19
	v_mov_b32_e32 v37, v1
	s_waitcnt lgkmcnt(0)
	v_cvt_pk_bf16_f32 v32, v220, v221
	s_waitcnt lgkmcnt(0)
	v_cvt_pk_bf16_f32 v33, v222, v223
	s_waitcnt lgkmcnt(0)
	v_cvt_pk_bf16_f32 v34, v224, v225
	v_lshlrev_b32_e32 v36, 11, v18
	s_waitcnt lgkmcnt(0)
	v_cvt_pk_bf16_f32 v35, v226, v227
	v_lshl_add_u64 v[36:37], v[40:41], 0, v[36:37]
	global_store_dwordx4 v[36:37], v[32:35], off
	v_or_b32_e32 v18, s6, v21
	v_mov_b32_e32 v37, v1
	s_waitcnt lgkmcnt(0)
	v_cvt_pk_bf16_f32 v32, v228, v229
	s_waitcnt lgkmcnt(0)
	v_cvt_pk_bf16_f32 v33, v230, v231
	s_waitcnt lgkmcnt(0)
	v_cvt_pk_bf16_f32 v34, v232, v233
	v_lshlrev_b32_e32 v36, 11, v18
	s_waitcnt lgkmcnt(0)
	v_cvt_pk_bf16_f32 v35, v234, v235
	v_lshl_add_u64 v[36:37], v[40:41], 0, v[36:37]
	global_store_dwordx4 v[36:37], v[32:35], off
	v_or_b32_e32 v18, s6, v22
	v_mov_b32_e32 v37, v1
	s_waitcnt lgkmcnt(0)
	v_cvt_pk_bf16_f32 v32, v236, v237
	s_waitcnt lgkmcnt(0)
	v_cvt_pk_bf16_f32 v33, v238, v239
	s_waitcnt lgkmcnt(0)
	v_cvt_pk_bf16_f32 v34, v240, v241
	v_lshlrev_b32_e32 v36, 11, v18
	s_waitcnt lgkmcnt(0)
	v_cvt_pk_bf16_f32 v35, v242, v243
	v_lshl_add_u64 v[16:17], v[40:41], 0, v[36:37]
	global_store_dwordx4 v[16:17], v[32:35], off
	s_waitcnt lgkmcnt(0)

.LBB0_892:
	v_or_b32_e32 v20, s10, v26
	v_mad_u64_u32 v[16:17], s[6:7], v20, s27, v[16:17]
	global_load_dwordx4 v[32:35], v[16:17], off
	v_add_u32_e32 v20, 0x14a0, v31
	s_and_b32 s6, 0xffff, s31
	v_add_u32_e32 v36, 0x14a8, v31
	s_lshl_b32 s10, s10, 1
	s_lshr_b32 s31, s6, 4
	v_lshl_add_u64 v[40:41], v[2:3], 0, s[10:11]
	s_lshr_b32 s7, s6, 6
	s_lshl_b32 s10, s6, 2
	s_and_b32 s6, s6, 0x60
	s_and_b32 s31, s31, 0x80
	s_and_b32 s7, s7, 16
	s_or_b32 s33, s31, s6
	s_and_b32 s10, s10, 0xe00
	s_or_b32 s33, s33, s7
	s_or_b32 s33, s33, s10
	v_mov_b32_e32 v37, v1
	v_mov_b32_e32 v43, v1
	s_waitcnt vmcnt(0)
	v_pk_mul_f32 v[32:33], v[32:33], v[18:19] op_sel_hi:[1,0]
	v_pk_mul_f32 v[16:17], v[34:35], v[18:19] op_sel_hi:[1,0]
	ds_write2_b32 v20, v32, v33 offset1:1
	ds_write2_b32 v36, v16, v17 offset1:1
	s_waitcnt lgkmcnt(0)
	ds_read2_b32 v[212:213], v27 offset1:33
	ds_read2_b32 v[214:215], v27 offset0:66 offset1:99
	ds_read2_b32 v[216:217], v27 offset0:132 offset1:165
	ds_read2_b32 v[218:219], v27 offset0:198 offset1:231
	ds_read2_b32 v[220:221], v27 offset0:8 offset1:41
	ds_read2_b32 v[222:223], v27 offset0:74 offset1:107
	ds_read2_b32 v[224:225], v27 offset0:140 offset1:173
	ds_read2_b32 v[226:227], v27 offset0:206 offset1:239
	ds_read2_b32 v[228:229], v27 offset0:16 offset1:49
	ds_read2_b32 v[230:231], v27 offset0:82 offset1:115
	ds_read2_b32 v[232:233], v27 offset0:148 offset1:181
	ds_read2_b32 v[234:235], v27 offset0:214 offset1:247
	ds_read2_b32 v[236:237], v27 offset0:24 offset1:57
	ds_read2_b32 v[238:239], v27 offset0:90 offset1:123
	ds_read2_b32 v[240:241], v27 offset0:156 offset1:189
	ds_read2_b32 v[242:243], v27 offset0:222 offset1:255
	s_waitcnt lgkmcnt(0)
	v_cvt_pk_bf16_f32 v32, v212, v213
	s_waitcnt lgkmcnt(0)
	v_cvt_pk_bf16_f32 v33, v214, v215
	v_or_b32_e32 v18, s33, v9
	s_waitcnt lgkmcnt(0)
	v_cvt_pk_bf16_f32 v34, v216, v217
	v_lshlrev_b32_e32 v36, 11, v18
	s_waitcnt lgkmcnt(0)
	v_cvt_pk_bf16_f32 v35, v218, v219
	v_lshl_add_u64 v[36:37], v[40:41], 0, v[36:37]
	global_store_dwordx4 v[36:37], v[32:35], off
	v_or_b32_e32 v18, s33, v19
	v_lshlrev_b32_e32 v42, 11, v18
	s_waitcnt lgkmcnt(0)
	v_cvt_pk_bf16_f32 v32, v220, v221
	s_waitcnt lgkmcnt(0)
	v_cvt_pk_bf16_f32 v33, v222, v223
	s_waitcnt lgkmcnt(0)
	v_cvt_pk_bf16_f32 v34, v224, v225
	v_or_b32_e32 v18, s6, v28
	s_waitcnt lgkmcnt(0)
	v_cvt_pk_bf16_f32 v35, v226, v227
	v_lshl_add_u64 v[42:43], v[40:41], 0, v[42:43]
	v_or_b32_e32 v18, s31, v18
	global_store_dwordx4 v[42:43], v[32:35], off
	v_add_co_u32_e32 v36, vcc, s28, v36
	s_waitcnt lgkmcnt(0)
	v_cvt_pk_bf16_f32 v32, v228, v229
	v_or_b32_e32 v18, s7, v18
	s_waitcnt lgkmcnt(0)
	v_cvt_pk_bf16_f32 v33, v230, v231
	v_addc_co_u32_e32 v37, vcc, 0, v37, vcc
	v_or_b32_e32 v18, s10, v18
	s_waitcnt lgkmcnt(0)
	v_cvt_pk_bf16_f32 v34, v232, v233
	s_waitcnt lgkmcnt(0)
	v_cvt_pk_bf16_f32 v35, v234, v235
	global_store_dwordx4 v[36:37], v[32:35], off
	v_mov_b32_e32 v37, v1
	v_lshlrev_b32_e32 v36, 11, v18
	v_lshl_add_u64 v[36:37], v[40:41], 0, v[36:37]
	s_waitcnt lgkmcnt(0)
	v_cvt_pk_bf16_f32 v32, v236, v237
	v_add_co_u32_e32 v36, vcc, 0x80000, v36
	s_waitcnt lgkmcnt(0)
	v_cvt_pk_bf16_f32 v33, v238, v239
	v_addc_co_u32_e32 v37, vcc, 0, v37, vcc
	s_waitcnt lgkmcnt(0)
	v_cvt_pk_bf16_f32 v34, v240, v241
	s_waitcnt lgkmcnt(0)
	v_cvt_pk_bf16_f32 v35, v242, v243
	global_store_dwordx4 v[36:37], v[32:35], off
	s_waitcnt lgkmcnt(0)
	s_and_b32 s31, s2, 0xfffffe00
	s_cmpk_lt_i32 s31, 0xa00
	s_mov_b64 s[6:7], -1
	s_cbranch_scc0 .LBB0_885

.LBB0_894:
	s_cmpk_lg_i32 s31, 0x800
	s_cbranch_scc1 .LBB0_896
	s_load_dwordx2 s[34:35], s[44:45], 0x110
	s_lshl_b32 s6, s2, 5
	s_and_b32 s6, s6, 0x3e0
	s_and_b32 s7, s22, 0x1ffc0
	s_lshl_b32 s10, s6, 2
	s_waitcnt lgkmcnt(0)
	s_add_u32 s34, s34, s10
	v_or_b32_e32 v18, s7, v9
	s_addc_u32 s35, s35, 0
	v_lshlrev_b32_e32 v32, 12, v18
	v_or_b32_e32 v18, s7, v19
	v_lshl_add_u64 v[16:17], s[34:35], 0, v[0:1]
	v_mov_b32_e32 v33, v1
	v_lshlrev_b32_e32 v34, 12, v18
	v_mov_b32_e32 v35, v1
	v_lshl_add_u64 v[32:33], v[16:17], 0, v[32:33]
	v_lshl_add_u64 v[36:37], v[16:17], 0, v[34:35]
	v_or_b32_e32 v18, s7, v21
	global_load_dwordx4 v[32:35], v[32:33], off
	s_nop 0
	global_load_dwordx4 v[40:43], v[36:37], off
	v_lshlrev_b32_e32 v36, 12, v18
	v_or_b32_e32 v18, s7, v22
	v_mov_b32_e32 v37, v1
	v_lshlrev_b32_e32 v44, 12, v18
	v_mov_b32_e32 v45, v1
	v_lshl_add_u64 v[36:37], v[16:17], 0, v[36:37]
	v_lshl_add_u64 v[48:49], v[16:17], 0, v[44:45]
	v_or_b32_e32 v18, s7, v23
	global_load_dwordx4 v[44:47], v[36:37], off
	s_nop 0
	global_load_dwordx4 v[48:51], v[48:49], off
	v_lshlrev_b32_e32 v36, 12, v18
	v_or_b32_e32 v18, s7, v24
	v_mov_b32_e32 v37, v1
	v_lshlrev_b32_e32 v52, 12, v18
	v_mov_b32_e32 v53, v1
	v_lshl_add_u64 v[36:37], v[16:17], 0, v[36:37]
	v_lshl_add_u64 v[56:57], v[16:17], 0, v[52:53]
	global_load_dwordx4 v[52:55], v[36:37], off
	s_nop 0
	global_load_dwordx4 v[56:59], v[56:57], off
	v_or_b32_e32 v18, s7, v25
	v_lshlrev_b32_e32 v36, 12, v18
	v_mov_b32_e32 v37, v1
	v_lshl_add_u64 v[36:37], v[16:17], 0, v[36:37]
	v_or_b32_e32 v18, s7, v26
	global_load_dwordx4 v[60:63], v[36:37], off
	v_lshlrev_b32_e32 v36, 12, v18
	v_mov_b32_e32 v37, v1
	v_lshl_add_u64 v[16:17], v[16:17], 0, v[36:37]
	global_load_dwordx4 v[68:71], v[16:17], off
	v_add_u32_e32 v16, 0x420, v29
	v_add_u32_e32 v17, 0x428, v29
	v_add_u32_e32 v18, 0x840, v29
	v_add_u32_e32 v20, 0x848, v29
	v_add_u32_e32 v36, 0xc60, v29
	v_add_u32_e32 v37, 0xc68, v29
	v_add_u32_e32 v65, 0x1080, v29
	v_add_u32_e32 v72, 0x1088, v29
	v_add_u32_e32 v73, 0x14a0, v29
	v_add_u32_e32 v74, 0x14a8, v29
	v_add_u32_e32 v75, 0x18c0, v29
	v_add_u32_e32 v76, 0x18c8, v29
	v_add_u32_e32 v77, 0x1ce0, v29
	v_add_u32_e32 v78, 0x1ce8, v29
	s_lshl_b32 s10, s7, 1
	s_waitcnt vmcnt(7)
	ds_write2_b32 v29, v32, v33 offset1:1
	ds_write2_b32 v29, v34, v35 offset0:2 offset1:3
	s_waitcnt vmcnt(6)
	ds_write2_b32 v16, v40, v41 offset1:1
	ds_write2_b32 v17, v42, v43 offset1:1
	s_waitcnt vmcnt(5)
	ds_write2_b32 v18, v44, v45 offset1:1
	ds_write2_b32 v20, v46, v47 offset1:1
	s_waitcnt vmcnt(4)
	ds_write2_b32 v36, v48, v49 offset1:1
	ds_write2_b32 v37, v50, v51 offset1:1
	s_waitcnt vmcnt(3)
	ds_write2_b32 v65, v52, v53 offset1:1
	ds_write2_b32 v72, v54, v55 offset1:1
	s_waitcnt vmcnt(2)
	ds_write2_b32 v73, v56, v57 offset1:1
	ds_write2_b32 v74, v58, v59 offset1:1
	s_waitcnt vmcnt(1)
	ds_write2_b32 v75, v60, v61 offset1:1
	ds_write2_b32 v76, v62, v63 offset1:1
	s_waitcnt vmcnt(0)
	ds_write2_b32 v77, v68, v69 offset1:1
	ds_write2_b32 v78, v70, v71 offset1:1
	s_waitcnt lgkmcnt(0)
	ds_read2_b32 v[212:213], v27 offset1:33
	ds_read2_b32 v[214:215], v27 offset0:66 offset1:99
	ds_read2_b32 v[216:217], v27 offset0:132 offset1:165
	ds_read2_b32 v[218:219], v27 offset0:198 offset1:231
	ds_read2_b32 v[220:221], v27 offset0:8 offset1:41
	ds_read2_b32 v[222:223], v27 offset0:74 offset1:107
	ds_read2_b32 v[224:225], v27 offset0:140 offset1:173
	ds_read2_b32 v[226:227], v27 offset0:206 offset1:239
	ds_read2_b32 v[228:229], v27 offset0:16 offset1:49
	ds_read2_b32 v[230:231], v27 offset0:82 offset1:115
	ds_read2_b32 v[232:233], v27 offset0:148 offset1:181
	ds_read2_b32 v[234:235], v27 offset0:214 offset1:247
	ds_read2_b32 v[236:237], v27 offset0:24 offset1:57
	ds_read2_b32 v[238:239], v27 offset0:90 offset1:123
	ds_read2_b32 v[240:241], v27 offset0:156 offset1:189
	ds_read2_b32 v[242:243], v27 offset0:222 offset1:255
	s_waitcnt lgkmcnt(0)
	v_cvt_pk_bf16_f32 v32, v212, v213
	s_waitcnt lgkmcnt(0)
	v_cvt_pk_bf16_f32 v33, v214, v215
	v_or_b32_e32 v18, s6, v9
	s_waitcnt lgkmcnt(0)
	v_cvt_pk_bf16_f32 v34, v216, v217
	v_mov_b32_e32 v37, v1
	v_lshlrev_b32_e32 v36, 11, v18
	v_lshl_add_u64 v[40:41], v[6:7], 0, s[10:11]
	s_waitcnt lgkmcnt(0)
	v_cvt_pk_bf16_f32 v35, v218, v219
	v_lshl_add_u64 v[36:37], v[40:41], 0, v[36:37]
	global_store_dwordx4 v[36:37], v[32:35], off
	v_or_b32_e32 v18, s6, v19
	v_mov_b32_e32 v37, v1
	s_waitcnt lgkmcnt(0)
	v_cvt_pk_bf16_f32 v32, v220, v221
	s_waitcnt lgkmcnt(0)
	v_cvt_pk_bf16_f32 v33, v222, v223
	s_waitcnt lgkmcnt(0)
	v_cvt_pk_bf16_f32 v34, v224, v225
	v_lshlrev_b32_e32 v36, 11, v18
	s_waitcnt lgkmcnt(0)
	v_cvt_pk_bf16_f32 v35, v226, v227
	v_lshl_add_u64 v[36:37], v[40:41], 0, v[36:37]
	global_store_dwordx4 v[36:37], v[32:35], off
	v_or_b32_e32 v18, s6, v21
	v_mov_b32_e32 v37, v1
	s_waitcnt lgkmcnt(0)
	v_cvt_pk_bf16_f32 v32, v228, v229
	s_waitcnt lgkmcnt(0)
	v_cvt_pk_bf16_f32 v33, v230, v231
	s_waitcnt lgkmcnt(0)
	v_cvt_pk_bf16_f32 v34, v232, v233
	v_lshlrev_b32_e32 v36, 11, v18
	s_waitcnt lgkmcnt(0)
	v_cvt_pk_bf16_f32 v35, v234, v235
	v_lshl_add_u64 v[36:37], v[40:41], 0, v[36:37]
	global_store_dwordx4 v[36:37], v[32:35], off
	v_or_b32_e32 v18, s6, v22
	v_mov_b32_e32 v37, v1
	s_waitcnt lgkmcnt(0)
	v_cvt_pk_bf16_f32 v32, v236, v237
	s_waitcnt lgkmcnt(0)
	v_cvt_pk_bf16_f32 v33, v238, v239
	s_waitcnt lgkmcnt(0)
	v_cvt_pk_bf16_f32 v34, v240, v241
	v_lshlrev_b32_e32 v36, 11, v18
	s_waitcnt lgkmcnt(0)
	v_cvt_pk_bf16_f32 v35, v242, v243
	v_lshl_add_u64 v[16:17], v[40:41], 0, v[36:37]
	global_store_dwordx4 v[16:17], v[32:35], off
	s_waitcnt lgkmcnt(0)

.LBB0_913:
	v_or_b32_e32 v18, s10, v26
	v_mad_u64_u32 v[16:17], s[34:35], v18, s29, v[16:17]
	v_add_u32_e32 v18, 0x14a0, v31
	v_add_u32_e32 v36, 0x14a8, v31
	s_lshl_b32 s31, s31, 5
	s_lshl_b32 s10, s10, 1
	s_and_b32 s31, 0xffff, s31
	v_lshl_add_u64 v[40:41], v[10:11], 0, s[10:11]
	s_lshl_b32 s10, s31, 1
	s_and_b32 s31, s31, 0x60
	s_and_b32 s10, s10, 0x1f00
	s_or_b32 s10, s10, s31
	v_mov_b32_e32 v37, v1
	s_waitcnt vmcnt(0)
	v_pk_mul_f32 v[32:33], v[236:237], v[20:21] op_sel_hi:[1,0]
	v_pk_mul_f32 v[16:17], v[238:239], v[20:21] op_sel_hi:[1,0]
	ds_write2_b32 v18, v32, v33 offset1:1
	ds_write2_b32 v36, v16, v17 offset1:1
	s_waitcnt lgkmcnt(0)
	ds_read2_b32 v[212:213], v27 offset1:33
	ds_read2_b32 v[214:215], v27 offset0:66 offset1:99
	ds_read2_b32 v[216:217], v27 offset0:132 offset1:165
	ds_read2_b32 v[218:219], v27 offset0:198 offset1:231
	ds_read2_b32 v[220:221], v27 offset0:8 offset1:41
	ds_read2_b32 v[222:223], v27 offset0:74 offset1:107
	ds_read2_b32 v[224:225], v27 offset0:140 offset1:173
	ds_read2_b32 v[226:227], v27 offset0:206 offset1:239
	ds_read2_b32 v[228:229], v27 offset0:16 offset1:49
	ds_read2_b32 v[230:231], v27 offset0:82 offset1:115
	ds_read2_b32 v[232:233], v27 offset0:148 offset1:181
	ds_read2_b32 v[234:235], v27 offset0:214 offset1:247
	ds_read2_b32 v[236:237], v27 offset0:24 offset1:57
	ds_read2_b32 v[238:239], v27 offset0:90 offset1:123
	ds_read2_b32 v[240:241], v27 offset0:156 offset1:189
	ds_read2_b32 v[242:243], v27 offset0:222 offset1:255
	s_waitcnt lgkmcnt(0)
	v_cvt_pk_bf16_f32 v32, v212, v213
	s_waitcnt lgkmcnt(0)
	v_cvt_pk_bf16_f32 v33, v214, v215
	v_or_b32_e32 v18, s10, v9
	s_waitcnt lgkmcnt(0)
	v_cvt_pk_bf16_f32 v34, v216, v217
	v_lshlrev_b32_e32 v36, 11, v18
	s_waitcnt lgkmcnt(0)
	v_cvt_pk_bf16_f32 v35, v218, v219
	v_lshl_add_u64 v[36:37], v[40:41], 0, v[36:37]
	global_store_dwordx4 v[36:37], v[32:35], off
	v_or_b32_e32 v18, s10, v19
	v_mov_b32_e32 v37, v1
	s_waitcnt lgkmcnt(0)
	v_cvt_pk_bf16_f32 v32, v220, v221
	s_waitcnt lgkmcnt(0)
	v_cvt_pk_bf16_f32 v33, v222, v223
	s_waitcnt lgkmcnt(0)
	v_cvt_pk_bf16_f32 v34, v224, v225
	v_lshlrev_b32_e32 v36, 11, v18
	s_waitcnt lgkmcnt(0)
	v_cvt_pk_bf16_f32 v35, v226, v227
	v_lshl_add_u64 v[36:37], v[40:41], 0, v[36:37]
	global_store_dwordx4 v[36:37], v[32:35], off
	v_or_b32_e32 v18, s10, v21
	v_mov_b32_e32 v37, v1
	s_waitcnt lgkmcnt(0)
	v_cvt_pk_bf16_f32 v32, v228, v229
	s_waitcnt lgkmcnt(0)
	v_cvt_pk_bf16_f32 v33, v230, v231
	s_waitcnt lgkmcnt(0)
	v_cvt_pk_bf16_f32 v34, v232, v233
	v_lshlrev_b32_e32 v36, 11, v18
	s_waitcnt lgkmcnt(0)
	v_cvt_pk_bf16_f32 v35, v234, v235
	v_lshl_add_u64 v[36:37], v[40:41], 0, v[36:37]
	global_store_dwordx4 v[36:37], v[32:35], off
	v_or_b32_e32 v18, s10, v22
	v_mov_b32_e32 v37, v1
	s_waitcnt lgkmcnt(0)
	v_cvt_pk_bf16_f32 v32, v236, v237
	s_waitcnt lgkmcnt(0)
	v_cvt_pk_bf16_f32 v33, v238, v239
	s_waitcnt lgkmcnt(0)
	v_cvt_pk_bf16_f32 v34, v240, v241
	v_lshlrev_b32_e32 v36, 11, v18
	s_waitcnt lgkmcnt(0)
	v_cvt_pk_bf16_f32 v35, v242, v243
	v_lshl_add_u64 v[16:17], v[40:41], 0, v[36:37]
	global_store_dwordx4 v[16:17], v[32:35], off
	s_waitcnt lgkmcnt(0)

.LBB0_931:
	v_or_b32_e32 v18, s10, v26
	v_mad_u64_u32 v[16:17], s[6:7], v18, s29, v[16:17]
	s_lshl_b32 s6, s31, 5
	s_and_b32 s6, 0xffff, s6
	s_lshl_b32 s7, s6, 1
	v_add_u32_e32 v18, 0x14a0, v31
	s_and_b32 s6, s6, 0x60
	s_and_b32 s7, s7, 0x1f00
	v_add_u32_e32 v36, 0x14a8, v31
	s_or_b32 s6, s7, s6
	s_lshl_b32 s10, s10, 1
	v_mov_b32_e32 v37, v1
	v_lshl_add_u64 v[40:41], v[10:11], 0, s[10:11]
	s_waitcnt vmcnt(0)
	v_pk_mul_f32 v[32:33], v[236:237], v[20:21] op_sel_hi:[1,0]
	v_pk_mul_f32 v[16:17], v[238:239], v[20:21] op_sel_hi:[1,0]
	ds_write2_b32 v18, v32, v33 offset1:1
	ds_write2_b32 v36, v16, v17 offset1:1
	s_waitcnt lgkmcnt(0)
	v_or_b32_e32 v18, s6, v9
	v_lshlrev_b32_e32 v36, 11, v18
	ds_read2_b32 v[212:213], v27 offset1:33
	ds_read2_b32 v[214:215], v27 offset0:66 offset1:99
	ds_read2_b32 v[216:217], v27 offset0:132 offset1:165
	ds_read2_b32 v[218:219], v27 offset0:198 offset1:231
	ds_read2_b32 v[220:221], v27 offset0:8 offset1:41
	ds_read2_b32 v[222:223], v27 offset0:74 offset1:107
	ds_read2_b32 v[224:225], v27 offset0:140 offset1:173
	ds_read2_b32 v[226:227], v27 offset0:206 offset1:239
	ds_read2_b32 v[228:229], v27 offset0:16 offset1:49
	ds_read2_b32 v[230:231], v27 offset0:82 offset1:115
	ds_read2_b32 v[232:233], v27 offset0:148 offset1:181
	ds_read2_b32 v[234:235], v27 offset0:214 offset1:247
	ds_read2_b32 v[236:237], v27 offset0:24 offset1:57
	ds_read2_b32 v[238:239], v27 offset0:90 offset1:123
	ds_read2_b32 v[240:241], v27 offset0:156 offset1:189
	ds_read2_b32 v[242:243], v27 offset0:222 offset1:255
	v_lshl_add_u64 v[36:37], v[40:41], 0, v[36:37]
	s_waitcnt lgkmcnt(0)
	v_cvt_pk_bf16_f32 v32, v212, v213
	v_add_co_u32_e32 v36, vcc, s30, v36
	s_waitcnt lgkmcnt(0)
	v_cvt_pk_bf16_f32 v33, v214, v215
	v_addc_co_u32_e32 v37, vcc, 0, v37, vcc
	v_or_b32_e32 v18, s6, v19
	s_waitcnt lgkmcnt(0)
	v_cvt_pk_bf16_f32 v34, v216, v217
	s_waitcnt lgkmcnt(0)
	v_cvt_pk_bf16_f32 v35, v218, v219
	global_store_dwordx4 v[36:37], v[32:35], off
	v_mov_b32_e32 v37, v1
	v_lshlrev_b32_e32 v36, 11, v18
	v_lshl_add_u64 v[36:37], v[40:41], 0, v[36:37]
	s_waitcnt lgkmcnt(0)
	v_cvt_pk_bf16_f32 v32, v220, v221
	v_add_co_u32_e32 v36, vcc, s30, v36
	s_waitcnt lgkmcnt(0)
	v_cvt_pk_bf16_f32 v33, v222, v223
	v_addc_co_u32_e32 v37, vcc, 0, v37, vcc
	v_or_b32_e32 v18, s6, v21
	s_waitcnt lgkmcnt(0)
	v_cvt_pk_bf16_f32 v34, v224, v225
	s_waitcnt lgkmcnt(0)
	v_cvt_pk_bf16_f32 v35, v226, v227
	global_store_dwordx4 v[36:37], v[32:35], off
	v_mov_b32_e32 v37, v1
	v_lshlrev_b32_e32 v36, 11, v18
	v_lshl_add_u64 v[36:37], v[40:41], 0, v[36:37]
	s_waitcnt lgkmcnt(0)
	v_cvt_pk_bf16_f32 v32, v228, v229
	v_add_co_u32_e32 v36, vcc, s30, v36
	s_waitcnt lgkmcnt(0)
	v_cvt_pk_bf16_f32 v33, v230, v231
	v_addc_co_u32_e32 v37, vcc, 0, v37, vcc
	v_or_b32_e32 v18, s6, v22
	s_waitcnt lgkmcnt(0)
	v_cvt_pk_bf16_f32 v34, v232, v233
	s_waitcnt lgkmcnt(0)
	v_cvt_pk_bf16_f32 v35, v234, v235
	global_store_dwordx4 v[36:37], v[32:35], off
	v_mov_b32_e32 v37, v1
	v_lshlrev_b32_e32 v36, 11, v18
	v_lshl_add_u64 v[36:37], v[40:41], 0, v[36:37]
	s_waitcnt lgkmcnt(0)
	v_cvt_pk_bf16_f32 v32, v236, v237
	v_add_co_u32_e32 v36, vcc, 0x40000, v36
	s_waitcnt lgkmcnt(0)
	v_cvt_pk_bf16_f32 v33, v238, v239
	v_addc_co_u32_e32 v37, vcc, 0, v37, vcc
	s_waitcnt lgkmcnt(0)
	v_cvt_pk_bf16_f32 v34, v240, v241
	s_waitcnt lgkmcnt(0)
	v_cvt_pk_bf16_f32 v35, v242, v243
	global_store_dwordx4 v[36:37], v[32:35], off
	s_waitcnt lgkmcnt(0)
.LBB0_932:
	s_add_i32 s6, s2, 0xffffe900
	s_cmpk_gt_u32 s6, 0x57f
	v_add_u32_e32 v16, 0x420, v29
	v_add_u32_e32 v17, 0x428, v29
	v_add_u32_e32 v18, 0x840, v29
	v_add_u32_e32 v20, 0x848, v29
	v_add_u32_e32 v32, 0xc60, v29
	v_add_u32_e32 v33, 0xc68, v29
	v_add_u32_e32 v34, 0x1080, v29
	v_add_u32_e32 v35, 0x1088, v29
	v_add_u32_e32 v36, 0x14a0, v29
	v_add_u32_e32 v37, 0x14a8, v29
	v_add_u32_e32 v40, 0x18c0, v29
	v_add_u32_e32 v41, 0x18c8, v29
	v_add_u32_e32 v42, 0x1ce0, v29
	v_add_u32_e32 v43, 0x1ce8, v29
	s_cbranch_scc1 .LBB0_934
	s_load_dwordx2 s[34:35], s[44:45], 0x138
	s_add_i32 s6, s22, 0xfffde200
	s_and_b32 s7, s6, 0xfc0
	s_lshl_b32 s6, s2, 5
	s_and_b32 s6, s6, 0x3e0
	s_lshl_b32 s10, s6, 2
	s_waitcnt lgkmcnt(0)
	s_add_u32 s34, s34, s10
	s_addc_u32 s35, s35, 0
	v_or_b32_e32 v44, s7, v9
	v_or_b32_e32 v46, s7, v19
	v_or_b32_e32 v52, s7, v21
	v_or_b32_e32 v54, s7, v22
	v_or_b32_e32 v60, s7, v23
	v_or_b32_e32 v62, s7, v24
	v_lshl_add_u64 v[76:77], s[34:35], 0, v[0:1]
	v_lshlrev_b32_e32 v44, 12, v44
	v_mov_b32_e32 v45, v1
	v_lshlrev_b32_e32 v46, 12, v46
	v_mov_b32_e32 v47, v1
	v_lshlrev_b32_e32 v52, 12, v52
	v_mov_b32_e32 v53, v1
	v_lshlrev_b32_e32 v54, 12, v54
	v_mov_b32_e32 v55, v1
	v_lshlrev_b32_e32 v60, 12, v60
	v_mov_b32_e32 v61, v1
	v_lshlrev_b32_e32 v62, 12, v62
	v_mov_b32_e32 v63, v1
	v_lshl_add_u64 v[44:45], v[76:77], 0, v[44:45]
	v_lshl_add_u64 v[48:49], v[76:77], 0, v[46:47]
	v_lshl_add_u64 v[52:53], v[76:77], 0, v[52:53]
	v_lshl_add_u64 v[56:57], v[76:77], 0, v[54:55]
	v_lshl_add_u64 v[60:61], v[76:77], 0, v[60:61]
	v_lshl_add_u64 v[68:69], v[76:77], 0, v[62:63]
	global_load_dwordx4 v[44:47], v[44:45], off
	s_nop 0
	global_load_dwordx4 v[48:51], v[48:49], off
	s_nop 0
	global_load_dwordx4 v[52:55], v[52:53], off
	s_nop 0
	global_load_dwordx4 v[56:59], v[56:57], off
	s_nop 0
	global_load_dwordx4 v[60:63], v[60:61], off
	s_nop 0
	global_load_dwordx4 v[68:71], v[68:69], off
	v_or_b32_e32 v65, s7, v25
	v_lshlrev_b32_e32 v72, 12, v65
	v_mov_b32_e32 v73, v1
	v_lshl_add_u64 v[72:73], v[76:77], 0, v[72:73]
	v_or_b32_e32 v65, s7, v26
	global_load_dwordx4 v[72:75], v[72:73], off
	v_lshlrev_b32_e32 v78, 12, v65
	v_mov_b32_e32 v79, v1
	v_lshl_add_u64 v[76:77], v[76:77], 0, v[78:79]
	global_load_dwordx4 v[76:79], v[76:77], off
	s_lshl_b32 s10, s7, 1
	s_waitcnt vmcnt(7)
	ds_write2_b32 v29, v44, v45 offset1:1
	ds_write2_b32 v29, v46, v47 offset0:2 offset1:3
	s_waitcnt vmcnt(6)
	ds_write2_b32 v16, v48, v49 offset1:1
	ds_write2_b32 v17, v50, v51 offset1:1
	s_waitcnt vmcnt(5)
	ds_write2_b32 v18, v52, v53 offset1:1
	ds_write2_b32 v20, v54, v55 offset1:1
	s_waitcnt vmcnt(4)
	ds_write2_b32 v32, v56, v57 offset1:1
	ds_write2_b32 v33, v58, v59 offset1:1
	s_waitcnt vmcnt(3)
	ds_write2_b32 v34, v60, v61 offset1:1
	ds_write2_b32 v35, v62, v63 offset1:1
	s_waitcnt vmcnt(2)
	ds_write2_b32 v36, v68, v69 offset1:1
	ds_write2_b32 v37, v70, v71 offset1:1
	s_waitcnt vmcnt(1)
	ds_write2_b32 v40, v72, v73 offset1:1
	ds_write2_b32 v41, v74, v75 offset1:1
	s_waitcnt vmcnt(0)
	ds_write2_b32 v42, v76, v77 offset1:1
	ds_write2_b32 v43, v78, v79 offset1:1
	s_waitcnt lgkmcnt(0)
	ds_read2_b32 v[212:213], v27 offset1:33
	ds_read2_b32 v[214:215], v27 offset0:66 offset1:99
	ds_read2_b32 v[216:217], v27 offset0:132 offset1:165
	ds_read2_b32 v[218:219], v27 offset0:198 offset1:231
	ds_read2_b32 v[220:221], v27 offset0:8 offset1:41
	ds_read2_b32 v[222:223], v27 offset0:74 offset1:107
	ds_read2_b32 v[224:225], v27 offset0:140 offset1:173
	ds_read2_b32 v[226:227], v27 offset0:206 offset1:239
	ds_read2_b32 v[228:229], v27 offset0:16 offset1:49
	ds_read2_b32 v[230:231], v27 offset0:82 offset1:115
	ds_read2_b32 v[232:233], v27 offset0:148 offset1:181
	ds_read2_b32 v[234:235], v27 offset0:214 offset1:247
	ds_read2_b32 v[236:237], v27 offset0:24 offset1:57
	ds_read2_b32 v[238:239], v27 offset0:90 offset1:123
	ds_read2_b32 v[240:241], v27 offset0:156 offset1:189
	ds_read2_b32 v[242:243], v27 offset0:222 offset1:255
	s_waitcnt lgkmcnt(0)
	v_cvt_pk_bf16_f32 v44, v212, v213
	s_waitcnt lgkmcnt(0)
	v_cvt_pk_bf16_f32 v45, v214, v215
	s_waitcnt lgkmcnt(0)
	v_cvt_pk_bf16_f32 v46, v216, v217
	v_or_b32_e32 v47, s6, v9
	v_mov_b32_e32 v51, v1
	v_mul_u32_u24_e32 v50, 0x1600, v47
	v_lshl_add_u64 v[52:53], v[12:13], 0, s[10:11]
	s_waitcnt lgkmcnt(0)
	v_cvt_pk_bf16_f32 v47, v218, v219
	v_lshl_add_u64 v[50:51], v[52:53], 0, v[50:51]
	global_store_dwordx4 v[50:51], v[44:47], off
	v_or_b32_e32 v50, s6, v19
	v_mov_b32_e32 v51, v1
	s_waitcnt lgkmcnt(0)
	v_cvt_pk_bf16_f32 v44, v220, v221
	s_waitcnt lgkmcnt(0)
	v_cvt_pk_bf16_f32 v45, v222, v223
	v_mul_u32_u24_e32 v50, 0x1600, v50
	s_waitcnt lgkmcnt(0)
	v_cvt_pk_bf16_f32 v46, v224, v225
	s_waitcnt lgkmcnt(0)
	v_cvt_pk_bf16_f32 v47, v226, v227
	v_lshl_add_u64 v[50:51], v[52:53], 0, v[50:51]
	global_store_dwordx4 v[50:51], v[44:47], off
	v_or_b32_e32 v50, s6, v21
	v_mov_b32_e32 v51, v1
	s_waitcnt lgkmcnt(0)
	v_cvt_pk_bf16_f32 v44, v228, v229
	s_waitcnt lgkmcnt(0)
	v_cvt_pk_bf16_f32 v45, v230, v231
	v_mul_u32_u24_e32 v50, 0x1600, v50
	s_waitcnt lgkmcnt(0)
	v_cvt_pk_bf16_f32 v46, v232, v233
	s_waitcnt lgkmcnt(0)
	v_cvt_pk_bf16_f32 v47, v234, v235
	v_lshl_add_u64 v[50:51], v[52:53], 0, v[50:51]
	global_store_dwordx4 v[50:51], v[44:47], off
	v_mov_b32_e32 v51, v1
	s_waitcnt lgkmcnt(0)
	v_cvt_pk_bf16_f32 v44, v236, v237
	s_waitcnt lgkmcnt(0)
	v_cvt_pk_bf16_f32 v45, v238, v239
	s_waitcnt lgkmcnt(0)
	v_cvt_pk_bf16_f32 v46, v240, v241
	v_or_b32_e32 v47, s6, v22
	v_mul_u32_u24_e32 v50, 0x1600, v47
	s_waitcnt lgkmcnt(0)
	v_cvt_pk_bf16_f32 v47, v242, v243
	v_lshl_add_u64 v[48:49], v[52:53], 0, v[50:51]
	global_store_dwordx4 v[48:49], v[44:47], off
	s_waitcnt lgkmcnt(0)
.LBB0_934:
	s_and_b32 s6, s2, 0xffffffe0
	s_cmpk_lg_i32 s6, 0x1c80
	s_cbranch_scc1 .LBB0_868
	s_load_dwordx2 s[34:35], s[44:45], 0x78
	s_lshl_b32 s6, s2, 5
	s_and_b32 s6, s6, 0xe0
	s_and_b32 s7, s24, 0xc0
	s_lshl_b32 s10, s6, 2
	s_waitcnt lgkmcnt(0)
	s_add_u32 s34, s34, s10
	s_addc_u32 s35, s35, 0
	v_or_b32_e32 v44, s7, v9
	v_or_b32_e32 v46, s7, v19
	v_or_b32_e32 v52, s7, v21
	v_or_b32_e32 v54, s7, v22
	v_or_b32_e32 v60, s7, v23
	v_or_b32_e32 v62, s7, v24
	v_lshl_add_u64 v[76:77], s[34:35], 0, v[0:1]
	v_lshlrev_b32_e32 v44, 10, v44
	v_mov_b32_e32 v45, v1
	v_lshlrev_b32_e32 v46, 10, v46
	v_mov_b32_e32 v47, v1
	v_lshlrev_b32_e32 v52, 10, v52
	v_mov_b32_e32 v53, v1
	v_lshlrev_b32_e32 v54, 10, v54
	v_mov_b32_e32 v55, v1
	v_lshlrev_b32_e32 v60, 10, v60
	v_mov_b32_e32 v61, v1
	v_lshlrev_b32_e32 v62, 10, v62
	v_mov_b32_e32 v63, v1
	v_lshl_add_u64 v[44:45], v[76:77], 0, v[44:45]
	v_lshl_add_u64 v[48:49], v[76:77], 0, v[46:47]
	v_lshl_add_u64 v[52:53], v[76:77], 0, v[52:53]
	v_lshl_add_u64 v[56:57], v[76:77], 0, v[54:55]
	v_lshl_add_u64 v[60:61], v[76:77], 0, v[60:61]
	v_lshl_add_u64 v[68:69], v[76:77], 0, v[62:63]
	global_load_dwordx4 v[44:47], v[44:45], off
	s_nop 0
	global_load_dwordx4 v[48:51], v[48:49], off
	s_nop 0
	global_load_dwordx4 v[52:55], v[52:53], off
	s_nop 0
	global_load_dwordx4 v[56:59], v[56:57], off
	s_nop 0
	global_load_dwordx4 v[60:63], v[60:61], off
	s_nop 0
	global_load_dwordx4 v[68:71], v[68:69], off
	v_or_b32_e32 v65, s7, v25
	v_lshlrev_b32_e32 v72, 10, v65
	v_mov_b32_e32 v73, v1
	v_lshl_add_u64 v[72:73], v[76:77], 0, v[72:73]
	v_or_b32_e32 v65, s7, v26
	global_load_dwordx4 v[72:75], v[72:73], off
	v_lshlrev_b32_e32 v78, 10, v65
	v_mov_b32_e32 v79, v1
	v_lshl_add_u64 v[76:77], v[76:77], 0, v[78:79]
	global_load_dwordx4 v[76:79], v[76:77], off
	s_lshl_b32 s10, s7, 1
	s_waitcnt vmcnt(7)
	ds_write2_b32 v29, v44, v45 offset1:1
	ds_write2_b32 v29, v46, v47 offset0:2 offset1:3
	s_waitcnt vmcnt(6)
	ds_write2_b32 v16, v48, v49 offset1:1
	ds_write2_b32 v17, v50, v51 offset1:1
	s_waitcnt vmcnt(5)
	ds_write2_b32 v18, v52, v53 offset1:1
	ds_write2_b32 v20, v54, v55 offset1:1
	s_waitcnt vmcnt(4)
	ds_write2_b32 v32, v56, v57 offset1:1
	ds_write2_b32 v33, v58, v59 offset1:1
	s_waitcnt vmcnt(3)
	ds_write2_b32 v34, v60, v61 offset1:1
	ds_write2_b32 v35, v62, v63 offset1:1
	s_waitcnt vmcnt(2)
	ds_write2_b32 v36, v68, v69 offset1:1
	ds_write2_b32 v37, v70, v71 offset1:1
	s_waitcnt vmcnt(1)
	ds_write2_b32 v40, v72, v73 offset1:1
	ds_write2_b32 v41, v74, v75 offset1:1
	s_waitcnt vmcnt(0)
	ds_write2_b32 v42, v76, v77 offset1:1
	ds_write2_b32 v43, v78, v79 offset1:1
	s_waitcnt lgkmcnt(0)
	ds_read2_b32 v[212:213], v27 offset1:33
	ds_read2_b32 v[214:215], v27 offset0:66 offset1:99
	ds_read2_b32 v[216:217], v27 offset0:132 offset1:165
	ds_read2_b32 v[218:219], v27 offset0:198 offset1:231
	ds_read2_b32 v[220:221], v27 offset0:8 offset1:41
	ds_read2_b32 v[222:223], v27 offset0:74 offset1:107
	ds_read2_b32 v[224:225], v27 offset0:140 offset1:173
	ds_read2_b32 v[226:227], v27 offset0:206 offset1:239
	ds_read2_b32 v[228:229], v27 offset0:16 offset1:49
	ds_read2_b32 v[230:231], v27 offset0:82 offset1:115
	ds_read2_b32 v[232:233], v27 offset0:148 offset1:181
	ds_read2_b32 v[234:235], v27 offset0:214 offset1:247
	ds_read2_b32 v[236:237], v27 offset0:24 offset1:57
	ds_read2_b32 v[238:239], v27 offset0:90 offset1:123
	ds_read2_b32 v[240:241], v27 offset0:156 offset1:189
	ds_read2_b32 v[242:243], v27 offset0:222 offset1:255
	s_waitcnt lgkmcnt(0)
	v_cvt_pk_bf16_f32 v32, v212, v213
	s_waitcnt lgkmcnt(0)
	v_cvt_pk_bf16_f32 v33, v214, v215
	v_or_b32_e32 v18, s6, v9
	s_waitcnt lgkmcnt(0)
	v_cvt_pk_bf16_f32 v34, v216, v217
	v_mov_b32_e32 v37, v1
	v_lshlrev_b32_e32 v36, 9, v18
	v_lshl_add_u64 v[40:41], v[14:15], 0, s[10:11]
	s_waitcnt lgkmcnt(0)
	v_cvt_pk_bf16_f32 v35, v218, v219
	v_lshl_add_u64 v[36:37], v[40:41], 0, v[36:37]
	global_store_dwordx4 v[36:37], v[32:35], off
	v_or_b32_e32 v18, s6, v19
	v_mov_b32_e32 v37, v1
	s_waitcnt lgkmcnt(0)
	v_cvt_pk_bf16_f32 v32, v220, v221
	s_waitcnt lgkmcnt(0)
	v_cvt_pk_bf16_f32 v33, v222, v223
	s_waitcnt lgkmcnt(0)
	v_cvt_pk_bf16_f32 v34, v224, v225
	v_lshlrev_b32_e32 v36, 9, v18
	s_waitcnt lgkmcnt(0)
	v_cvt_pk_bf16_f32 v35, v226, v227
	v_lshl_add_u64 v[36:37], v[40:41], 0, v[36:37]
	global_store_dwordx4 v[36:37], v[32:35], off
	v_or_b32_e32 v18, s6, v21
	v_mov_b32_e32 v37, v1
	s_waitcnt lgkmcnt(0)
	v_cvt_pk_bf16_f32 v32, v228, v229
	s_waitcnt lgkmcnt(0)
	v_cvt_pk_bf16_f32 v33, v230, v231
	s_waitcnt lgkmcnt(0)
	v_cvt_pk_bf16_f32 v34, v232, v233
	v_lshlrev_b32_e32 v36, 9, v18
	s_waitcnt lgkmcnt(0)
	v_cvt_pk_bf16_f32 v35, v234, v235
	v_lshl_add_u64 v[36:37], v[40:41], 0, v[36:37]
	global_store_dwordx4 v[36:37], v[32:35], off
	v_or_b32_e32 v18, s6, v22
	v_mov_b32_e32 v37, v1
	s_waitcnt lgkmcnt(0)
	v_cvt_pk_bf16_f32 v32, v236, v237
	s_waitcnt lgkmcnt(0)
	v_cvt_pk_bf16_f32 v33, v238, v239
	s_waitcnt lgkmcnt(0)
	v_cvt_pk_bf16_f32 v34, v240, v241
	v_lshlrev_b32_e32 v36, 9, v18
	s_waitcnt lgkmcnt(0)
	v_cvt_pk_bf16_f32 v35, v242, v243
	v_lshl_add_u64 v[16:17], v[40:41], 0, v[36:37]
	global_store_dwordx4 v[16:17], v[32:35], off
	s_waitcnt lgkmcnt(0)
	s_branch .LBB0_868

.LBB0_1716:
	v_mad_u64_u32 v[56:57], s[48:49], v58, s3, v[56:57]
	v_add_u32_e32 v58, 0x840, v60
	v_add_u32_e32 v60, 0x848, v60
	s_lshl_b32 s37, s37, 5
	s_lshl_b32 s8, s8, 1
	s_and_b32 s37, 0xffff, s37
	v_lshl_add_u64 v[80:81], v[4:5], 0, s[8:9]
	s_lshl_b32 s8, s37, 1
	s_and_b32 s37, s37, 0x60
	s_and_b32 s8, s8, 0x1f00
	s_or_b32 s8, s8, s37
	s_waitcnt vmcnt(0)
	v_pk_mul_f32 v[76:77], v[236:237], v[2:3] op_sel_hi:[1,0]
	v_pk_mul_f32 v[56:57], v[238:239], v[2:3] op_sel_hi:[1,0]
	ds_write2_b32 v58, v76, v77 offset1:1
	ds_write2_b32 v60, v56, v57 offset1:1
	s_waitcnt lgkmcnt(0)
	ds_read2_b32 v[212:213], v74 offset1:33
	ds_read2_b32 v[214:215], v74 offset0:66 offset1:99
	ds_read2_b32 v[216:217], v74 offset0:132 offset1:165
	ds_read2_b32 v[218:219], v74 offset0:198 offset1:231
	ds_read2_b32 v[220:221], v74 offset0:8 offset1:41
	ds_read2_b32 v[222:223], v74 offset0:74 offset1:107
	ds_read2_b32 v[224:225], v74 offset0:140 offset1:173
	ds_read2_b32 v[226:227], v74 offset0:206 offset1:239
	ds_read2_b32 v[228:229], v74 offset0:16 offset1:49
	ds_read2_b32 v[230:231], v74 offset0:82 offset1:115
	ds_read2_b32 v[232:233], v74 offset0:148 offset1:181
	ds_read2_b32 v[234:235], v74 offset0:214 offset1:247
	ds_read2_b32 v[236:237], v74 offset0:24 offset1:57
	ds_read2_b32 v[238:239], v74 offset0:90 offset1:123
	ds_read2_b32 v[240:241], v74 offset0:156 offset1:189
	ds_read2_b32 v[242:243], v74 offset0:222 offset1:255
	s_waitcnt lgkmcnt(0)
	v_cvt_pk_bf16_f32 v76, v212, v213
	s_waitcnt lgkmcnt(0)
	v_cvt_pk_bf16_f32 v77, v214, v215
	v_or_b32_e32 v2, s8, v1
	s_waitcnt lgkmcnt(0)
	v_cvt_pk_bf16_f32 v78, v216, v217
	v_lshlrev_b32_e32 v2, 11, v2
	s_waitcnt lgkmcnt(0)
	v_cvt_pk_bf16_f32 v79, v218, v219
	v_lshl_add_u64 v[82:83], v[80:81], 0, v[2:3]
	global_store_dwordx4 v[82:83], v[76:79], off
	v_or_b32_e32 v2, s8, v62
	v_lshlrev_b32_e32 v2, 11, v2
	s_waitcnt lgkmcnt(0)
	v_cvt_pk_bf16_f32 v76, v220, v221
	s_waitcnt lgkmcnt(0)
	v_cvt_pk_bf16_f32 v77, v222, v223
	s_waitcnt lgkmcnt(0)
	v_cvt_pk_bf16_f32 v78, v224, v225
	s_waitcnt lgkmcnt(0)
	v_cvt_pk_bf16_f32 v79, v226, v227
	v_lshl_add_u64 v[82:83], v[80:81], 0, v[2:3]
	global_store_dwordx4 v[82:83], v[76:79], off
	v_or_b32_e32 v2, s8, v64
	v_lshlrev_b32_e32 v2, 11, v2
	s_waitcnt lgkmcnt(0)
	v_cvt_pk_bf16_f32 v76, v228, v229
	s_waitcnt lgkmcnt(0)
	v_cvt_pk_bf16_f32 v77, v230, v231
	s_waitcnt lgkmcnt(0)
	v_cvt_pk_bf16_f32 v78, v232, v233
	s_waitcnt lgkmcnt(0)
	v_cvt_pk_bf16_f32 v79, v234, v235
	v_lshl_add_u64 v[82:83], v[80:81], 0, v[2:3]
	global_store_dwordx4 v[82:83], v[76:79], off
	v_or_b32_e32 v2, s8, v66
	v_lshlrev_b32_e32 v2, 11, v2
	s_waitcnt lgkmcnt(0)
	v_cvt_pk_bf16_f32 v76, v236, v237
	s_waitcnt lgkmcnt(0)
	v_cvt_pk_bf16_f32 v77, v238, v239
	s_waitcnt lgkmcnt(0)
	v_cvt_pk_bf16_f32 v78, v240, v241
	s_waitcnt lgkmcnt(0)
	v_cvt_pk_bf16_f32 v79, v242, v243
	v_lshl_add_u64 v[56:57], v[80:81], 0, v[2:3]
	global_store_dwordx4 v[56:57], v[76:79], off
	s_waitcnt lgkmcnt(0)
	s_add_i32 s37, s1, 0xfffffa80
	s_cmpk_gt_u32 s37, 0x57f
	s_cbranch_scc0 .LBB0_1739

.LBB0_1718:
	s_load_dwordx2 s[48:49], s[10:11], 0x20
	s_lshl_b32 s4, s4, 1
	s_and_b32 s5, s4, 0xfc0
	s_lshl_b32 s4, s1, 5
	s_and_b32 s4, s4, 0x3e0
	s_lshl_b32 s8, s4, 2
	s_waitcnt lgkmcnt(0)
	s_add_u32 s48, s48, s8
	s_addc_u32 s49, s49, 0
	v_lshlrev_b32_e32 v2, 2, v0
	v_lshl_add_u64 v[56:57], s[48:49], 0, v[2:3]
	v_or_b32_e32 v2, s5, v1
	v_lshl_add_u64 v[56:57], v[56:57], 0, s[26:27]
	v_lshlrev_b32_e32 v2, 12, v2
	v_lshl_add_u64 v[76:77], v[56:57], 0, v[2:3]
	v_or_b32_e32 v2, s5, v62
	v_lshlrev_b32_e32 v2, 12, v2
	v_lshl_add_u64 v[80:81], v[56:57], 0, v[2:3]
	v_or_b32_e32 v2, s5, v64
	v_lshlrev_b32_e32 v2, 12, v2
	v_lshl_add_u64 v[84:85], v[56:57], 0, v[2:3]
	v_or_b32_e32 v2, s5, v66
	v_lshlrev_b32_e32 v2, 12, v2
	v_lshl_add_u64 v[88:89], v[56:57], 0, v[2:3]
	v_or_b32_e32 v2, s5, v68
	v_lshlrev_b32_e32 v2, 12, v2
	v_lshl_add_u64 v[92:93], v[56:57], 0, v[2:3]
	v_or_b32_e32 v2, s5, v70
	v_lshlrev_b32_e32 v2, 12, v2
	v_lshl_add_u64 v[96:97], v[56:57], 0, v[2:3]
	global_load_dwordx4 v[76:79], v[76:77], off
	s_nop 0
	global_load_dwordx4 v[80:83], v[80:81], off
	s_nop 0
	global_load_dwordx4 v[84:87], v[84:85], off
	s_nop 0
	global_load_dwordx4 v[88:91], v[88:89], off
	s_nop 0
	global_load_dwordx4 v[92:95], v[92:93], off
	s_nop 0
	global_load_dwordx4 v[96:99], v[96:97], off
	v_or_b32_e32 v2, s5, v72
	v_lshlrev_b32_e32 v2, 12, v2
	v_lshl_add_u64 v[100:101], v[56:57], 0, v[2:3]
	v_or_b32_e32 v2, s5, v73
	global_load_dwordx4 v[100:103], v[100:101], off
	v_lshlrev_b32_e32 v2, 12, v2
	v_lshl_add_u64 v[56:57], v[56:57], 0, v[2:3]
	global_load_dwordx4 v[104:107], v[56:57], off
	v_add_u32_e32 v2, v59, v61
	v_add_u32_e32 v56, v59, v71
	v_add_u32_e32 v57, 0x420, v2
	v_add_u32_e32 v58, 0x428, v2
	v_add_u32_e32 v60, 0x840, v2
	v_add_u32_e32 v108, 0x848, v2
	v_add_u32_e32 v109, 0xc60, v2
	v_add_u32_e32 v110, 0xc68, v2
	v_add_u32_e32 v111, 0x1080, v2
	v_add_u32_e32 v112, 0x1088, v2
	v_add_u32_e32 v113, 0x14a0, v2
	v_add_u32_e32 v114, 0x420, v56
	v_add_u32_e32 v115, 0x428, v56
	v_add_u32_e32 v116, 0x840, v56
	v_add_u32_e32 v117, 0x848, v56
	s_lshl_b32 s8, s5, 1
	s_waitcnt vmcnt(7)
	ds_write2_b32 v2, v76, v77 offset1:1
	ds_write2_b32 v2, v78, v79 offset0:2 offset1:3
	s_waitcnt vmcnt(6)
	ds_write2_b32 v57, v80, v81 offset1:1
	ds_write2_b32 v58, v82, v83 offset1:1
	s_waitcnt vmcnt(5)
	ds_write2_b32 v60, v84, v85 offset1:1
	ds_write2_b32 v108, v86, v87 offset1:1
	s_waitcnt vmcnt(4)
	ds_write2_b32 v109, v88, v89 offset1:1
	ds_write2_b32 v110, v90, v91 offset1:1
	s_waitcnt vmcnt(3)
	ds_write2_b32 v111, v92, v93 offset1:1
	ds_write2_b32 v112, v94, v95 offset1:1
	s_waitcnt vmcnt(2)
	ds_write2_b32 v113, v96, v97 offset1:1
	ds_write2_b32 v56, v98, v99 offset0:2 offset1:3
	s_waitcnt vmcnt(1)
	ds_write2_b32 v114, v100, v101 offset1:1
	ds_write2_b32 v115, v102, v103 offset1:1
	s_waitcnt vmcnt(0)
	ds_write2_b32 v116, v104, v105 offset1:1
	ds_write2_b32 v117, v106, v107 offset1:1
	s_waitcnt lgkmcnt(0)
	ds_read2_b32 v[212:213], v74 offset1:33
	ds_read2_b32 v[214:215], v74 offset0:66 offset1:99
	ds_read2_b32 v[216:217], v74 offset0:132 offset1:165
	ds_read2_b32 v[218:219], v74 offset0:198 offset1:231
	ds_read2_b32 v[220:221], v74 offset0:8 offset1:41
	ds_read2_b32 v[222:223], v74 offset0:74 offset1:107
	ds_read2_b32 v[224:225], v74 offset0:140 offset1:173
	ds_read2_b32 v[226:227], v74 offset0:206 offset1:239
	ds_read2_b32 v[228:229], v74 offset0:16 offset1:49
	ds_read2_b32 v[230:231], v74 offset0:82 offset1:115
	ds_read2_b32 v[232:233], v74 offset0:148 offset1:181
	ds_read2_b32 v[234:235], v74 offset0:214 offset1:247
	ds_read2_b32 v[236:237], v74 offset0:24 offset1:57
	ds_read2_b32 v[238:239], v74 offset0:90 offset1:123
	ds_read2_b32 v[240:241], v74 offset0:156 offset1:189
	ds_read2_b32 v[242:243], v74 offset0:222 offset1:255
	s_waitcnt lgkmcnt(0)
	v_cvt_pk_bf16_f32 v76, v212, v213
	s_waitcnt lgkmcnt(0)
	v_cvt_pk_bf16_f32 v77, v214, v215
	v_or_b32_e32 v2, s4, v1
	s_waitcnt lgkmcnt(0)
	v_cvt_pk_bf16_f32 v78, v216, v217
	v_lshl_add_u64 v[80:81], v[6:7], 0, s[8:9]
	v_mul_u32_u24_e32 v2, 0x1600, v2
	s_waitcnt lgkmcnt(0)
	v_cvt_pk_bf16_f32 v79, v218, v219
	v_lshl_add_u64 v[82:83], v[80:81], 0, v[2:3]
	global_store_dwordx4 v[82:83], v[76:79], off
	v_or_b32_e32 v2, s4, v62
	v_mul_u32_u24_e32 v2, 0x1600, v2
	s_waitcnt lgkmcnt(0)
	v_cvt_pk_bf16_f32 v76, v220, v221
	s_waitcnt lgkmcnt(0)
	v_cvt_pk_bf16_f32 v77, v222, v223
	s_waitcnt lgkmcnt(0)
	v_cvt_pk_bf16_f32 v78, v224, v225
	s_waitcnt lgkmcnt(0)
	v_cvt_pk_bf16_f32 v79, v226, v227
	v_lshl_add_u64 v[82:83], v[80:81], 0, v[2:3]
	global_store_dwordx4 v[82:83], v[76:79], off
	v_or_b32_e32 v2, s4, v64
	v_mul_u32_u24_e32 v2, 0x1600, v2
	s_waitcnt lgkmcnt(0)
	v_cvt_pk_bf16_f32 v76, v228, v229
	s_waitcnt lgkmcnt(0)
	v_cvt_pk_bf16_f32 v77, v230, v231
	s_waitcnt lgkmcnt(0)
	v_cvt_pk_bf16_f32 v78, v232, v233
	s_waitcnt lgkmcnt(0)
	v_cvt_pk_bf16_f32 v79, v234, v235
	v_lshl_add_u64 v[82:83], v[80:81], 0, v[2:3]
	global_store_dwordx4 v[82:83], v[76:79], off
	v_or_b32_e32 v2, s4, v66
	v_mul_u32_u24_e32 v2, 0x1600, v2
	s_waitcnt lgkmcnt(0)
	v_cvt_pk_bf16_f32 v76, v236, v237
	s_waitcnt lgkmcnt(0)
	v_cvt_pk_bf16_f32 v77, v238, v239
	s_waitcnt lgkmcnt(0)
	v_cvt_pk_bf16_f32 v78, v240, v241
	s_waitcnt lgkmcnt(0)
	v_cvt_pk_bf16_f32 v79, v242, v243
	v_lshl_add_u64 v[56:57], v[80:81], 0, v[2:3]
	global_store_dwordx4 v[56:57], v[76:79], off
	s_waitcnt lgkmcnt(0)

.LBB0_1736:
	v_mad_u64_u32 v[56:57], s[48:49], v58, s36, v[56:57]
	v_add_u32_e32 v58, 0x840, v60
	v_add_u32_e32 v60, 0x848, v60
	s_and_b32 s37, 0xffff, s37
	s_lshl_b32 s8, s8, 1
	v_lshl_add_u64 v[80:81], v[8:9], 0, s[8:9]
	s_waitcnt vmcnt(0)
	v_pk_mul_f32 v[76:77], v[236:237], v[2:3] op_sel_hi:[1,0]
	v_pk_mul_f32 v[56:57], v[238:239], v[2:3] op_sel_hi:[1,0]
	ds_write2_b32 v58, v76, v77 offset1:1
	ds_write2_b32 v60, v56, v57 offset1:1
	s_waitcnt lgkmcnt(0)
	ds_read2_b32 v[212:213], v74 offset1:33
	ds_read2_b32 v[214:215], v74 offset0:66 offset1:99
	ds_read2_b32 v[216:217], v74 offset0:132 offset1:165
	ds_read2_b32 v[218:219], v74 offset0:198 offset1:231
	ds_read2_b32 v[220:221], v74 offset0:8 offset1:41
	ds_read2_b32 v[222:223], v74 offset0:74 offset1:107
	ds_read2_b32 v[224:225], v74 offset0:140 offset1:173
	ds_read2_b32 v[226:227], v74 offset0:206 offset1:239
	ds_read2_b32 v[228:229], v74 offset0:16 offset1:49
	ds_read2_b32 v[230:231], v74 offset0:82 offset1:115
	ds_read2_b32 v[232:233], v74 offset0:148 offset1:181
	ds_read2_b32 v[234:235], v74 offset0:214 offset1:247
	ds_read2_b32 v[236:237], v74 offset0:24 offset1:57
	ds_read2_b32 v[238:239], v74 offset0:90 offset1:123
	ds_read2_b32 v[240:241], v74 offset0:156 offset1:189
	ds_read2_b32 v[242:243], v74 offset0:222 offset1:255
	s_waitcnt lgkmcnt(0)
	v_cvt_pk_bf16_f32 v76, v212, v213
	s_waitcnt lgkmcnt(0)
	v_cvt_pk_bf16_f32 v77, v214, v215
	v_or_b32_e32 v2, s37, v1
	s_waitcnt lgkmcnt(0)
	v_cvt_pk_bf16_f32 v78, v216, v217
	v_lshlrev_b32_e32 v2, 11, v2
	s_waitcnt lgkmcnt(0)
	v_cvt_pk_bf16_f32 v79, v218, v219
	v_lshl_add_u64 v[82:83], v[80:81], 0, v[2:3]
	global_store_dwordx4 v[82:83], v[76:79], off
	v_or_b32_e32 v2, s37, v62
	v_lshlrev_b32_e32 v2, 11, v2
	s_waitcnt lgkmcnt(0)
	v_cvt_pk_bf16_f32 v76, v220, v221
	s_waitcnt lgkmcnt(0)
	v_cvt_pk_bf16_f32 v77, v222, v223
	s_waitcnt lgkmcnt(0)
	v_cvt_pk_bf16_f32 v78, v224, v225
	s_waitcnt lgkmcnt(0)
	v_cvt_pk_bf16_f32 v79, v226, v227
	v_lshl_add_u64 v[82:83], v[80:81], 0, v[2:3]
	global_store_dwordx4 v[82:83], v[76:79], off
	v_or_b32_e32 v2, s37, v64
	v_lshlrev_b32_e32 v2, 11, v2
	s_waitcnt lgkmcnt(0)
	v_cvt_pk_bf16_f32 v76, v228, v229
	s_waitcnt lgkmcnt(0)
	v_cvt_pk_bf16_f32 v77, v230, v231
	s_waitcnt lgkmcnt(0)
	v_cvt_pk_bf16_f32 v78, v232, v233
	s_waitcnt lgkmcnt(0)
	v_cvt_pk_bf16_f32 v79, v234, v235
	v_lshl_add_u64 v[82:83], v[80:81], 0, v[2:3]
	global_store_dwordx4 v[82:83], v[76:79], off
	v_or_b32_e32 v2, s37, v66
	v_lshlrev_b32_e32 v2, 11, v2
	s_waitcnt lgkmcnt(0)
	v_cvt_pk_bf16_f32 v76, v236, v237
	s_waitcnt lgkmcnt(0)
	v_cvt_pk_bf16_f32 v77, v238, v239
	s_waitcnt lgkmcnt(0)
	v_cvt_pk_bf16_f32 v78, v240, v241
	s_waitcnt lgkmcnt(0)
	v_cvt_pk_bf16_f32 v79, v242, v243
	v_lshl_add_u64 v[56:57], v[80:81], 0, v[2:3]
	global_store_dwordx4 v[56:57], v[76:79], off
	s_waitcnt lgkmcnt(0)
	s_and_b32 s37, s1, 0xffffffe0
	s_cmpk_lt_i32 s37, 0x14a0
	s_mov_b64 s[48:49], -1
	s_cbranch_scc0 .LBB0_1757

.LBB0_1755:
	v_mad_u64_u32 v[56:57], s[4:5], v58, s3, v[56:57]
	s_lshl_b32 s4, s37, 5
	v_add_u32_e32 v58, 0x840, v60
	s_and_b32 s4, 0xffff, s4
	v_add_u32_e32 v60, 0x848, v60
	s_lshl_b32 s5, s4, 1
	s_and_b32 s4, s4, 0x60
	s_and_b32 s5, s5, 0x1f00
	s_or_b32 s4, s5, s4
	s_lshl_b32 s8, s8, 1
	v_lshl_add_u64 v[80:81], v[4:5], 0, s[8:9]
	s_waitcnt vmcnt(0)
	v_pk_mul_f32 v[76:77], v[236:237], v[2:3] op_sel_hi:[1,0]
	v_pk_mul_f32 v[56:57], v[238:239], v[2:3] op_sel_hi:[1,0]
	ds_write2_b32 v58, v76, v77 offset1:1
	ds_write2_b32 v60, v56, v57 offset1:1
	s_waitcnt lgkmcnt(0)
	ds_read2_b32 v[212:213], v74 offset1:33
	ds_read2_b32 v[214:215], v74 offset0:66 offset1:99
	ds_read2_b32 v[216:217], v74 offset0:132 offset1:165
	ds_read2_b32 v[218:219], v74 offset0:198 offset1:231
	ds_read2_b32 v[220:221], v74 offset0:8 offset1:41
	ds_read2_b32 v[222:223], v74 offset0:74 offset1:107
	ds_read2_b32 v[224:225], v74 offset0:140 offset1:173
	ds_read2_b32 v[226:227], v74 offset0:206 offset1:239
	ds_read2_b32 v[228:229], v74 offset0:16 offset1:49
	ds_read2_b32 v[230:231], v74 offset0:82 offset1:115
	ds_read2_b32 v[232:233], v74 offset0:148 offset1:181
	ds_read2_b32 v[234:235], v74 offset0:214 offset1:247
	ds_read2_b32 v[236:237], v74 offset0:24 offset1:57
	ds_read2_b32 v[238:239], v74 offset0:90 offset1:123
	ds_read2_b32 v[240:241], v74 offset0:156 offset1:189
	ds_read2_b32 v[242:243], v74 offset0:222 offset1:255
	v_or_b32_e32 v2, s4, v1
	s_waitcnt lgkmcnt(0)
	v_cvt_pk_bf16_f32 v76, v212, v213
	v_lshlrev_b32_e32 v2, 11, v2
	s_waitcnt lgkmcnt(0)
	v_cvt_pk_bf16_f32 v77, v214, v215
	v_lshl_add_u64 v[82:83], v[80:81], 0, v[2:3]
	s_waitcnt lgkmcnt(0)
	v_cvt_pk_bf16_f32 v78, v216, v217
	v_add_co_u32_e32 v82, vcc, s33, v82
	s_waitcnt lgkmcnt(0)
	v_cvt_pk_bf16_f32 v79, v218, v219
	v_addc_co_u32_e32 v83, vcc, 0, v83, vcc
	v_or_b32_e32 v2, s4, v62
	global_store_dwordx4 v[82:83], v[76:79], off
	v_lshlrev_b32_e32 v2, 11, v2
	v_lshl_add_u64 v[82:83], v[80:81], 0, v[2:3]
	s_waitcnt lgkmcnt(0)
	v_cvt_pk_bf16_f32 v76, v220, v221
	s_waitcnt lgkmcnt(0)
	v_cvt_pk_bf16_f32 v77, v222, v223
	s_waitcnt lgkmcnt(0)
	v_cvt_pk_bf16_f32 v78, v224, v225
	v_add_co_u32_e32 v82, vcc, s33, v82
	s_waitcnt lgkmcnt(0)
	v_cvt_pk_bf16_f32 v79, v226, v227
	v_addc_co_u32_e32 v83, vcc, 0, v83, vcc
	v_or_b32_e32 v2, s4, v64
	global_store_dwordx4 v[82:83], v[76:79], off
	v_lshlrev_b32_e32 v2, 11, v2
	v_lshl_add_u64 v[82:83], v[80:81], 0, v[2:3]
	s_waitcnt lgkmcnt(0)
	v_cvt_pk_bf16_f32 v76, v228, v229
	s_waitcnt lgkmcnt(0)
	v_cvt_pk_bf16_f32 v77, v230, v231
	v_or_b32_e32 v2, s4, v66
	s_waitcnt lgkmcnt(0)
	v_cvt_pk_bf16_f32 v78, v232, v233
	v_add_co_u32_e32 v82, vcc, s33, v82
	v_lshlrev_b32_e32 v2, 11, v2
	s_waitcnt lgkmcnt(0)
	v_cvt_pk_bf16_f32 v79, v234, v235
	v_addc_co_u32_e32 v83, vcc, 0, v83, vcc
	v_lshl_add_u64 v[80:81], v[80:81], 0, v[2:3]
	global_store_dwordx4 v[82:83], v[76:79], off
	v_add_co_u32_e32 v80, vcc, 0x40000, v80
	s_waitcnt lgkmcnt(0)
	v_cvt_pk_bf16_f32 v76, v236, v237
	s_waitcnt lgkmcnt(0)
	v_cvt_pk_bf16_f32 v77, v238, v239
	v_addc_co_u32_e32 v81, vcc, 0, v81, vcc
	s_waitcnt lgkmcnt(0)
	v_cvt_pk_bf16_f32 v78, v240, v241
	s_waitcnt lgkmcnt(0)
	v_cvt_pk_bf16_f32 v79, v242, v243
	global_store_dwordx4 v[80:81], v[76:79], off
	s_waitcnt lgkmcnt(0)
	s_add_i32 s4, s1, 0xfffff500
	s_cmpk_gt_u32 s4, 0x57f
	s_cbranch_scc0 .LBB0_1718
	s_branch .LBB0_1719

.LBB0_1774:
	s_nop 0
	global_load_dword v60, v60, s[22:23]
	v_lshlrev_b32_e32 v2, 8, v2
	v_lshl_add_u64 v[56:57], v[56:57], 0, v[2:3]
	global_load_dwordx4 v[78:81], v[56:57], off
	v_add_u32_e32 v82, 0x840, v76
	v_add_u32_e32 v83, 0x848, v76
	s_and_b32 s49, 0xffff, s49
	s_lshl_b32 s8, s48, 1
	s_waitcnt vmcnt(1)
	v_sub_f32_e32 v2, 1.0, v60
	v_mul_f32_e32 v2, v58, v2
	s_waitcnt vmcnt(0)
	v_pk_mul_f32 v[76:77], v[78:79], v[2:3] op_sel_hi:[1,0]
	v_pk_mul_f32 v[56:57], v[80:81], v[2:3] op_sel_hi:[1,0]
	ds_write2_b32 v82, v76, v77 offset1:1
	ds_write2_b32 v83, v56, v57 offset1:1
	s_waitcnt lgkmcnt(0)
	ds_read2_b32 v[212:213], v74 offset1:33
	ds_read2_b32 v[214:215], v74 offset0:66 offset1:99
	ds_read2_b32 v[216:217], v74 offset0:132 offset1:165
	ds_read2_b32 v[218:219], v74 offset0:198 offset1:231
	ds_read2_b32 v[220:221], v74 offset0:8 offset1:41
	ds_read2_b32 v[222:223], v74 offset0:74 offset1:107
	ds_read2_b32 v[224:225], v74 offset0:140 offset1:173
	ds_read2_b32 v[226:227], v74 offset0:206 offset1:239
	ds_read2_b32 v[228:229], v74 offset0:16 offset1:49
	ds_read2_b32 v[230:231], v74 offset0:82 offset1:115
	ds_read2_b32 v[232:233], v74 offset0:148 offset1:181
	ds_read2_b32 v[234:235], v74 offset0:214 offset1:247
	ds_read2_b32 v[236:237], v74 offset0:24 offset1:57
	ds_read2_b32 v[238:239], v74 offset0:90 offset1:123
	ds_read2_b32 v[240:241], v74 offset0:156 offset1:189
	ds_read2_b32 v[242:243], v74 offset0:222 offset1:255
	s_waitcnt lgkmcnt(0)
	v_cvt_pk_bf16_f32 v76, v212, v213
	v_lshl_add_u64 v[80:81], v[8:9], 0, s[8:9]
	s_or_b32 s8, s49, 0x840
	s_waitcnt lgkmcnt(0)
	v_cvt_pk_bf16_f32 v77, v214, v215
	v_or_b32_e32 v2, s8, v1
	s_waitcnt lgkmcnt(0)
	v_cvt_pk_bf16_f32 v78, v216, v217
	v_lshlrev_b32_e32 v2, 11, v2
	s_waitcnt lgkmcnt(0)
	v_cvt_pk_bf16_f32 v79, v218, v219
	v_lshl_add_u64 v[82:83], v[80:81], 0, v[2:3]
	global_store_dwordx4 v[82:83], v[76:79], off
	v_or_b32_e32 v2, s8, v62
	v_lshlrev_b32_e32 v2, 11, v2
	s_waitcnt lgkmcnt(0)
	v_cvt_pk_bf16_f32 v76, v220, v221
	s_waitcnt lgkmcnt(0)
	v_cvt_pk_bf16_f32 v77, v222, v223
	s_waitcnt lgkmcnt(0)
	v_cvt_pk_bf16_f32 v78, v224, v225
	s_waitcnt lgkmcnt(0)
	v_cvt_pk_bf16_f32 v79, v226, v227
	v_lshl_add_u64 v[82:83], v[80:81], 0, v[2:3]
	global_store_dwordx4 v[82:83], v[76:79], off
	v_or_b32_e32 v2, s8, v64
	v_lshlrev_b32_e32 v2, 11, v2
	s_waitcnt lgkmcnt(0)
	v_cvt_pk_bf16_f32 v76, v228, v229
	s_waitcnt lgkmcnt(0)
	v_cvt_pk_bf16_f32 v77, v230, v231
	s_waitcnt lgkmcnt(0)
	v_cvt_pk_bf16_f32 v78, v232, v233
	s_waitcnt lgkmcnt(0)
	v_cvt_pk_bf16_f32 v79, v234, v235
	v_lshl_add_u64 v[82:83], v[80:81], 0, v[2:3]
	global_store_dwordx4 v[82:83], v[76:79], off
	v_or_b32_e32 v2, s8, v66
	v_lshlrev_b32_e32 v2, 11, v2
	s_waitcnt lgkmcnt(0)
	v_cvt_pk_bf16_f32 v76, v236, v237
	s_waitcnt lgkmcnt(0)
	v_cvt_pk_bf16_f32 v77, v238, v239
	s_waitcnt lgkmcnt(0)
	v_cvt_pk_bf16_f32 v78, v240, v241
	s_waitcnt lgkmcnt(0)
	v_cvt_pk_bf16_f32 v79, v242, v243
	v_lshl_add_u64 v[56:57], v[80:81], 0, v[2:3]
	global_store_dwordx4 v[56:57], v[76:79], off
	s_waitcnt lgkmcnt(0)

.LBB0_1793:
	s_nop 0
	global_load_dword v60, v60, s[16:17]
	v_lshlrev_b32_e32 v2, 8, v2
	v_lshl_add_u64 v[56:57], v[56:57], 0, v[2:3]
	global_load_dwordx4 v[78:81], v[56:57], off
	v_add_u32_e32 v82, 0x840, v76
	v_add_u32_e32 v83, 0x848, v76
	s_and_b32 s48, 0xffff, s48
	s_bitset1_b32 s48, 11
	s_lshl_b32 s8, s8, 1
	s_waitcnt vmcnt(1)
	v_sub_f32_e32 v2, 1.0, v60
	v_mul_f32_e32 v2, v58, v2
	s_waitcnt vmcnt(0)
	v_pk_mul_f32 v[76:77], v[78:79], v[2:3] op_sel_hi:[1,0]
	v_pk_mul_f32 v[56:57], v[80:81], v[2:3] op_sel_hi:[1,0]
	ds_write2_b32 v82, v76, v77 offset1:1
	ds_write2_b32 v83, v56, v57 offset1:1
	s_waitcnt lgkmcnt(0)
	ds_read2_b32 v[212:213], v74 offset1:33
	ds_read2_b32 v[214:215], v74 offset0:66 offset1:99
	ds_read2_b32 v[216:217], v74 offset0:132 offset1:165
	ds_read2_b32 v[218:219], v74 offset0:198 offset1:231
	ds_read2_b32 v[220:221], v74 offset0:8 offset1:41
	ds_read2_b32 v[222:223], v74 offset0:74 offset1:107
	ds_read2_b32 v[224:225], v74 offset0:140 offset1:173
	ds_read2_b32 v[226:227], v74 offset0:206 offset1:239
	ds_read2_b32 v[228:229], v74 offset0:16 offset1:49
	ds_read2_b32 v[230:231], v74 offset0:82 offset1:115
	ds_read2_b32 v[232:233], v74 offset0:148 offset1:181
	ds_read2_b32 v[234:235], v74 offset0:214 offset1:247
	ds_read2_b32 v[236:237], v74 offset0:24 offset1:57
	ds_read2_b32 v[238:239], v74 offset0:90 offset1:123
	ds_read2_b32 v[240:241], v74 offset0:156 offset1:189
	ds_read2_b32 v[242:243], v74 offset0:222 offset1:255
	s_waitcnt lgkmcnt(0)
	v_cvt_pk_bf16_f32 v76, v212, v213
	s_waitcnt lgkmcnt(0)
	v_cvt_pk_bf16_f32 v77, v214, v215
	v_or_b32_e32 v2, s48, v1
	s_waitcnt lgkmcnt(0)
	v_cvt_pk_bf16_f32 v78, v216, v217
	v_lshl_add_u64 v[80:81], v[8:9], 0, s[8:9]
	v_lshlrev_b32_e32 v2, 11, v2
	s_waitcnt lgkmcnt(0)
	v_cvt_pk_bf16_f32 v79, v218, v219
	v_lshl_add_u64 v[82:83], v[80:81], 0, v[2:3]
	global_store_dwordx4 v[82:83], v[76:79], off
	v_or_b32_e32 v2, s48, v62
	v_lshlrev_b32_e32 v2, 11, v2
	s_waitcnt lgkmcnt(0)
	v_cvt_pk_bf16_f32 v76, v220, v221
	s_waitcnt lgkmcnt(0)
	v_cvt_pk_bf16_f32 v77, v222, v223
	s_waitcnt lgkmcnt(0)
	v_cvt_pk_bf16_f32 v78, v224, v225
	s_waitcnt lgkmcnt(0)
	v_cvt_pk_bf16_f32 v79, v226, v227
	v_lshl_add_u64 v[82:83], v[80:81], 0, v[2:3]
	global_store_dwordx4 v[82:83], v[76:79], off
	v_or_b32_e32 v2, s48, v64
	v_lshlrev_b32_e32 v2, 11, v2
	s_waitcnt lgkmcnt(0)
	v_cvt_pk_bf16_f32 v76, v228, v229
	s_waitcnt lgkmcnt(0)
	v_cvt_pk_bf16_f32 v77, v230, v231
	s_waitcnt lgkmcnt(0)
	v_cvt_pk_bf16_f32 v78, v232, v233
	s_waitcnt lgkmcnt(0)
	v_cvt_pk_bf16_f32 v79, v234, v235
	v_lshl_add_u64 v[82:83], v[80:81], 0, v[2:3]
	global_store_dwordx4 v[82:83], v[76:79], off
	v_or_b32_e32 v2, s48, v66
	v_lshlrev_b32_e32 v2, 11, v2
	s_waitcnt lgkmcnt(0)
	v_cvt_pk_bf16_f32 v76, v236, v237
	s_waitcnt lgkmcnt(0)
	v_cvt_pk_bf16_f32 v77, v238, v239
	s_waitcnt lgkmcnt(0)
	v_cvt_pk_bf16_f32 v78, v240, v241
	s_waitcnt lgkmcnt(0)
	v_cvt_pk_bf16_f32 v79, v242, v243
	v_lshl_add_u64 v[56:57], v[80:81], 0, v[2:3]
	global_store_dwordx4 v[56:57], v[76:79], off
	s_waitcnt lgkmcnt(0)

.LBB0_1811:
	s_nop 0
	global_load_dword v60, v60, s[24:25]
	v_lshlrev_b32_e32 v2, 9, v2
	v_lshl_add_u64 v[56:57], v[56:57], 0, v[2:3]
	global_load_dwordx4 v[78:81], v[56:57], off
	v_add_u32_e32 v82, 0x840, v76
	v_add_u32_e32 v83, 0x848, v76
	s_lshl_b32 s49, s1, 5
	s_lshl_b32 s8, s48, 1
	s_or_b32 s48, s49, 0x880
	s_waitcnt vmcnt(1)
	v_sub_f32_e32 v2, 1.0, v60
	v_mul_f32_e32 v2, v58, v2
	s_waitcnt vmcnt(0)
	v_pk_mul_f32 v[76:77], v[78:79], v[2:3] op_sel_hi:[1,0]
	v_pk_mul_f32 v[56:57], v[80:81], v[2:3] op_sel_hi:[1,0]
	ds_write2_b32 v82, v76, v77 offset1:1
	ds_write2_b32 v83, v56, v57 offset1:1
	s_waitcnt lgkmcnt(0)
	ds_read2_b32 v[212:213], v74 offset1:33
	ds_read2_b32 v[214:215], v74 offset0:66 offset1:99
	ds_read2_b32 v[216:217], v74 offset0:132 offset1:165
	ds_read2_b32 v[218:219], v74 offset0:198 offset1:231
	ds_read2_b32 v[220:221], v74 offset0:8 offset1:41
	ds_read2_b32 v[222:223], v74 offset0:74 offset1:107
	ds_read2_b32 v[224:225], v74 offset0:140 offset1:173
	ds_read2_b32 v[226:227], v74 offset0:206 offset1:239
	ds_read2_b32 v[228:229], v74 offset0:16 offset1:49
	ds_read2_b32 v[230:231], v74 offset0:82 offset1:115
	ds_read2_b32 v[232:233], v74 offset0:148 offset1:181
	ds_read2_b32 v[234:235], v74 offset0:214 offset1:247
	ds_read2_b32 v[236:237], v74 offset0:24 offset1:57
	ds_read2_b32 v[238:239], v74 offset0:90 offset1:123
	ds_read2_b32 v[240:241], v74 offset0:156 offset1:189
	ds_read2_b32 v[242:243], v74 offset0:222 offset1:255
	s_waitcnt lgkmcnt(0)
	v_cvt_pk_bf16_f32 v76, v212, v213
	v_lshl_add_u64 v[80:81], v[8:9], 0, s[8:9]
	s_and_b32 s8, s48, 0x8ff
	s_waitcnt lgkmcnt(0)
	v_cvt_pk_bf16_f32 v77, v214, v215
	v_or_b32_e32 v2, s8, v1
	s_waitcnt lgkmcnt(0)
	v_cvt_pk_bf16_f32 v78, v216, v217
	v_lshlrev_b32_e32 v2, 11, v2
	s_waitcnt lgkmcnt(0)
	v_cvt_pk_bf16_f32 v79, v218, v219
	v_lshl_add_u64 v[82:83], v[80:81], 0, v[2:3]
	global_store_dwordx4 v[82:83], v[76:79], off
	v_or_b32_e32 v2, s8, v62
	v_lshlrev_b32_e32 v2, 11, v2
	s_waitcnt lgkmcnt(0)
	v_cvt_pk_bf16_f32 v76, v220, v221
	s_waitcnt lgkmcnt(0)
	v_cvt_pk_bf16_f32 v77, v222, v223
	s_waitcnt lgkmcnt(0)
	v_cvt_pk_bf16_f32 v78, v224, v225
	s_waitcnt lgkmcnt(0)
	v_cvt_pk_bf16_f32 v79, v226, v227
	v_lshl_add_u64 v[82:83], v[80:81], 0, v[2:3]
	global_store_dwordx4 v[82:83], v[76:79], off
	v_or_b32_e32 v2, s8, v64
	v_lshlrev_b32_e32 v2, 11, v2
	s_waitcnt lgkmcnt(0)
	v_cvt_pk_bf16_f32 v76, v228, v229
	s_waitcnt lgkmcnt(0)
	v_cvt_pk_bf16_f32 v77, v230, v231
	s_waitcnt lgkmcnt(0)
	v_cvt_pk_bf16_f32 v78, v232, v233
	s_waitcnt lgkmcnt(0)
	v_cvt_pk_bf16_f32 v79, v234, v235
	v_lshl_add_u64 v[82:83], v[80:81], 0, v[2:3]
	global_store_dwordx4 v[82:83], v[76:79], off
	v_or_b32_e32 v2, s8, v66
	v_lshlrev_b32_e32 v2, 11, v2
	s_waitcnt lgkmcnt(0)
	v_cvt_pk_bf16_f32 v76, v236, v237
	s_waitcnt lgkmcnt(0)
	v_cvt_pk_bf16_f32 v77, v238, v239
	s_waitcnt lgkmcnt(0)
	v_cvt_pk_bf16_f32 v78, v240, v241
	s_waitcnt lgkmcnt(0)
	v_cvt_pk_bf16_f32 v79, v242, v243
	v_lshl_add_u64 v[56:57], v[80:81], 0, v[2:3]
	global_store_dwordx4 v[56:57], v[76:79], off
	s_waitcnt lgkmcnt(0)
	s_cmpk_lt_i32 s37, 0x1520
	s_mov_b64 s[48:49], -1
	s_cbranch_scc0 .LBB0_1814

.LBB0_1831:
	v_lshlrev_b32_e32 v2, 8, v2
	global_load_dword v80, v76, s[22:23]
	v_lshl_add_u64 v[56:57], v[56:57], 0, v[2:3]
	global_load_dwordx4 v[76:79], v[56:57], off
	v_add_u32_e32 v81, 0x840, v58
	v_add_u32_e32 v58, 0x848, v58
	s_and_b32 s49, 0xffff, s49
	s_lshl_b32 s8, s48, 1
	s_waitcnt vmcnt(1)
	v_mul_f32_e32 v2, v60, v80
	s_waitcnt vmcnt(0)
	v_pk_mul_f32 v[76:77], v[76:77], v[2:3] op_sel_hi:[1,0]
	v_pk_mul_f32 v[56:57], v[78:79], v[2:3] op_sel_hi:[1,0]
	ds_write2_b32 v81, v76, v77 offset1:1
	ds_write2_b32 v58, v56, v57 offset1:1
	s_waitcnt lgkmcnt(0)
	ds_read2_b32 v[212:213], v74 offset1:33
	ds_read2_b32 v[214:215], v74 offset0:66 offset1:99
	ds_read2_b32 v[216:217], v74 offset0:132 offset1:165
	ds_read2_b32 v[218:219], v74 offset0:198 offset1:231
	ds_read2_b32 v[220:221], v74 offset0:8 offset1:41
	ds_read2_b32 v[222:223], v74 offset0:74 offset1:107
	ds_read2_b32 v[224:225], v74 offset0:140 offset1:173
	ds_read2_b32 v[226:227], v74 offset0:206 offset1:239
	ds_read2_b32 v[228:229], v74 offset0:16 offset1:49
	ds_read2_b32 v[230:231], v74 offset0:82 offset1:115
	ds_read2_b32 v[232:233], v74 offset0:148 offset1:181
	ds_read2_b32 v[234:235], v74 offset0:214 offset1:247
	ds_read2_b32 v[236:237], v74 offset0:24 offset1:57
	ds_read2_b32 v[238:239], v74 offset0:90 offset1:123
	ds_read2_b32 v[240:241], v74 offset0:156 offset1:189
	ds_read2_b32 v[242:243], v74 offset0:222 offset1:255
	s_waitcnt lgkmcnt(0)
	v_cvt_pk_bf16_f32 v76, v212, v213
	v_lshl_add_u64 v[80:81], v[8:9], 0, s[8:9]
	s_or_b32 s8, s49, 0x940
	s_waitcnt lgkmcnt(0)
	v_cvt_pk_bf16_f32 v77, v214, v215
	v_or_b32_e32 v2, s8, v1
	s_waitcnt lgkmcnt(0)
	v_cvt_pk_bf16_f32 v78, v216, v217
	v_lshlrev_b32_e32 v2, 11, v2
	s_waitcnt lgkmcnt(0)
	v_cvt_pk_bf16_f32 v79, v218, v219
	v_lshl_add_u64 v[82:83], v[80:81], 0, v[2:3]
	global_store_dwordx4 v[82:83], v[76:79], off
	v_or_b32_e32 v2, s8, v62
	v_lshlrev_b32_e32 v2, 11, v2
	s_waitcnt lgkmcnt(0)
	v_cvt_pk_bf16_f32 v76, v220, v221
	s_waitcnt lgkmcnt(0)
	v_cvt_pk_bf16_f32 v77, v222, v223
	s_waitcnt lgkmcnt(0)
	v_cvt_pk_bf16_f32 v78, v224, v225
	s_waitcnt lgkmcnt(0)
	v_cvt_pk_bf16_f32 v79, v226, v227
	v_lshl_add_u64 v[82:83], v[80:81], 0, v[2:3]
	global_store_dwordx4 v[82:83], v[76:79], off
	v_or_b32_e32 v2, s8, v64
	v_lshlrev_b32_e32 v2, 11, v2
	s_waitcnt lgkmcnt(0)
	v_cvt_pk_bf16_f32 v76, v228, v229
	s_waitcnt lgkmcnt(0)
	v_cvt_pk_bf16_f32 v77, v230, v231
	s_waitcnt lgkmcnt(0)
	v_cvt_pk_bf16_f32 v78, v232, v233
	s_waitcnt lgkmcnt(0)
	v_cvt_pk_bf16_f32 v79, v234, v235
	v_lshl_add_u64 v[82:83], v[80:81], 0, v[2:3]
	global_store_dwordx4 v[82:83], v[76:79], off
	v_or_b32_e32 v2, s8, v66
	v_lshlrev_b32_e32 v2, 11, v2
	s_waitcnt lgkmcnt(0)
	v_cvt_pk_bf16_f32 v76, v236, v237
	s_waitcnt lgkmcnt(0)
	v_cvt_pk_bf16_f32 v77, v238, v239
	s_waitcnt lgkmcnt(0)
	v_cvt_pk_bf16_f32 v78, v240, v241
	s_waitcnt lgkmcnt(0)
	v_cvt_pk_bf16_f32 v79, v242, v243
	v_lshl_add_u64 v[56:57], v[80:81], 0, v[2:3]
	global_store_dwordx4 v[56:57], v[76:79], off
	s_waitcnt lgkmcnt(0)

.LBB0_1850:
	v_lshlrev_b32_e32 v2, 8, v2
	global_load_dword v80, v76, s[16:17]
	v_lshl_add_u64 v[56:57], v[56:57], 0, v[2:3]
	global_load_dwordx4 v[76:79], v[56:57], off
	v_add_u32_e32 v81, 0x840, v58
	v_add_u32_e32 v58, 0x848, v58
	s_and_b32 s48, 0xffff, s48
	s_lshl_b32 s8, s37, 1
	s_waitcnt vmcnt(1)
	v_mul_f32_e32 v2, v60, v80
	s_waitcnt vmcnt(0)
	v_pk_mul_f32 v[76:77], v[76:77], v[2:3] op_sel_hi:[1,0]
	v_pk_mul_f32 v[56:57], v[78:79], v[2:3] op_sel_hi:[1,0]
	ds_write2_b32 v81, v76, v77 offset1:1
	ds_write2_b32 v58, v56, v57 offset1:1
	s_waitcnt lgkmcnt(0)
	ds_read2_b32 v[212:213], v74 offset1:33
	ds_read2_b32 v[214:215], v74 offset0:66 offset1:99
	ds_read2_b32 v[216:217], v74 offset0:132 offset1:165
	ds_read2_b32 v[218:219], v74 offset0:198 offset1:231
	ds_read2_b32 v[220:221], v74 offset0:8 offset1:41
	ds_read2_b32 v[222:223], v74 offset0:74 offset1:107
	ds_read2_b32 v[224:225], v74 offset0:140 offset1:173
	ds_read2_b32 v[226:227], v74 offset0:206 offset1:239
	ds_read2_b32 v[228:229], v74 offset0:16 offset1:49
	ds_read2_b32 v[230:231], v74 offset0:82 offset1:115
	ds_read2_b32 v[232:233], v74 offset0:148 offset1:181
	ds_read2_b32 v[234:235], v74 offset0:214 offset1:247
	ds_read2_b32 v[236:237], v74 offset0:24 offset1:57
	ds_read2_b32 v[238:239], v74 offset0:90 offset1:123
	ds_read2_b32 v[240:241], v74 offset0:156 offset1:189
	ds_read2_b32 v[242:243], v74 offset0:222 offset1:255
	s_waitcnt lgkmcnt(0)
	v_cvt_pk_bf16_f32 v76, v212, v213
	v_lshl_add_u64 v[80:81], v[8:9], 0, s[8:9]
	s_or_b32 s8, s48, 0x900
	s_waitcnt lgkmcnt(0)
	v_cvt_pk_bf16_f32 v77, v214, v215
	v_or_b32_e32 v2, s8, v1
	s_waitcnt lgkmcnt(0)
	v_cvt_pk_bf16_f32 v78, v216, v217
	v_lshlrev_b32_e32 v2, 11, v2
	s_waitcnt lgkmcnt(0)
	v_cvt_pk_bf16_f32 v79, v218, v219
	v_lshl_add_u64 v[82:83], v[80:81], 0, v[2:3]
	global_store_dwordx4 v[82:83], v[76:79], off
	v_or_b32_e32 v2, s8, v62
	v_lshlrev_b32_e32 v2, 11, v2
	s_waitcnt lgkmcnt(0)
	v_cvt_pk_bf16_f32 v76, v220, v221
	s_waitcnt lgkmcnt(0)
	v_cvt_pk_bf16_f32 v77, v222, v223
	s_waitcnt lgkmcnt(0)
	v_cvt_pk_bf16_f32 v78, v224, v225
	s_waitcnt lgkmcnt(0)
	v_cvt_pk_bf16_f32 v79, v226, v227
	v_lshl_add_u64 v[82:83], v[80:81], 0, v[2:3]
	global_store_dwordx4 v[82:83], v[76:79], off
	v_or_b32_e32 v2, s8, v64
	v_lshlrev_b32_e32 v2, 11, v2
	s_waitcnt lgkmcnt(0)
	v_cvt_pk_bf16_f32 v76, v228, v229
	s_waitcnt lgkmcnt(0)
	v_cvt_pk_bf16_f32 v77, v230, v231
	s_waitcnt lgkmcnt(0)
	v_cvt_pk_bf16_f32 v78, v232, v233
	s_waitcnt lgkmcnt(0)
	v_cvt_pk_bf16_f32 v79, v234, v235
	v_lshl_add_u64 v[82:83], v[80:81], 0, v[2:3]
	global_store_dwordx4 v[82:83], v[76:79], off
	v_or_b32_e32 v2, s8, v66
	v_lshlrev_b32_e32 v2, 11, v2
	s_waitcnt lgkmcnt(0)
	v_cvt_pk_bf16_f32 v76, v236, v237
	s_waitcnt lgkmcnt(0)
	v_cvt_pk_bf16_f32 v77, v238, v239
	s_waitcnt lgkmcnt(0)
	v_cvt_pk_bf16_f32 v78, v240, v241
	s_waitcnt lgkmcnt(0)
	v_cvt_pk_bf16_f32 v79, v242, v243
	v_lshl_add_u64 v[56:57], v[80:81], 0, v[2:3]
	global_store_dwordx4 v[56:57], v[76:79], off
	s_waitcnt lgkmcnt(0)

.LBB0_1868:
	v_lshlrev_b32_e32 v2, 9, v2
	global_load_dword v80, v76, s[24:25]
	v_lshl_add_u64 v[56:57], v[56:57], 0, v[2:3]
	global_load_dwordx4 v[76:79], v[56:57], off
	v_add_u32_e32 v81, 0x840, v58
	v_add_u32_e32 v58, 0x848, v58
	s_lshl_b32 s4, s1, 5
	s_or_b32 s4, s4, 0x980
	s_and_b32 s4, s4, 0x9ff
	s_lshl_b32 s8, s37, 1
	s_waitcnt vmcnt(1)
	v_mul_f32_e32 v2, v60, v80
	s_waitcnt vmcnt(0)
	v_pk_mul_f32 v[76:77], v[76:77], v[2:3] op_sel_hi:[1,0]
	v_pk_mul_f32 v[56:57], v[78:79], v[2:3] op_sel_hi:[1,0]
	ds_write2_b32 v81, v76, v77 offset1:1
	ds_write2_b32 v58, v56, v57 offset1:1
	s_waitcnt lgkmcnt(0)
	ds_read2_b32 v[212:213], v74 offset1:33
	ds_read2_b32 v[214:215], v74 offset0:66 offset1:99
	ds_read2_b32 v[216:217], v74 offset0:132 offset1:165
	ds_read2_b32 v[218:219], v74 offset0:198 offset1:231
	ds_read2_b32 v[220:221], v74 offset0:8 offset1:41
	ds_read2_b32 v[222:223], v74 offset0:74 offset1:107
	ds_read2_b32 v[224:225], v74 offset0:140 offset1:173
	ds_read2_b32 v[226:227], v74 offset0:206 offset1:239
	ds_read2_b32 v[228:229], v74 offset0:16 offset1:49
	ds_read2_b32 v[230:231], v74 offset0:82 offset1:115
	ds_read2_b32 v[232:233], v74 offset0:148 offset1:181
	ds_read2_b32 v[234:235], v74 offset0:214 offset1:247
	ds_read2_b32 v[236:237], v74 offset0:24 offset1:57
	ds_read2_b32 v[238:239], v74 offset0:90 offset1:123
	ds_read2_b32 v[240:241], v74 offset0:156 offset1:189
	ds_read2_b32 v[242:243], v74 offset0:222 offset1:255
	s_waitcnt lgkmcnt(0)
	v_cvt_pk_bf16_f32 v76, v212, v213
	s_waitcnt lgkmcnt(0)
	v_cvt_pk_bf16_f32 v77, v214, v215
	v_or_b32_e32 v2, s4, v1
	s_waitcnt lgkmcnt(0)
	v_cvt_pk_bf16_f32 v78, v216, v217
	v_lshl_add_u64 v[80:81], v[8:9], 0, s[8:9]
	v_lshlrev_b32_e32 v2, 11, v2
	s_waitcnt lgkmcnt(0)
	v_cvt_pk_bf16_f32 v79, v218, v219
	v_lshl_add_u64 v[82:83], v[80:81], 0, v[2:3]
	global_store_dwordx4 v[82:83], v[76:79], off
	v_or_b32_e32 v2, s4, v62
	v_lshlrev_b32_e32 v2, 11, v2
	s_waitcnt lgkmcnt(0)
	v_cvt_pk_bf16_f32 v76, v220, v221
	s_waitcnt lgkmcnt(0)
	v_cvt_pk_bf16_f32 v77, v222, v223
	s_waitcnt lgkmcnt(0)
	v_cvt_pk_bf16_f32 v78, v224, v225
	s_waitcnt lgkmcnt(0)
	v_cvt_pk_bf16_f32 v79, v226, v227
	v_lshl_add_u64 v[82:83], v[80:81], 0, v[2:3]
	global_store_dwordx4 v[82:83], v[76:79], off
	v_or_b32_e32 v2, s4, v64
	v_lshlrev_b32_e32 v2, 11, v2
	s_waitcnt lgkmcnt(0)
	v_cvt_pk_bf16_f32 v76, v228, v229
	s_waitcnt lgkmcnt(0)
	v_cvt_pk_bf16_f32 v77, v230, v231
	s_waitcnt lgkmcnt(0)
	v_cvt_pk_bf16_f32 v78, v232, v233
	s_waitcnt lgkmcnt(0)
	v_cvt_pk_bf16_f32 v79, v234, v235
	v_lshl_add_u64 v[82:83], v[80:81], 0, v[2:3]
	global_store_dwordx4 v[82:83], v[76:79], off
	v_or_b32_e32 v2, s4, v66
	v_lshlrev_b32_e32 v2, 11, v2
	s_waitcnt lgkmcnt(0)
	v_cvt_pk_bf16_f32 v76, v236, v237
	s_waitcnt lgkmcnt(0)
	v_cvt_pk_bf16_f32 v77, v238, v239
	s_waitcnt lgkmcnt(0)
	v_cvt_pk_bf16_f32 v78, v240, v241
	s_waitcnt lgkmcnt(0)
	v_cvt_pk_bf16_f32 v79, v242, v243
	v_lshl_add_u64 v[56:57], v[80:81], 0, v[2:3]
	global_store_dwordx4 v[56:57], v[76:79], off
	s_waitcnt lgkmcnt(0)
	s_and_b32 s8, s1, -8
	s_cmpk_lt_i32 s8, 0x1588
	s_mov_b64 s[4:5], -1
	s_cbranch_scc0 .LBB0_1871

.LBB0_1871:
	s_cmpk_eq_i32 s8, 0x1588
	s_cbranch_scc0 .LBB0_1873
	s_load_dwordx2 s[4:5], s[10:11], 0xc8
	s_lshl_b32 s37, s1, 5
	s_addk_i32 s37, 0x4f00
	s_and_b32 s37, s37, 0xffe0
	s_lshl_b32 s48, s37, 2
	s_waitcnt lgkmcnt(0)
	s_add_u32 s4, s4, s48
	s_addc_u32 s5, s5, 0
	v_lshlrev_b32_e32 v2, 2, v0
	v_lshl_add_u64 v[56:57], s[4:5], 0, v[2:3]
	v_lshl_add_u64 v[56:57], v[56:57], 0, s[30:31]
	v_lshl_add_u64 v[76:77], v[56:57], 0, v[16:17]
	global_load_dwordx4 v[76:79], v[76:77], off
	v_lshl_add_u64 v[80:81], v[56:57], 0, v[18:19]
	global_load_dwordx4 v[80:83], v[80:81], off
	v_lshl_add_u64 v[84:85], v[56:57], 0, v[20:21]
	global_load_dwordx4 v[84:87], v[84:85], off
	v_lshl_add_u64 v[88:89], v[56:57], 0, v[22:23]
	global_load_dwordx4 v[88:91], v[88:89], off
	v_lshl_add_u64 v[92:93], v[56:57], 0, v[24:25]
	global_load_dwordx4 v[92:95], v[92:93], off
	v_lshl_add_u64 v[96:97], v[56:57], 0, v[26:27]
	global_load_dwordx4 v[96:99], v[96:97], off
	v_lshl_add_u64 v[100:101], v[56:57], 0, v[28:29]
	global_load_dwordx4 v[100:103], v[100:101], off
	v_lshl_add_u64 v[56:57], v[56:57], 0, v[30:31]
	global_load_dwordx4 v[104:107], v[56:57], off
	v_add_u32_e32 v2, v59, v61
	v_add_u32_e32 v56, v59, v71
	v_add_u32_e32 v57, 0x420, v2
	v_add_u32_e32 v58, 0x428, v2
	v_add_u32_e32 v60, 0x840, v2
	v_add_u32_e32 v108, 0x848, v2
	v_add_u32_e32 v109, 0xc60, v2
	v_add_u32_e32 v110, 0xc68, v2
	v_add_u32_e32 v111, 0x1080, v2
	v_add_u32_e32 v112, 0x1088, v2
	v_add_u32_e32 v113, 0x14a0, v2
	v_add_u32_e32 v114, 0x420, v56
	v_add_u32_e32 v115, 0x428, v56
	v_add_u32_e32 v116, 0x840, v56
	v_add_u32_e32 v117, 0x848, v56
	s_waitcnt vmcnt(7)
	ds_write2_b32 v2, v76, v77 offset1:1
	ds_write2_b32 v2, v78, v79 offset0:2 offset1:3
	s_waitcnt vmcnt(6)
	ds_write2_b32 v57, v80, v81 offset1:1
	ds_write2_b32 v58, v82, v83 offset1:1
	s_waitcnt vmcnt(5)
	ds_write2_b32 v60, v84, v85 offset1:1
	ds_write2_b32 v108, v86, v87 offset1:1
	s_waitcnt vmcnt(4)
	ds_write2_b32 v109, v88, v89 offset1:1
	ds_write2_b32 v110, v90, v91 offset1:1
	s_waitcnt vmcnt(3)
	ds_write2_b32 v111, v92, v93 offset1:1
	ds_write2_b32 v112, v94, v95 offset1:1
	s_waitcnt vmcnt(2)
	ds_write2_b32 v113, v96, v97 offset1:1
	ds_write2_b32 v56, v98, v99 offset0:2 offset1:3
	s_waitcnt vmcnt(1)
	ds_write2_b32 v114, v100, v101 offset1:1
	ds_write2_b32 v115, v102, v103 offset1:1
	s_waitcnt vmcnt(0)
	ds_write2_b32 v116, v104, v105 offset1:1
	ds_write2_b32 v117, v106, v107 offset1:1
	s_waitcnt lgkmcnt(0)
	ds_read2_b32 v[212:213], v74 offset1:33
	ds_read2_b32 v[214:215], v74 offset0:66 offset1:99
	ds_read2_b32 v[216:217], v74 offset0:132 offset1:165
	ds_read2_b32 v[218:219], v74 offset0:198 offset1:231
	ds_read2_b32 v[220:221], v74 offset0:8 offset1:41
	ds_read2_b32 v[222:223], v74 offset0:74 offset1:107
	ds_read2_b32 v[224:225], v74 offset0:140 offset1:173
	ds_read2_b32 v[226:227], v74 offset0:206 offset1:239
	ds_read2_b32 v[228:229], v74 offset0:16 offset1:49
	ds_read2_b32 v[230:231], v74 offset0:82 offset1:115
	ds_read2_b32 v[232:233], v74 offset0:148 offset1:181
	ds_read2_b32 v[234:235], v74 offset0:214 offset1:247
	ds_read2_b32 v[236:237], v74 offset0:24 offset1:57
	ds_read2_b32 v[238:239], v74 offset0:90 offset1:123
	ds_read2_b32 v[240:241], v74 offset0:156 offset1:189
	ds_read2_b32 v[242:243], v74 offset0:222 offset1:255
	s_waitcnt lgkmcnt(0)
	v_cvt_pk_bf16_f32 v76, v212, v213
	s_waitcnt lgkmcnt(0)
	v_cvt_pk_bf16_f32 v77, v214, v215
	v_or_b32_e32 v2, s37, v1
	s_waitcnt lgkmcnt(0)
	v_cvt_pk_bf16_f32 v78, v216, v217
	v_lshlrev_b32_e32 v2, 7, v2
	s_waitcnt lgkmcnt(0)
	v_cvt_pk_bf16_f32 v79, v218, v219
	v_lshl_add_u64 v[80:81], v[32:33], 0, v[2:3]
	global_store_dwordx4 v[80:81], v[76:79], off
	v_or_b32_e32 v2, s37, v62
	v_lshlrev_b32_e32 v2, 7, v2
	s_waitcnt lgkmcnt(0)
	v_cvt_pk_bf16_f32 v76, v220, v221
	s_waitcnt lgkmcnt(0)
	v_cvt_pk_bf16_f32 v77, v222, v223
	s_waitcnt lgkmcnt(0)
	v_cvt_pk_bf16_f32 v78, v224, v225
	s_waitcnt lgkmcnt(0)
	v_cvt_pk_bf16_f32 v79, v226, v227
	v_lshl_add_u64 v[80:81], v[32:33], 0, v[2:3]
	global_store_dwordx4 v[80:81], v[76:79], off
	v_or_b32_e32 v2, s37, v64
	v_lshlrev_b32_e32 v2, 7, v2
	s_waitcnt lgkmcnt(0)
	v_cvt_pk_bf16_f32 v76, v228, v229
	s_waitcnt lgkmcnt(0)
	v_cvt_pk_bf16_f32 v77, v230, v231
	s_waitcnt lgkmcnt(0)
	v_cvt_pk_bf16_f32 v78, v232, v233
	s_waitcnt lgkmcnt(0)
	v_cvt_pk_bf16_f32 v79, v234, v235
	v_lshl_add_u64 v[80:81], v[32:33], 0, v[2:3]
	global_store_dwordx4 v[80:81], v[76:79], off
	v_or_b32_e32 v2, s37, v66
	v_lshlrev_b32_e32 v2, 7, v2
	s_waitcnt lgkmcnt(0)
	v_cvt_pk_bf16_f32 v76, v236, v237
	s_waitcnt lgkmcnt(0)
	v_cvt_pk_bf16_f32 v77, v238, v239
	s_waitcnt lgkmcnt(0)
	v_cvt_pk_bf16_f32 v78, v240, v241
	s_waitcnt lgkmcnt(0)
	v_cvt_pk_bf16_f32 v79, v242, v243
	v_lshl_add_u64 v[56:57], v[32:33], 0, v[2:3]
	global_store_dwordx4 v[56:57], v[76:79], off
	s_waitcnt lgkmcnt(0)

.LBB0_1874:
	s_cmpk_lg_i32 s8, 0x1580
	s_cbranch_scc1 .LBB0_1876
	s_load_dwordx2 s[4:5], s[10:11], 0xb0
	s_lshl_b32 s8, s1, 5
	s_addk_i32 s8, 0x5000
	s_and_b32 s8, s8, 0xffe0
	s_lshl_b32 s37, s8, 2
	s_waitcnt lgkmcnt(0)
	s_add_u32 s4, s4, s37
	s_addc_u32 s5, s5, 0
	v_lshlrev_b32_e32 v2, 2, v0
	v_lshl_add_u64 v[56:57], s[4:5], 0, v[2:3]
	v_lshl_add_u64 v[56:57], v[56:57], 0, s[30:31]
	v_lshl_add_u64 v[76:77], v[56:57], 0, v[16:17]
	global_load_dwordx4 v[76:79], v[76:77], off
	v_lshl_add_u64 v[80:81], v[56:57], 0, v[18:19]
	global_load_dwordx4 v[80:83], v[80:81], off
	v_lshl_add_u64 v[84:85], v[56:57], 0, v[20:21]
	global_load_dwordx4 v[84:87], v[84:85], off
	v_lshl_add_u64 v[88:89], v[56:57], 0, v[22:23]
	global_load_dwordx4 v[88:91], v[88:89], off
	v_lshl_add_u64 v[92:93], v[56:57], 0, v[24:25]
	global_load_dwordx4 v[92:95], v[92:93], off
	v_lshl_add_u64 v[96:97], v[56:57], 0, v[26:27]
	global_load_dwordx4 v[96:99], v[96:97], off
	v_lshl_add_u64 v[100:101], v[56:57], 0, v[28:29]
	global_load_dwordx4 v[100:103], v[100:101], off
	v_lshl_add_u64 v[56:57], v[56:57], 0, v[30:31]
	global_load_dwordx4 v[104:107], v[56:57], off
	v_add_u32_e32 v2, v59, v61
	v_add_u32_e32 v56, v59, v71
	v_add_u32_e32 v57, 0x420, v2
	v_add_u32_e32 v58, 0x428, v2
	v_add_u32_e32 v60, 0x840, v2
	v_add_u32_e32 v108, 0x848, v2
	v_add_u32_e32 v109, 0xc60, v2
	v_add_u32_e32 v110, 0xc68, v2
	v_add_u32_e32 v111, 0x1080, v2
	v_add_u32_e32 v112, 0x1088, v2
	v_add_u32_e32 v113, 0x14a0, v2
	v_add_u32_e32 v114, 0x420, v56
	v_add_u32_e32 v115, 0x428, v56
	v_add_u32_e32 v116, 0x840, v56
	v_add_u32_e32 v117, 0x848, v56
	s_waitcnt vmcnt(7)
	ds_write2_b32 v2, v76, v77 offset1:1
	ds_write2_b32 v2, v78, v79 offset0:2 offset1:3
	s_waitcnt vmcnt(6)
	ds_write2_b32 v57, v80, v81 offset1:1
	ds_write2_b32 v58, v82, v83 offset1:1
	s_waitcnt vmcnt(5)
	ds_write2_b32 v60, v84, v85 offset1:1
	ds_write2_b32 v108, v86, v87 offset1:1
	s_waitcnt vmcnt(4)
	ds_write2_b32 v109, v88, v89 offset1:1
	ds_write2_b32 v110, v90, v91 offset1:1
	s_waitcnt vmcnt(3)
	ds_write2_b32 v111, v92, v93 offset1:1
	ds_write2_b32 v112, v94, v95 offset1:1
	s_waitcnt vmcnt(2)
	ds_write2_b32 v113, v96, v97 offset1:1
	ds_write2_b32 v56, v98, v99 offset0:2 offset1:3
	s_waitcnt vmcnt(1)
	ds_write2_b32 v114, v100, v101 offset1:1
	ds_write2_b32 v115, v102, v103 offset1:1
	s_waitcnt vmcnt(0)
	ds_write2_b32 v116, v104, v105 offset1:1
	ds_write2_b32 v117, v106, v107 offset1:1
	s_waitcnt lgkmcnt(0)
	ds_read2_b32 v[212:213], v74 offset1:33
	ds_read2_b32 v[214:215], v74 offset0:66 offset1:99
	ds_read2_b32 v[216:217], v74 offset0:132 offset1:165
	ds_read2_b32 v[218:219], v74 offset0:198 offset1:231
	ds_read2_b32 v[220:221], v74 offset0:8 offset1:41
	ds_read2_b32 v[222:223], v74 offset0:74 offset1:107
	ds_read2_b32 v[224:225], v74 offset0:140 offset1:173
	ds_read2_b32 v[226:227], v74 offset0:206 offset1:239
	ds_read2_b32 v[228:229], v74 offset0:16 offset1:49
	ds_read2_b32 v[230:231], v74 offset0:82 offset1:115
	ds_read2_b32 v[232:233], v74 offset0:148 offset1:181
	ds_read2_b32 v[234:235], v74 offset0:214 offset1:247
	ds_read2_b32 v[236:237], v74 offset0:24 offset1:57
	ds_read2_b32 v[238:239], v74 offset0:90 offset1:123
	ds_read2_b32 v[240:241], v74 offset0:156 offset1:189
	ds_read2_b32 v[242:243], v74 offset0:222 offset1:255
	s_waitcnt lgkmcnt(0)
	v_cvt_pk_bf16_f32 v76, v212, v213
	s_waitcnt lgkmcnt(0)
	v_cvt_pk_bf16_f32 v77, v214, v215
	v_or_b32_e32 v2, s8, v1
	s_waitcnt lgkmcnt(0)
	v_cvt_pk_bf16_f32 v78, v216, v217
	v_lshlrev_b32_e32 v2, 7, v2
	s_waitcnt lgkmcnt(0)
	v_cvt_pk_bf16_f32 v79, v218, v219
	v_lshl_add_u64 v[80:81], v[34:35], 0, v[2:3]
	global_store_dwordx4 v[80:81], v[76:79], off
	v_or_b32_e32 v2, s8, v62
	v_lshlrev_b32_e32 v2, 7, v2
	s_waitcnt lgkmcnt(0)
	v_cvt_pk_bf16_f32 v76, v220, v221
	s_waitcnt lgkmcnt(0)
	v_cvt_pk_bf16_f32 v77, v222, v223
	s_waitcnt lgkmcnt(0)
	v_cvt_pk_bf16_f32 v78, v224, v225
	s_waitcnt lgkmcnt(0)
	v_cvt_pk_bf16_f32 v79, v226, v227
	v_lshl_add_u64 v[80:81], v[34:35], 0, v[2:3]
	global_store_dwordx4 v[80:81], v[76:79], off
	v_or_b32_e32 v2, s8, v64
	v_lshlrev_b32_e32 v2, 7, v2
	s_waitcnt lgkmcnt(0)
	v_cvt_pk_bf16_f32 v76, v228, v229
	s_waitcnt lgkmcnt(0)
	v_cvt_pk_bf16_f32 v77, v230, v231
	s_waitcnt lgkmcnt(0)
	v_cvt_pk_bf16_f32 v78, v232, v233
	s_waitcnt lgkmcnt(0)
	v_cvt_pk_bf16_f32 v79, v234, v235
	v_lshl_add_u64 v[80:81], v[34:35], 0, v[2:3]
	global_store_dwordx4 v[80:81], v[76:79], off
	v_or_b32_e32 v2, s8, v66
	v_lshlrev_b32_e32 v2, 7, v2
	s_waitcnt lgkmcnt(0)
	v_cvt_pk_bf16_f32 v76, v236, v237
	s_waitcnt lgkmcnt(0)
	v_cvt_pk_bf16_f32 v77, v238, v239
	s_waitcnt lgkmcnt(0)
	v_cvt_pk_bf16_f32 v78, v240, v241
	s_waitcnt lgkmcnt(0)
	v_cvt_pk_bf16_f32 v79, v242, v243
	v_lshl_add_u64 v[56:57], v[34:35], 0, v[2:3]
	global_store_dwordx4 v[56:57], v[76:79], off
	s_waitcnt lgkmcnt(0)
.LBB0_1876:
	s_and_b32 s4, s1, -16
	s_cmpk_lg_i32 s4, 0x1590
	s_cbranch_scc1 .LBB0_1879
	s_add_i32 s4, s1, 0xea70
	s_and_b32 s5, s4, 0xffff
	s_add_i32 s8, s1, 0xea68
	s_load_dwordx2 s[48:49], s[10:11], 0xd8
	s_cmp_lt_u32 s5, 8
	s_cselect_b32 s4, s4, s8
	s_cmp_gt_u32 s5, 7
	s_cselect_b32 s5, 64, 0
	s_lshl_b32 s4, s4, 5
	s_and_b32 s4, s4, 0xffe0
	s_lshl_b32 s8, s4, 2
	s_waitcnt lgkmcnt(0)
	s_add_u32 s48, s48, s8
	s_addc_u32 s49, s49, 0
	v_lshlrev_b32_e32 v2, 2, v0
	v_lshl_add_u64 v[56:57], s[48:49], 0, v[2:3]
	v_or_b32_e32 v2, s5, v1
	v_lshl_add_u64 v[56:57], v[56:57], 0, s[34:35]
	v_lshlrev_b32_e32 v2, 10, v2
	v_lshl_add_u64 v[76:77], v[56:57], 0, v[2:3]
	v_or_b32_e32 v2, s5, v62
	v_lshlrev_b32_e32 v2, 10, v2
	v_lshl_add_u64 v[80:81], v[56:57], 0, v[2:3]
	v_or_b32_e32 v2, s5, v64
	v_lshlrev_b32_e32 v2, 10, v2
	v_lshl_add_u64 v[84:85], v[56:57], 0, v[2:3]
	v_or_b32_e32 v2, s5, v66
	v_lshlrev_b32_e32 v2, 10, v2
	v_lshl_add_u64 v[88:89], v[56:57], 0, v[2:3]
	v_or_b32_e32 v2, s5, v68
	v_lshlrev_b32_e32 v2, 10, v2
	v_lshl_add_u64 v[92:93], v[56:57], 0, v[2:3]
	v_or_b32_e32 v2, s5, v70
	v_lshlrev_b32_e32 v2, 10, v2
	v_lshl_add_u64 v[96:97], v[56:57], 0, v[2:3]
	global_load_dwordx4 v[76:79], v[76:77], off
	s_nop 0
	global_load_dwordx4 v[80:83], v[80:81], off
	s_nop 0
	global_load_dwordx4 v[84:87], v[84:85], off
	s_nop 0
	global_load_dwordx4 v[88:91], v[88:89], off
	s_nop 0
	global_load_dwordx4 v[92:95], v[92:93], off
	s_nop 0
	global_load_dwordx4 v[96:99], v[96:97], off
	v_or_b32_e32 v2, s5, v72
	v_lshlrev_b32_e32 v2, 10, v2
	v_lshl_add_u64 v[100:101], v[56:57], 0, v[2:3]
	v_or_b32_e32 v2, s5, v73
	global_load_dwordx4 v[100:103], v[100:101], off
	v_lshlrev_b32_e32 v2, 10, v2
	v_lshl_add_u64 v[56:57], v[56:57], 0, v[2:3]
	global_load_dwordx4 v[104:107], v[56:57], off
	v_add_u32_e32 v2, v59, v61
	v_add_u32_e32 v56, v59, v71
	v_add_u32_e32 v57, 0x420, v2
	v_add_u32_e32 v58, 0x428, v2
	v_add_u32_e32 v60, 0x840, v2
	v_add_u32_e32 v108, 0x848, v2
	v_add_u32_e32 v109, 0xc60, v2
	v_add_u32_e32 v110, 0xc68, v2
	v_add_u32_e32 v111, 0x1080, v2
	v_add_u32_e32 v112, 0x1088, v2
	v_add_u32_e32 v113, 0x14a0, v2
	v_add_u32_e32 v114, 0x420, v56
	v_add_u32_e32 v115, 0x428, v56
	v_add_u32_e32 v116, 0x840, v56
	v_add_u32_e32 v117, 0x848, v56
	s_lshl_b32 s8, s5, 1
	s_waitcnt vmcnt(7)
	ds_write2_b32 v2, v76, v77 offset1:1
	ds_write2_b32 v2, v78, v79 offset0:2 offset1:3
	s_waitcnt vmcnt(6)
	ds_write2_b32 v57, v80, v81 offset1:1
	ds_write2_b32 v58, v82, v83 offset1:1
	s_waitcnt vmcnt(5)
	ds_write2_b32 v60, v84, v85 offset1:1
	ds_write2_b32 v108, v86, v87 offset1:1
	s_waitcnt vmcnt(4)
	ds_write2_b32 v109, v88, v89 offset1:1
	ds_write2_b32 v110, v90, v91 offset1:1
	s_waitcnt vmcnt(3)
	ds_write2_b32 v111, v92, v93 offset1:1
	ds_write2_b32 v112, v94, v95 offset1:1
	s_waitcnt vmcnt(2)
	ds_write2_b32 v113, v96, v97 offset1:1
	ds_write2_b32 v56, v98, v99 offset0:2 offset1:3
	s_waitcnt vmcnt(1)
	ds_write2_b32 v114, v100, v101 offset1:1
	ds_write2_b32 v115, v102, v103 offset1:1
	s_waitcnt vmcnt(0)
	ds_write2_b32 v116, v104, v105 offset1:1
	ds_write2_b32 v117, v106, v107 offset1:1
	s_waitcnt lgkmcnt(0)
	ds_read2_b32 v[212:213], v74 offset1:33
	ds_read2_b32 v[214:215], v74 offset0:66 offset1:99
	ds_read2_b32 v[216:217], v74 offset0:132 offset1:165
	ds_read2_b32 v[218:219], v74 offset0:198 offset1:231
	ds_read2_b32 v[220:221], v74 offset0:8 offset1:41
	ds_read2_b32 v[222:223], v74 offset0:74 offset1:107
	ds_read2_b32 v[224:225], v74 offset0:140 offset1:173
	ds_read2_b32 v[226:227], v74 offset0:206 offset1:239
	ds_read2_b32 v[228:229], v74 offset0:16 offset1:49
	ds_read2_b32 v[230:231], v74 offset0:82 offset1:115
	ds_read2_b32 v[232:233], v74 offset0:148 offset1:181
	ds_read2_b32 v[234:235], v74 offset0:214 offset1:247
	ds_read2_b32 v[236:237], v74 offset0:24 offset1:57
	ds_read2_b32 v[238:239], v74 offset0:90 offset1:123
	ds_read2_b32 v[240:241], v74 offset0:156 offset1:189
	ds_read2_b32 v[242:243], v74 offset0:222 offset1:255
	s_waitcnt lgkmcnt(0)
	v_cvt_pk_bf16_f32 v76, v212, v213
	s_waitcnt lgkmcnt(0)
	v_cvt_pk_bf16_f32 v77, v214, v215
	v_or_b32_e32 v2, s4, v1
	s_waitcnt lgkmcnt(0)
	v_cvt_pk_bf16_f32 v78, v216, v217
	v_lshl_add_u64 v[80:81], v[36:37], 0, s[8:9]
	v_lshlrev_b32_e32 v2, 8, v2
	s_waitcnt lgkmcnt(0)
	v_cvt_pk_bf16_f32 v79, v218, v219
	v_lshl_add_u64 v[82:83], v[80:81], 0, v[2:3]
	global_store_dwordx4 v[82:83], v[76:79], off
	v_or_b32_e32 v2, s4, v62
	v_lshlrev_b32_e32 v2, 8, v2
	s_waitcnt lgkmcnt(0)
	v_cvt_pk_bf16_f32 v76, v220, v221
	s_waitcnt lgkmcnt(0)
	v_cvt_pk_bf16_f32 v77, v222, v223
	s_waitcnt lgkmcnt(0)
	v_cvt_pk_bf16_f32 v78, v224, v225
	s_waitcnt lgkmcnt(0)
	v_cvt_pk_bf16_f32 v79, v226, v227
	v_lshl_add_u64 v[82:83], v[80:81], 0, v[2:3]
	global_store_dwordx4 v[82:83], v[76:79], off
	v_or_b32_e32 v2, s4, v64
	v_lshlrev_b32_e32 v2, 8, v2
	s_waitcnt lgkmcnt(0)
	v_cvt_pk_bf16_f32 v76, v228, v229
	s_waitcnt lgkmcnt(0)
	v_cvt_pk_bf16_f32 v77, v230, v231
	s_waitcnt lgkmcnt(0)
	v_cvt_pk_bf16_f32 v78, v232, v233
	s_waitcnt lgkmcnt(0)
	v_cvt_pk_bf16_f32 v79, v234, v235
	v_lshl_add_u64 v[82:83], v[80:81], 0, v[2:3]
	global_store_dwordx4 v[82:83], v[76:79], off
	v_or_b32_e32 v2, s4, v66
	v_lshlrev_b32_e32 v2, 8, v2
	s_waitcnt lgkmcnt(0)
	v_cvt_pk_bf16_f32 v76, v236, v237
	s_waitcnt lgkmcnt(0)
	v_cvt_pk_bf16_f32 v77, v238, v239
	s_waitcnt lgkmcnt(0)
	v_cvt_pk_bf16_f32 v78, v240, v241
	s_waitcnt lgkmcnt(0)
	v_cvt_pk_bf16_f32 v79, v242, v243
	v_lshl_add_u64 v[56:57], v[80:81], 0, v[2:3]
	global_store_dwordx4 v[56:57], v[76:79], off
	s_waitcnt lgkmcnt(0)
	s_and_b32 s8, s1, -2
	s_cmpk_lt_i32 s8, 0x15a4
	s_mov_b64 s[4:5], -1
	s_cbranch_scc0 .LBB0_1880

.LBB0_1880:
	s_cmpk_lt_i32 s8, 0x15a6
	s_cbranch_scc1 .LBB0_1884
	s_cmpk_eq_i32 s8, 0x15a6
	s_cbranch_scc0 .LBB0_1883
	s_load_dwordx2 s[4:5], s[10:11], 0x80
	s_lshl_b32 s37, s1, 5
	s_addk_i32 s37, 0x4b40
	s_and_b32 s37, s37, 0xffe0
	s_lshl_b32 s48, s37, 2
	s_waitcnt lgkmcnt(0)
	s_add_u32 s4, s4, s48
	s_addc_u32 s5, s5, 0
	v_lshlrev_b32_e32 v2, 2, v0
	v_lshl_add_u64 v[56:57], s[4:5], 0, v[2:3]
	v_lshl_add_u64 v[56:57], v[56:57], 0, s[38:39]
	v_lshl_add_u64 v[76:77], v[56:57], 0, v[38:39]
	global_load_dwordx4 v[76:79], v[76:77], off
	v_lshl_add_u64 v[80:81], v[56:57], 0, v[40:41]
	global_load_dwordx4 v[80:83], v[80:81], off
	v_lshl_add_u64 v[84:85], v[56:57], 0, v[42:43]
	global_load_dwordx4 v[84:87], v[84:85], off
	v_lshl_add_u64 v[88:89], v[56:57], 0, v[44:45]
	global_load_dwordx4 v[88:91], v[88:89], off
	v_lshl_add_u64 v[92:93], v[56:57], 0, v[46:47]
	global_load_dwordx4 v[92:95], v[92:93], off
	v_lshl_add_u64 v[96:97], v[56:57], 0, v[48:49]
	global_load_dwordx4 v[96:99], v[96:97], off
	v_lshl_add_u64 v[100:101], v[56:57], 0, v[50:51]
	global_load_dwordx4 v[100:103], v[100:101], off
	v_lshl_add_u64 v[56:57], v[56:57], 0, v[52:53]
	global_load_dwordx4 v[104:107], v[56:57], off
	v_add_u32_e32 v2, v59, v61
	v_add_u32_e32 v56, v59, v71
	v_add_u32_e32 v57, 0x420, v2
	v_add_u32_e32 v58, 0x428, v2
	v_add_u32_e32 v60, 0x840, v2
	v_add_u32_e32 v108, 0x848, v2
	v_add_u32_e32 v109, 0xc60, v2
	v_add_u32_e32 v110, 0xc68, v2
	v_add_u32_e32 v111, 0x1080, v2
	v_add_u32_e32 v112, 0x1088, v2
	v_add_u32_e32 v113, 0x14a0, v2
	v_add_u32_e32 v114, 0x420, v56
	v_add_u32_e32 v115, 0x428, v56
	v_add_u32_e32 v116, 0x840, v56
	v_add_u32_e32 v117, 0x848, v56
	s_addk_i32 s37, 0xc0
	s_waitcnt vmcnt(7)
	ds_write2_b32 v2, v76, v77 offset1:1
	ds_write2_b32 v2, v78, v79 offset0:2 offset1:3
	s_waitcnt vmcnt(6)
	ds_write2_b32 v57, v80, v81 offset1:1
	ds_write2_b32 v58, v82, v83 offset1:1
	s_waitcnt vmcnt(5)
	ds_write2_b32 v60, v84, v85 offset1:1
	ds_write2_b32 v108, v86, v87 offset1:1
	s_waitcnt vmcnt(4)
	ds_write2_b32 v109, v88, v89 offset1:1
	ds_write2_b32 v110, v90, v91 offset1:1
	s_waitcnt vmcnt(3)
	ds_write2_b32 v111, v92, v93 offset1:1
	ds_write2_b32 v112, v94, v95 offset1:1
	s_waitcnt vmcnt(2)
	ds_write2_b32 v113, v96, v97 offset1:1
	ds_write2_b32 v56, v98, v99 offset0:2 offset1:3
	s_waitcnt vmcnt(1)
	ds_write2_b32 v114, v100, v101 offset1:1
	ds_write2_b32 v115, v102, v103 offset1:1
	s_waitcnt vmcnt(0)
	ds_write2_b32 v116, v104, v105 offset1:1
	ds_write2_b32 v117, v106, v107 offset1:1
	s_waitcnt lgkmcnt(0)
	ds_read2_b32 v[212:213], v74 offset1:33
	ds_read2_b32 v[214:215], v74 offset0:66 offset1:99
	ds_read2_b32 v[216:217], v74 offset0:132 offset1:165
	ds_read2_b32 v[218:219], v74 offset0:198 offset1:231
	ds_read2_b32 v[220:221], v74 offset0:8 offset1:41
	ds_read2_b32 v[222:223], v74 offset0:74 offset1:107
	ds_read2_b32 v[224:225], v74 offset0:140 offset1:173
	ds_read2_b32 v[226:227], v74 offset0:206 offset1:239
	ds_read2_b32 v[228:229], v74 offset0:16 offset1:49
	ds_read2_b32 v[230:231], v74 offset0:82 offset1:115
	ds_read2_b32 v[232:233], v74 offset0:148 offset1:181
	ds_read2_b32 v[234:235], v74 offset0:214 offset1:247
	ds_read2_b32 v[236:237], v74 offset0:24 offset1:57
	ds_read2_b32 v[238:239], v74 offset0:90 offset1:123
	ds_read2_b32 v[240:241], v74 offset0:156 offset1:189
	ds_read2_b32 v[242:243], v74 offset0:222 offset1:255
	s_waitcnt lgkmcnt(0)
	v_cvt_pk_bf16_f32 v76, v212, v213
	s_waitcnt lgkmcnt(0)
	v_cvt_pk_bf16_f32 v77, v214, v215
	v_or_b32_e32 v2, s37, v1
	s_waitcnt lgkmcnt(0)
	v_cvt_pk_bf16_f32 v78, v216, v217
	v_lshlrev_b32_e32 v2, 7, v2
	s_waitcnt lgkmcnt(0)
	v_cvt_pk_bf16_f32 v79, v218, v219
	v_lshl_add_u64 v[80:81], v[54:55], 0, v[2:3]
	global_store_dwordx4 v[80:81], v[76:79], off
	v_or_b32_e32 v2, s37, v62
	v_lshlrev_b32_e32 v2, 7, v2
	s_waitcnt lgkmcnt(0)
	v_cvt_pk_bf16_f32 v76, v220, v221
	s_waitcnt lgkmcnt(0)
	v_cvt_pk_bf16_f32 v77, v222, v223
	s_waitcnt lgkmcnt(0)
	v_cvt_pk_bf16_f32 v78, v224, v225
	s_waitcnt lgkmcnt(0)
	v_cvt_pk_bf16_f32 v79, v226, v227
	v_lshl_add_u64 v[80:81], v[54:55], 0, v[2:3]
	global_store_dwordx4 v[80:81], v[76:79], off
	v_or_b32_e32 v2, s37, v64
	v_lshlrev_b32_e32 v2, 7, v2
	s_waitcnt lgkmcnt(0)
	v_cvt_pk_bf16_f32 v76, v228, v229
	s_waitcnt lgkmcnt(0)
	v_cvt_pk_bf16_f32 v77, v230, v231
	s_waitcnt lgkmcnt(0)
	v_cvt_pk_bf16_f32 v78, v232, v233
	s_waitcnt lgkmcnt(0)
	v_cvt_pk_bf16_f32 v79, v234, v235
	v_lshl_add_u64 v[80:81], v[54:55], 0, v[2:3]
	global_store_dwordx4 v[80:81], v[76:79], off
	v_or_b32_e32 v2, s37, v66
	v_lshlrev_b32_e32 v2, 7, v2
	s_waitcnt lgkmcnt(0)
	v_cvt_pk_bf16_f32 v76, v236, v237
	s_waitcnt lgkmcnt(0)
	v_cvt_pk_bf16_f32 v77, v238, v239
	s_waitcnt lgkmcnt(0)
	v_cvt_pk_bf16_f32 v78, v240, v241
	s_waitcnt lgkmcnt(0)
	v_cvt_pk_bf16_f32 v79, v242, v243
	v_lshl_add_u64 v[56:57], v[54:55], 0, v[2:3]
	global_store_dwordx4 v[56:57], v[76:79], off
	s_waitcnt lgkmcnt(0)

.LBB0_1884:
	s_andn2_b64 vcc, exec, s[4:5]
	s_cbranch_vccnz .LBB0_1887
	s_cmpk_eq_i32 s8, 0x15a4
	s_cbranch_scc0 .LBB0_1887
	s_load_dwordx2 s[4:5], s[10:11], 0x80
	s_lshl_b32 s37, s1, 5
	s_addk_i32 s37, 0x4b80
	s_and_b32 s37, s37, 0xffe0
	s_lshl_b32 s48, s37, 2
	s_waitcnt lgkmcnt(0)
	s_add_u32 s4, s4, s48
	s_addc_u32 s5, s5, 0
	v_lshlrev_b32_e32 v2, 2, v0
	v_lshl_add_u64 v[56:57], s[4:5], 0, v[2:3]
	v_lshl_add_u64 v[56:57], v[56:57], 0, s[44:45]
	v_lshl_add_u64 v[76:77], v[56:57], 0, v[38:39]
	global_load_dwordx4 v[76:79], v[76:77], off
	v_lshl_add_u64 v[80:81], v[56:57], 0, v[40:41]
	global_load_dwordx4 v[80:83], v[80:81], off
	v_lshl_add_u64 v[84:85], v[56:57], 0, v[42:43]
	global_load_dwordx4 v[84:87], v[84:85], off
	v_lshl_add_u64 v[88:89], v[56:57], 0, v[44:45]
	global_load_dwordx4 v[88:91], v[88:89], off
	v_lshl_add_u64 v[92:93], v[56:57], 0, v[46:47]
	global_load_dwordx4 v[92:95], v[92:93], off
	v_lshl_add_u64 v[96:97], v[56:57], 0, v[48:49]
	global_load_dwordx4 v[96:99], v[96:97], off
	v_lshl_add_u64 v[100:101], v[56:57], 0, v[50:51]
	global_load_dwordx4 v[100:103], v[100:101], off
	v_lshl_add_u64 v[56:57], v[56:57], 0, v[52:53]
	global_load_dwordx4 v[104:107], v[56:57], off
	v_add_u32_e32 v2, v59, v61
	v_add_u32_e32 v56, v59, v71
	v_add_u32_e32 v57, 0x420, v2
	v_add_u32_e32 v58, 0x428, v2
	v_add_u32_e32 v60, 0x840, v2
	v_add_u32_e32 v108, 0x848, v2
	v_add_u32_e32 v109, 0xc60, v2
	v_add_u32_e32 v110, 0xc68, v2
	v_add_u32_e32 v111, 0x1080, v2
	v_add_u32_e32 v112, 0x1088, v2
	v_add_u32_e32 v113, 0x14a0, v2
	v_add_u32_e32 v114, 0x420, v56
	v_add_u32_e32 v115, 0x428, v56
	v_add_u32_e32 v116, 0x840, v56
	v_add_u32_e32 v117, 0x848, v56
	s_addk_i32 s37, 0x80
	s_waitcnt vmcnt(7)
	ds_write2_b32 v2, v76, v77 offset1:1
	ds_write2_b32 v2, v78, v79 offset0:2 offset1:3
	s_waitcnt vmcnt(6)
	ds_write2_b32 v57, v80, v81 offset1:1
	ds_write2_b32 v58, v82, v83 offset1:1
	s_waitcnt vmcnt(5)
	ds_write2_b32 v60, v84, v85 offset1:1
	ds_write2_b32 v108, v86, v87 offset1:1
	s_waitcnt vmcnt(4)
	ds_write2_b32 v109, v88, v89 offset1:1
	ds_write2_b32 v110, v90, v91 offset1:1
	s_waitcnt vmcnt(3)
	ds_write2_b32 v111, v92, v93 offset1:1
	ds_write2_b32 v112, v94, v95 offset1:1
	s_waitcnt vmcnt(2)
	ds_write2_b32 v113, v96, v97 offset1:1
	ds_write2_b32 v56, v98, v99 offset0:2 offset1:3
	s_waitcnt vmcnt(1)
	ds_write2_b32 v114, v100, v101 offset1:1
	ds_write2_b32 v115, v102, v103 offset1:1
	s_waitcnt vmcnt(0)
	ds_write2_b32 v116, v104, v105 offset1:1
	ds_write2_b32 v117, v106, v107 offset1:1
	s_waitcnt lgkmcnt(0)
	ds_read2_b32 v[212:213], v74 offset1:33
	ds_read2_b32 v[214:215], v74 offset0:66 offset1:99
	ds_read2_b32 v[216:217], v74 offset0:132 offset1:165
	ds_read2_b32 v[218:219], v74 offset0:198 offset1:231
	ds_read2_b32 v[220:221], v74 offset0:8 offset1:41
	ds_read2_b32 v[222:223], v74 offset0:74 offset1:107
	ds_read2_b32 v[224:225], v74 offset0:140 offset1:173
	ds_read2_b32 v[226:227], v74 offset0:206 offset1:239
	ds_read2_b32 v[228:229], v74 offset0:16 offset1:49
	ds_read2_b32 v[230:231], v74 offset0:82 offset1:115
	ds_read2_b32 v[232:233], v74 offset0:148 offset1:181
	ds_read2_b32 v[234:235], v74 offset0:214 offset1:247
	ds_read2_b32 v[236:237], v74 offset0:24 offset1:57
	ds_read2_b32 v[238:239], v74 offset0:90 offset1:123
	ds_read2_b32 v[240:241], v74 offset0:156 offset1:189
	ds_read2_b32 v[242:243], v74 offset0:222 offset1:255
	s_waitcnt lgkmcnt(0)
	v_cvt_pk_bf16_f32 v76, v212, v213
	s_waitcnt lgkmcnt(0)
	v_cvt_pk_bf16_f32 v77, v214, v215
	v_or_b32_e32 v2, s37, v1
	s_waitcnt lgkmcnt(0)
	v_cvt_pk_bf16_f32 v78, v216, v217
	v_lshlrev_b32_e32 v2, 7, v2
	s_waitcnt lgkmcnt(0)
	v_cvt_pk_bf16_f32 v79, v218, v219
	v_lshl_add_u64 v[80:81], v[54:55], 0, v[2:3]
	global_store_dwordx4 v[80:81], v[76:79], off
	v_or_b32_e32 v2, s37, v62
	v_lshlrev_b32_e32 v2, 7, v2
	s_waitcnt lgkmcnt(0)
	v_cvt_pk_bf16_f32 v76, v220, v221
	s_waitcnt lgkmcnt(0)
	v_cvt_pk_bf16_f32 v77, v222, v223
	s_waitcnt lgkmcnt(0)
	v_cvt_pk_bf16_f32 v78, v224, v225
	s_waitcnt lgkmcnt(0)
	v_cvt_pk_bf16_f32 v79, v226, v227
	v_lshl_add_u64 v[80:81], v[54:55], 0, v[2:3]
	global_store_dwordx4 v[80:81], v[76:79], off
	v_or_b32_e32 v2, s37, v64
	v_lshlrev_b32_e32 v2, 7, v2
	s_waitcnt lgkmcnt(0)
	v_cvt_pk_bf16_f32 v76, v228, v229
	s_waitcnt lgkmcnt(0)
	v_cvt_pk_bf16_f32 v77, v230, v231
	s_waitcnt lgkmcnt(0)
	v_cvt_pk_bf16_f32 v78, v232, v233
	s_waitcnt lgkmcnt(0)
	v_cvt_pk_bf16_f32 v79, v234, v235
	v_lshl_add_u64 v[80:81], v[54:55], 0, v[2:3]
	global_store_dwordx4 v[80:81], v[76:79], off
	v_or_b32_e32 v2, s37, v66
	v_lshlrev_b32_e32 v2, 7, v2
	s_waitcnt lgkmcnt(0)
	v_cvt_pk_bf16_f32 v76, v236, v237
	s_waitcnt lgkmcnt(0)
	v_cvt_pk_bf16_f32 v77, v238, v239
	s_waitcnt lgkmcnt(0)
	v_cvt_pk_bf16_f32 v78, v240, v241
	s_waitcnt lgkmcnt(0)
	v_cvt_pk_bf16_f32 v79, v242, v243
	v_lshl_add_u64 v[56:57], v[54:55], 0, v[2:3]
	global_store_dwordx4 v[56:57], v[76:79], off
	s_waitcnt lgkmcnt(0)

.LBB0_1888:
	s_cmpk_lt_i32 s8, 0x15a2
	s_mov_b64 s[4:5], -1
	s_cbranch_scc1 .LBB0_1892
	s_cmpk_eq_i32 s8, 0x15a2
	s_cbranch_scc0 .LBB0_1891
	s_load_dwordx2 s[4:5], s[10:11], 0x80
	s_lshl_b32 s37, s1, 5
	s_addk_i32 s37, 0x4bc0
	s_and_b32 s37, s37, 0xffe0
	s_lshl_b32 s48, s37, 2
	s_waitcnt lgkmcnt(0)
	s_add_u32 s4, s4, s48
	s_addc_u32 s5, s5, 0
	v_lshlrev_b32_e32 v2, 2, v0
	v_lshl_add_u64 v[56:57], s[4:5], 0, v[2:3]
	v_lshl_add_u64 v[56:57], v[56:57], 0, s[46:47]
	v_lshl_add_u64 v[76:77], v[56:57], 0, v[38:39]
	global_load_dwordx4 v[76:79], v[76:77], off
	v_lshl_add_u64 v[80:81], v[56:57], 0, v[40:41]
	global_load_dwordx4 v[80:83], v[80:81], off
	v_lshl_add_u64 v[84:85], v[56:57], 0, v[42:43]
	global_load_dwordx4 v[84:87], v[84:85], off
	v_lshl_add_u64 v[88:89], v[56:57], 0, v[44:45]
	global_load_dwordx4 v[88:91], v[88:89], off
	v_lshl_add_u64 v[92:93], v[56:57], 0, v[46:47]
	global_load_dwordx4 v[92:95], v[92:93], off
	v_lshl_add_u64 v[96:97], v[56:57], 0, v[48:49]
	global_load_dwordx4 v[96:99], v[96:97], off
	v_lshl_add_u64 v[100:101], v[56:57], 0, v[50:51]
	global_load_dwordx4 v[100:103], v[100:101], off
	v_lshl_add_u64 v[56:57], v[56:57], 0, v[52:53]
	global_load_dwordx4 v[104:107], v[56:57], off
	v_add_u32_e32 v2, v59, v61
	v_add_u32_e32 v56, v59, v71
	v_add_u32_e32 v57, 0x420, v2
	v_add_u32_e32 v58, 0x428, v2
	v_add_u32_e32 v60, 0x840, v2
	v_add_u32_e32 v108, 0x848, v2
	v_add_u32_e32 v109, 0xc60, v2
	v_add_u32_e32 v110, 0xc68, v2
	v_add_u32_e32 v111, 0x1080, v2
	v_add_u32_e32 v112, 0x1088, v2
	v_add_u32_e32 v113, 0x14a0, v2
	v_add_u32_e32 v114, 0x420, v56
	v_add_u32_e32 v115, 0x428, v56
	v_add_u32_e32 v116, 0x840, v56
	v_add_u32_e32 v117, 0x848, v56
	s_add_i32 s37, s37, 64
	s_waitcnt vmcnt(7)
	ds_write2_b32 v2, v76, v77 offset1:1
	ds_write2_b32 v2, v78, v79 offset0:2 offset1:3
	s_waitcnt vmcnt(6)
	ds_write2_b32 v57, v80, v81 offset1:1
	ds_write2_b32 v58, v82, v83 offset1:1
	s_waitcnt vmcnt(5)
	ds_write2_b32 v60, v84, v85 offset1:1
	ds_write2_b32 v108, v86, v87 offset1:1
	s_waitcnt vmcnt(4)
	ds_write2_b32 v109, v88, v89 offset1:1
	ds_write2_b32 v110, v90, v91 offset1:1
	s_waitcnt vmcnt(3)
	ds_write2_b32 v111, v92, v93 offset1:1
	ds_write2_b32 v112, v94, v95 offset1:1
	s_waitcnt vmcnt(2)
	ds_write2_b32 v113, v96, v97 offset1:1
	ds_write2_b32 v56, v98, v99 offset0:2 offset1:3
	s_waitcnt vmcnt(1)
	ds_write2_b32 v114, v100, v101 offset1:1
	ds_write2_b32 v115, v102, v103 offset1:1
	s_waitcnt vmcnt(0)
	ds_write2_b32 v116, v104, v105 offset1:1
	ds_write2_b32 v117, v106, v107 offset1:1
	s_waitcnt lgkmcnt(0)
	ds_read2_b32 v[212:213], v74 offset1:33
	ds_read2_b32 v[214:215], v74 offset0:66 offset1:99
	ds_read2_b32 v[216:217], v74 offset0:132 offset1:165
	ds_read2_b32 v[218:219], v74 offset0:198 offset1:231
	ds_read2_b32 v[220:221], v74 offset0:8 offset1:41
	ds_read2_b32 v[222:223], v74 offset0:74 offset1:107
	ds_read2_b32 v[224:225], v74 offset0:140 offset1:173
	ds_read2_b32 v[226:227], v74 offset0:206 offset1:239
	ds_read2_b32 v[228:229], v74 offset0:16 offset1:49
	ds_read2_b32 v[230:231], v74 offset0:82 offset1:115
	ds_read2_b32 v[232:233], v74 offset0:148 offset1:181
	ds_read2_b32 v[234:235], v74 offset0:214 offset1:247
	ds_read2_b32 v[236:237], v74 offset0:24 offset1:57
	ds_read2_b32 v[238:239], v74 offset0:90 offset1:123
	ds_read2_b32 v[240:241], v74 offset0:156 offset1:189
	ds_read2_b32 v[242:243], v74 offset0:222 offset1:255
	s_waitcnt lgkmcnt(0)
	v_cvt_pk_bf16_f32 v76, v212, v213
	s_waitcnt lgkmcnt(0)
	v_cvt_pk_bf16_f32 v77, v214, v215
	v_or_b32_e32 v2, s37, v1
	s_waitcnt lgkmcnt(0)
	v_cvt_pk_bf16_f32 v78, v216, v217
	v_lshlrev_b32_e32 v2, 7, v2
	s_waitcnt lgkmcnt(0)
	v_cvt_pk_bf16_f32 v79, v218, v219
	v_lshl_add_u64 v[80:81], v[54:55], 0, v[2:3]
	global_store_dwordx4 v[80:81], v[76:79], off
	v_or_b32_e32 v2, s37, v62
	v_lshlrev_b32_e32 v2, 7, v2
	s_waitcnt lgkmcnt(0)
	v_cvt_pk_bf16_f32 v76, v220, v221
	s_waitcnt lgkmcnt(0)
	v_cvt_pk_bf16_f32 v77, v222, v223
	s_waitcnt lgkmcnt(0)
	v_cvt_pk_bf16_f32 v78, v224, v225
	s_waitcnt lgkmcnt(0)
	v_cvt_pk_bf16_f32 v79, v226, v227
	v_lshl_add_u64 v[80:81], v[54:55], 0, v[2:3]
	global_store_dwordx4 v[80:81], v[76:79], off
	v_or_b32_e32 v2, s37, v64
	v_lshlrev_b32_e32 v2, 7, v2
	s_waitcnt lgkmcnt(0)
	v_cvt_pk_bf16_f32 v76, v228, v229
	s_waitcnt lgkmcnt(0)
	v_cvt_pk_bf16_f32 v77, v230, v231
	s_waitcnt lgkmcnt(0)
	v_cvt_pk_bf16_f32 v78, v232, v233
	s_waitcnt lgkmcnt(0)
	v_cvt_pk_bf16_f32 v79, v234, v235
	v_lshl_add_u64 v[80:81], v[54:55], 0, v[2:3]
	global_store_dwordx4 v[80:81], v[76:79], off
	v_or_b32_e32 v2, s37, v66
	v_lshlrev_b32_e32 v2, 7, v2
	s_waitcnt lgkmcnt(0)
	v_cvt_pk_bf16_f32 v76, v236, v237
	s_waitcnt lgkmcnt(0)
	v_cvt_pk_bf16_f32 v77, v238, v239
	s_waitcnt lgkmcnt(0)
	v_cvt_pk_bf16_f32 v78, v240, v241
	s_waitcnt lgkmcnt(0)
	v_cvt_pk_bf16_f32 v79, v242, v243
	v_lshl_add_u64 v[56:57], v[54:55], 0, v[2:3]
	global_store_dwordx4 v[56:57], v[76:79], off
	s_waitcnt lgkmcnt(0)

.LBB0_1892:
	s_andn2_b64 vcc, exec, s[4:5]
	s_cbranch_vccnz .LBB0_1698
	s_cmpk_lg_i32 s8, 0x15a0
	s_cbranch_scc1 .LBB0_1698
	s_load_dwordx2 s[4:5], s[10:11], 0x80
	s_lshl_b32 s8, s1, 5
	s_addk_i32 s8, 0x4c00
	s_and_b32 s8, s8, 0xffe0
	s_lshl_b32 s37, s8, 2
	s_waitcnt lgkmcnt(0)
	s_add_u32 s4, s4, s37
	s_addc_u32 s5, s5, 0
	v_lshlrev_b32_e32 v2, 2, v0
	v_lshl_add_u64 v[56:57], s[4:5], 0, v[2:3]
	v_lshl_add_u64 v[56:57], v[56:57], 0, s[30:31]
	v_lshl_add_u64 v[76:77], v[56:57], 0, v[38:39]
	global_load_dwordx4 v[76:79], v[76:77], off
	v_lshl_add_u64 v[80:81], v[56:57], 0, v[40:41]
	global_load_dwordx4 v[80:83], v[80:81], off
	v_lshl_add_u64 v[84:85], v[56:57], 0, v[42:43]
	global_load_dwordx4 v[84:87], v[84:85], off
	v_lshl_add_u64 v[88:89], v[56:57], 0, v[44:45]
	global_load_dwordx4 v[88:91], v[88:89], off
	v_lshl_add_u64 v[92:93], v[56:57], 0, v[46:47]
	global_load_dwordx4 v[92:95], v[92:93], off
	v_lshl_add_u64 v[96:97], v[56:57], 0, v[48:49]
	global_load_dwordx4 v[96:99], v[96:97], off
	v_lshl_add_u64 v[100:101], v[56:57], 0, v[50:51]
	global_load_dwordx4 v[100:103], v[100:101], off
	v_lshl_add_u64 v[56:57], v[56:57], 0, v[52:53]
	global_load_dwordx4 v[104:107], v[56:57], off
	v_add_u32_e32 v2, v59, v61
	v_add_u32_e32 v56, v59, v71
	v_add_u32_e32 v57, 0x420, v2
	v_add_u32_e32 v58, 0x428, v2
	v_add_u32_e32 v60, 0x840, v2
	v_add_u32_e32 v108, 0x848, v2
	v_add_u32_e32 v109, 0xc60, v2
	v_add_u32_e32 v110, 0xc68, v2
	v_add_u32_e32 v111, 0x1080, v2
	v_add_u32_e32 v112, 0x1088, v2
	v_add_u32_e32 v113, 0x14a0, v2
	v_add_u32_e32 v114, 0x420, v56
	v_add_u32_e32 v115, 0x428, v56
	v_add_u32_e32 v116, 0x840, v56
	v_add_u32_e32 v117, 0x848, v56
	s_waitcnt vmcnt(7)
	ds_write2_b32 v2, v76, v77 offset1:1
	ds_write2_b32 v2, v78, v79 offset0:2 offset1:3
	s_waitcnt vmcnt(6)
	ds_write2_b32 v57, v80, v81 offset1:1
	ds_write2_b32 v58, v82, v83 offset1:1
	s_waitcnt vmcnt(5)
	ds_write2_b32 v60, v84, v85 offset1:1
	ds_write2_b32 v108, v86, v87 offset1:1
	s_waitcnt vmcnt(4)
	ds_write2_b32 v109, v88, v89 offset1:1
	ds_write2_b32 v110, v90, v91 offset1:1
	s_waitcnt vmcnt(3)
	ds_write2_b32 v111, v92, v93 offset1:1
	ds_write2_b32 v112, v94, v95 offset1:1
	s_waitcnt vmcnt(2)
	ds_write2_b32 v113, v96, v97 offset1:1
	ds_write2_b32 v56, v98, v99 offset0:2 offset1:3
	s_waitcnt vmcnt(1)
	ds_write2_b32 v114, v100, v101 offset1:1
	ds_write2_b32 v115, v102, v103 offset1:1
	s_waitcnt vmcnt(0)
	ds_write2_b32 v116, v104, v105 offset1:1
	ds_write2_b32 v117, v106, v107 offset1:1
	s_waitcnt lgkmcnt(0)
	ds_read2_b32 v[212:213], v74 offset1:33
	ds_read2_b32 v[214:215], v74 offset0:66 offset1:99
	ds_read2_b32 v[216:217], v74 offset0:132 offset1:165
	ds_read2_b32 v[218:219], v74 offset0:198 offset1:231
	ds_read2_b32 v[220:221], v74 offset0:8 offset1:41
	ds_read2_b32 v[222:223], v74 offset0:74 offset1:107
	ds_read2_b32 v[224:225], v74 offset0:140 offset1:173
	ds_read2_b32 v[226:227], v74 offset0:206 offset1:239
	ds_read2_b32 v[228:229], v74 offset0:16 offset1:49
	ds_read2_b32 v[230:231], v74 offset0:82 offset1:115
	ds_read2_b32 v[232:233], v74 offset0:148 offset1:181
	ds_read2_b32 v[234:235], v74 offset0:214 offset1:247
	ds_read2_b32 v[236:237], v74 offset0:24 offset1:57
	ds_read2_b32 v[238:239], v74 offset0:90 offset1:123
	ds_read2_b32 v[240:241], v74 offset0:156 offset1:189
	ds_read2_b32 v[242:243], v74 offset0:222 offset1:255
	s_waitcnt lgkmcnt(0)
	v_cvt_pk_bf16_f32 v76, v212, v213
	s_waitcnt lgkmcnt(0)
	v_cvt_pk_bf16_f32 v77, v214, v215
	v_or_b32_e32 v2, s8, v1
	s_waitcnt lgkmcnt(0)
	v_cvt_pk_bf16_f32 v78, v216, v217
	v_lshlrev_b32_e32 v2, 7, v2
	s_waitcnt lgkmcnt(0)
	v_cvt_pk_bf16_f32 v79, v218, v219
	v_lshl_add_u64 v[80:81], v[54:55], 0, v[2:3]
	global_store_dwordx4 v[80:81], v[76:79], off
	v_or_b32_e32 v2, s8, v62
	v_lshlrev_b32_e32 v2, 7, v2
	s_waitcnt lgkmcnt(0)
	v_cvt_pk_bf16_f32 v76, v220, v221
	s_waitcnt lgkmcnt(0)
	v_cvt_pk_bf16_f32 v77, v222, v223
	s_waitcnt lgkmcnt(0)
	v_cvt_pk_bf16_f32 v78, v224, v225
	s_waitcnt lgkmcnt(0)
	v_cvt_pk_bf16_f32 v79, v226, v227
	v_lshl_add_u64 v[80:81], v[54:55], 0, v[2:3]
	global_store_dwordx4 v[80:81], v[76:79], off
	v_or_b32_e32 v2, s8, v64
	v_lshlrev_b32_e32 v2, 7, v2
	s_waitcnt lgkmcnt(0)
	v_cvt_pk_bf16_f32 v76, v228, v229
	s_waitcnt lgkmcnt(0)
	v_cvt_pk_bf16_f32 v77, v230, v231
	s_waitcnt lgkmcnt(0)
	v_cvt_pk_bf16_f32 v78, v232, v233
	s_waitcnt lgkmcnt(0)
	v_cvt_pk_bf16_f32 v79, v234, v235
	v_lshl_add_u64 v[80:81], v[54:55], 0, v[2:3]
	global_store_dwordx4 v[80:81], v[76:79], off
	v_or_b32_e32 v2, s8, v66
	v_lshlrev_b32_e32 v2, 7, v2
	s_waitcnt lgkmcnt(0)
	v_cvt_pk_bf16_f32 v76, v236, v237
	s_waitcnt lgkmcnt(0)
	v_cvt_pk_bf16_f32 v77, v238, v239
	s_waitcnt lgkmcnt(0)
	v_cvt_pk_bf16_f32 v78, v240, v241
	s_waitcnt lgkmcnt(0)
	v_cvt_pk_bf16_f32 v79, v242, v243
	v_lshl_add_u64 v[56:57], v[54:55], 0, v[2:3]
	global_store_dwordx4 v[56:57], v[76:79], off
	s_waitcnt lgkmcnt(0)
	s_branch .LBB0_1698

.LBB0_2595:
	v_mad_u64_u32 v[16:17], s[36:37], v18, s31, v[16:17]
	v_add_u32_e32 v18, 0x14a0, v33
	s_and_b32 s7, 0xffff, s7
	v_add_u32_e32 v33, 0x14a8, v33
	s_lshl_b32 s10, s6, 1
	s_lshr_b32 s36, s7, 4
	v_lshl_add_u64 v[42:43], v[2:3], 0, s[10:11]
	s_lshr_b32 s6, s7, 6
	s_lshl_b32 s10, s7, 2
	s_and_b32 s7, s7, 0x60
	s_and_b32 s36, s36, 0x80
	s_and_b32 s6, s6, 16
	s_or_b32 s37, s36, s7
	s_and_b32 s10, s10, 0xe00
	s_or_b32 s37, s37, s6
	s_or_b32 s37, s37, s10
	v_mov_b32_e32 v41, v1
	v_mov_b32_e32 v45, v1
	s_waitcnt vmcnt(0)
	v_pk_mul_f32 v[34:35], v[236:237], v[20:21] op_sel_hi:[1,0]
	v_pk_mul_f32 v[16:17], v[238:239], v[20:21] op_sel_hi:[1,0]
	ds_write2_b32 v18, v34, v35 offset1:1
	ds_write2_b32 v33, v16, v17 offset1:1
	s_waitcnt lgkmcnt(0)
	ds_read2_b32 v[212:213], v29 offset1:33
	ds_read2_b32 v[214:215], v29 offset0:66 offset1:99
	ds_read2_b32 v[216:217], v29 offset0:132 offset1:165
	ds_read2_b32 v[218:219], v29 offset0:198 offset1:231
	ds_read2_b32 v[220:221], v29 offset0:8 offset1:41
	ds_read2_b32 v[222:223], v29 offset0:74 offset1:107
	ds_read2_b32 v[224:225], v29 offset0:140 offset1:173
	ds_read2_b32 v[226:227], v29 offset0:206 offset1:239
	ds_read2_b32 v[228:229], v29 offset0:16 offset1:49
	ds_read2_b32 v[230:231], v29 offset0:82 offset1:115
	ds_read2_b32 v[232:233], v29 offset0:148 offset1:181
	ds_read2_b32 v[234:235], v29 offset0:214 offset1:247
	ds_read2_b32 v[236:237], v29 offset0:24 offset1:57
	ds_read2_b32 v[238:239], v29 offset0:90 offset1:123
	ds_read2_b32 v[240:241], v29 offset0:156 offset1:189
	ds_read2_b32 v[242:243], v29 offset0:222 offset1:255
	s_waitcnt lgkmcnt(0)
	v_cvt_pk_bf16_f32 v34, v212, v213
	s_waitcnt lgkmcnt(0)
	v_cvt_pk_bf16_f32 v35, v214, v215
	v_or_b32_e32 v18, s37, v9
	s_waitcnt lgkmcnt(0)
	v_cvt_pk_bf16_f32 v36, v216, v217
	v_lshlrev_b32_e32 v40, 11, v18
	s_waitcnt lgkmcnt(0)
	v_cvt_pk_bf16_f32 v37, v218, v219
	v_lshl_add_u64 v[40:41], v[42:43], 0, v[40:41]
	global_store_dwordx4 v[40:41], v[34:37], off
	v_or_b32_e32 v18, s37, v21
	v_lshlrev_b32_e32 v44, 11, v18
	s_waitcnt lgkmcnt(0)
	v_cvt_pk_bf16_f32 v34, v220, v221
	s_waitcnt lgkmcnt(0)
	v_cvt_pk_bf16_f32 v35, v222, v223
	s_waitcnt lgkmcnt(0)
	v_cvt_pk_bf16_f32 v36, v224, v225
	v_or_b32_e32 v18, s7, v30
	s_waitcnt lgkmcnt(0)
	v_cvt_pk_bf16_f32 v37, v226, v227
	v_lshl_add_u64 v[44:45], v[42:43], 0, v[44:45]
	v_or_b32_e32 v18, s36, v18
	global_store_dwordx4 v[44:45], v[34:37], off
	v_add_co_u32_e32 v40, vcc, s33, v40
	s_waitcnt lgkmcnt(0)
	v_cvt_pk_bf16_f32 v34, v228, v229
	v_or_b32_e32 v18, s6, v18
	s_waitcnt lgkmcnt(0)
	v_cvt_pk_bf16_f32 v35, v230, v231
	v_addc_co_u32_e32 v41, vcc, 0, v41, vcc
	v_or_b32_e32 v18, s10, v18
	s_waitcnt lgkmcnt(0)
	v_cvt_pk_bf16_f32 v36, v232, v233
	s_waitcnt lgkmcnt(0)
	v_cvt_pk_bf16_f32 v37, v234, v235
	global_store_dwordx4 v[40:41], v[34:37], off
	v_mov_b32_e32 v41, v1
	v_lshlrev_b32_e32 v40, 11, v18
	v_lshl_add_u64 v[40:41], v[42:43], 0, v[40:41]
	s_waitcnt lgkmcnt(0)
	v_cvt_pk_bf16_f32 v34, v236, v237
	v_add_co_u32_e32 v40, vcc, 0x80000, v40
	s_waitcnt lgkmcnt(0)
	v_cvt_pk_bf16_f32 v35, v238, v239
	v_addc_co_u32_e32 v41, vcc, 0, v41, vcc
	s_waitcnt lgkmcnt(0)
	v_cvt_pk_bf16_f32 v36, v240, v241
	s_waitcnt lgkmcnt(0)
	v_cvt_pk_bf16_f32 v37, v242, v243
	global_store_dwordx4 v[40:41], v[34:37], off
	s_waitcnt lgkmcnt(0)
	s_and_b32 s36, s2, 0xfffffe00
	s_cmpk_lt_i32 s36, 0xa00
	s_mov_b64 s[6:7], -1
	s_cbranch_scc0 .LBB0_2598

.LBB0_2598:
	s_cmpk_eq_i32 s36, 0xa00
	s_cbranch_scc0 .LBB0_2600
	s_load_dwordx2 s[48:49], s[44:45], 0x118
	s_add_i32 s6, s26, 0xfffffc00
	s_and_b32 s7, s6, 0x1ffc0
	s_lshl_b32 s6, s2, 5
	v_or_b32_e32 v18, s7, v9
	s_and_b32 s6, s6, 0x3e0
	v_lshlrev_b32_e32 v34, 12, v18
	v_or_b32_e32 v18, s7, v21
	s_lshl_b32 s10, s6, 2
	v_lshlrev_b32_e32 v36, 12, v18
	v_or_b32_e32 v18, s7, v22
	s_waitcnt lgkmcnt(0)
	s_add_u32 s48, s48, s10
	v_lshlrev_b32_e32 v44, 12, v18
	v_or_b32_e32 v18, s7, v24
	s_addc_u32 s49, s49, 0
	v_lshlrev_b32_e32 v46, 12, v18
	v_or_b32_e32 v18, s7, v25
	v_lshl_add_u64 v[16:17], s[48:49], 0, v[0:1]
	v_lshlrev_b32_e32 v52, 12, v18
	v_or_b32_e32 v18, s7, v26
	v_lshl_add_u64 v[16:17], v[16:17], 0, s[18:19]
	v_mov_b32_e32 v35, v1
	v_mov_b32_e32 v37, v1
	v_mov_b32_e32 v45, v1
	v_mov_b32_e32 v47, v1
	v_mov_b32_e32 v53, v1
	v_lshlrev_b32_e32 v54, 12, v18
	v_mov_b32_e32 v55, v1
	v_lshl_add_u64 v[34:35], v[16:17], 0, v[34:35]
	v_lshl_add_u64 v[40:41], v[16:17], 0, v[36:37]
	v_lshl_add_u64 v[44:45], v[16:17], 0, v[44:45]
	v_lshl_add_u64 v[48:49], v[16:17], 0, v[46:47]
	v_lshl_add_u64 v[52:53], v[16:17], 0, v[52:53]
	v_lshl_add_u64 v[56:57], v[16:17], 0, v[54:55]
	global_load_dwordx4 v[34:37], v[34:35], off
	s_nop 0
	global_load_dwordx4 v[40:43], v[40:41], off
	s_nop 0
	global_load_dwordx4 v[44:47], v[44:45], off
	s_nop 0
	global_load_dwordx4 v[48:51], v[48:49], off
	s_nop 0
	global_load_dwordx4 v[52:55], v[52:53], off
	s_nop 0
	global_load_dwordx4 v[56:59], v[56:57], off
	v_or_b32_e32 v18, s7, v27
	v_lshlrev_b32_e32 v60, 12, v18
	v_mov_b32_e32 v61, v1
	v_lshl_add_u64 v[60:61], v[16:17], 0, v[60:61]
	v_or_b32_e32 v18, s7, v28
	global_load_dwordx4 v[60:63], v[60:61], off
	v_lshlrev_b32_e32 v68, 12, v18
	v_mov_b32_e32 v69, v1
	v_lshl_add_u64 v[16:17], v[16:17], 0, v[68:69]
	global_load_dwordx4 v[68:71], v[16:17], off
	v_add_u32_e32 v16, 0x420, v31
	v_add_u32_e32 v17, 0x428, v31
	v_add_u32_e32 v18, 0x840, v31
	v_add_u32_e32 v20, 0x848, v31
	v_add_u32_e32 v33, 0xc60, v31
	v_add_u32_e32 v65, 0xc68, v31
	v_add_u32_e32 v72, 0x1080, v31
	v_add_u32_e32 v73, 0x1088, v31
	v_add_u32_e32 v74, 0x14a0, v31
	v_add_u32_e32 v75, 0x14a8, v31
	v_add_u32_e32 v76, 0x18c0, v31
	v_add_u32_e32 v77, 0x18c8, v31
	v_add_u32_e32 v78, 0x1ce0, v31
	v_add_u32_e32 v79, 0x1ce8, v31
	s_lshl_b32 s10, s7, 1
	s_waitcnt vmcnt(7)
	ds_write2_b32 v31, v34, v35 offset1:1
	ds_write2_b32 v31, v36, v37 offset0:2 offset1:3
	s_waitcnt vmcnt(6)
	ds_write2_b32 v16, v40, v41 offset1:1
	ds_write2_b32 v17, v42, v43 offset1:1
	s_waitcnt vmcnt(5)
	ds_write2_b32 v18, v44, v45 offset1:1
	ds_write2_b32 v20, v46, v47 offset1:1
	s_waitcnt vmcnt(4)
	ds_write2_b32 v33, v48, v49 offset1:1
	ds_write2_b32 v65, v50, v51 offset1:1
	s_waitcnt vmcnt(3)
	ds_write2_b32 v72, v52, v53 offset1:1
	ds_write2_b32 v73, v54, v55 offset1:1
	s_waitcnt vmcnt(2)
	ds_write2_b32 v74, v56, v57 offset1:1
	ds_write2_b32 v75, v58, v59 offset1:1
	s_waitcnt vmcnt(1)
	ds_write2_b32 v76, v60, v61 offset1:1
	ds_write2_b32 v77, v62, v63 offset1:1
	s_waitcnt vmcnt(0)
	ds_write2_b32 v78, v68, v69 offset1:1
	ds_write2_b32 v79, v70, v71 offset1:1
	s_waitcnt lgkmcnt(0)
	ds_read2_b32 v[212:213], v29 offset1:33
	ds_read2_b32 v[214:215], v29 offset0:66 offset1:99
	ds_read2_b32 v[216:217], v29 offset0:132 offset1:165
	ds_read2_b32 v[218:219], v29 offset0:198 offset1:231
	ds_read2_b32 v[220:221], v29 offset0:8 offset1:41
	ds_read2_b32 v[222:223], v29 offset0:74 offset1:107
	ds_read2_b32 v[224:225], v29 offset0:140 offset1:173
	ds_read2_b32 v[226:227], v29 offset0:206 offset1:239
	ds_read2_b32 v[228:229], v29 offset0:16 offset1:49
	ds_read2_b32 v[230:231], v29 offset0:82 offset1:115
	ds_read2_b32 v[232:233], v29 offset0:148 offset1:181
	ds_read2_b32 v[234:235], v29 offset0:214 offset1:247
	ds_read2_b32 v[236:237], v29 offset0:24 offset1:57
	ds_read2_b32 v[238:239], v29 offset0:90 offset1:123
	ds_read2_b32 v[240:241], v29 offset0:156 offset1:189
	ds_read2_b32 v[242:243], v29 offset0:222 offset1:255
	s_waitcnt lgkmcnt(0)
	v_cvt_pk_bf16_f32 v34, v212, v213
	s_waitcnt lgkmcnt(0)
	v_cvt_pk_bf16_f32 v35, v214, v215
	v_or_b32_e32 v18, s6, v9
	s_waitcnt lgkmcnt(0)
	v_cvt_pk_bf16_f32 v36, v216, v217
	v_mov_b32_e32 v41, v1
	v_lshlrev_b32_e32 v40, 11, v18
	v_lshl_add_u64 v[42:43], v[4:5], 0, s[10:11]
	s_waitcnt lgkmcnt(0)
	v_cvt_pk_bf16_f32 v37, v218, v219
	v_lshl_add_u64 v[40:41], v[42:43], 0, v[40:41]
	global_store_dwordx4 v[40:41], v[34:37], off
	v_or_b32_e32 v18, s6, v21
	v_mov_b32_e32 v41, v1
	s_waitcnt lgkmcnt(0)
	v_cvt_pk_bf16_f32 v34, v220, v221
	s_waitcnt lgkmcnt(0)
	v_cvt_pk_bf16_f32 v35, v222, v223
	s_waitcnt lgkmcnt(0)
	v_cvt_pk_bf16_f32 v36, v224, v225
	v_lshlrev_b32_e32 v40, 11, v18
	s_waitcnt lgkmcnt(0)
	v_cvt_pk_bf16_f32 v37, v226, v227
	v_lshl_add_u64 v[40:41], v[42:43], 0, v[40:41]
	global_store_dwordx4 v[40:41], v[34:37], off
	v_or_b32_e32 v18, s6, v22
	v_mov_b32_e32 v41, v1
	s_waitcnt lgkmcnt(0)
	v_cvt_pk_bf16_f32 v34, v228, v229
	s_waitcnt lgkmcnt(0)
	v_cvt_pk_bf16_f32 v35, v230, v231
	s_waitcnt lgkmcnt(0)
	v_cvt_pk_bf16_f32 v36, v232, v233
	v_lshlrev_b32_e32 v40, 11, v18
	s_waitcnt lgkmcnt(0)
	v_cvt_pk_bf16_f32 v37, v234, v235
	v_lshl_add_u64 v[40:41], v[42:43], 0, v[40:41]
	global_store_dwordx4 v[40:41], v[34:37], off
	v_or_b32_e32 v18, s6, v24
	v_mov_b32_e32 v41, v1
	s_waitcnt lgkmcnt(0)
	v_cvt_pk_bf16_f32 v34, v236, v237
	s_waitcnt lgkmcnt(0)
	v_cvt_pk_bf16_f32 v35, v238, v239
	s_waitcnt lgkmcnt(0)
	v_cvt_pk_bf16_f32 v36, v240, v241
	v_lshlrev_b32_e32 v40, 11, v18
	s_waitcnt lgkmcnt(0)
	v_cvt_pk_bf16_f32 v37, v242, v243
	v_lshl_add_u64 v[16:17], v[42:43], 0, v[40:41]
	global_store_dwordx4 v[16:17], v[34:37], off
	s_waitcnt lgkmcnt(0)

.LBB0_2601:
	s_cmpk_lg_i32 s36, 0x800
	s_cbranch_scc1 .LBB0_2603
	s_load_dwordx2 s[36:37], s[44:45], 0x110
	s_and_b32 s7, s26, 0x1ffc0
	s_lshl_b32 s6, s2, 5
	v_or_b32_e32 v18, s7, v9
	s_and_b32 s6, s6, 0x3e0
	v_lshlrev_b32_e32 v34, 12, v18
	v_or_b32_e32 v18, s7, v21
	s_lshl_b32 s10, s6, 2
	v_lshlrev_b32_e32 v36, 12, v18
	v_or_b32_e32 v18, s7, v22
	s_waitcnt lgkmcnt(0)
	s_add_u32 s36, s36, s10
	v_lshlrev_b32_e32 v44, 12, v18
	v_or_b32_e32 v18, s7, v24
	s_addc_u32 s37, s37, 0
	v_lshlrev_b32_e32 v46, 12, v18
	v_or_b32_e32 v18, s7, v25
	v_lshl_add_u64 v[16:17], s[36:37], 0, v[0:1]
	v_lshlrev_b32_e32 v52, 12, v18
	v_or_b32_e32 v18, s7, v26
	v_lshl_add_u64 v[16:17], v[16:17], 0, s[18:19]
	v_mov_b32_e32 v35, v1
	v_mov_b32_e32 v37, v1
	v_mov_b32_e32 v45, v1
	v_mov_b32_e32 v47, v1
	v_mov_b32_e32 v53, v1
	v_lshlrev_b32_e32 v54, 12, v18
	v_mov_b32_e32 v55, v1
	v_lshl_add_u64 v[34:35], v[16:17], 0, v[34:35]
	v_lshl_add_u64 v[40:41], v[16:17], 0, v[36:37]
	v_lshl_add_u64 v[44:45], v[16:17], 0, v[44:45]
	v_lshl_add_u64 v[48:49], v[16:17], 0, v[46:47]
	v_lshl_add_u64 v[52:53], v[16:17], 0, v[52:53]
	v_lshl_add_u64 v[56:57], v[16:17], 0, v[54:55]
	global_load_dwordx4 v[34:37], v[34:35], off
	s_nop 0
	global_load_dwordx4 v[40:43], v[40:41], off
	s_nop 0
	global_load_dwordx4 v[44:47], v[44:45], off
	s_nop 0
	global_load_dwordx4 v[48:51], v[48:49], off
	s_nop 0
	global_load_dwordx4 v[52:55], v[52:53], off
	s_nop 0
	global_load_dwordx4 v[56:59], v[56:57], off
	v_or_b32_e32 v18, s7, v27
	v_lshlrev_b32_e32 v60, 12, v18
	v_mov_b32_e32 v61, v1
	v_lshl_add_u64 v[60:61], v[16:17], 0, v[60:61]
	v_or_b32_e32 v18, s7, v28
	global_load_dwordx4 v[60:63], v[60:61], off
	v_lshlrev_b32_e32 v68, 12, v18
	v_mov_b32_e32 v69, v1
	v_lshl_add_u64 v[16:17], v[16:17], 0, v[68:69]
	global_load_dwordx4 v[68:71], v[16:17], off
	v_add_u32_e32 v16, 0x420, v31
	v_add_u32_e32 v17, 0x428, v31
	v_add_u32_e32 v18, 0x840, v31
	v_add_u32_e32 v20, 0x848, v31
	v_add_u32_e32 v33, 0xc60, v31
	v_add_u32_e32 v65, 0xc68, v31
	v_add_u32_e32 v72, 0x1080, v31
	v_add_u32_e32 v73, 0x1088, v31
	v_add_u32_e32 v74, 0x14a0, v31
	v_add_u32_e32 v75, 0x14a8, v31
	v_add_u32_e32 v76, 0x18c0, v31
	v_add_u32_e32 v77, 0x18c8, v31
	v_add_u32_e32 v78, 0x1ce0, v31
	v_add_u32_e32 v79, 0x1ce8, v31
	s_lshl_b32 s10, s7, 1
	s_waitcnt vmcnt(7)
	ds_write2_b32 v31, v34, v35 offset1:1
	ds_write2_b32 v31, v36, v37 offset0:2 offset1:3
	s_waitcnt vmcnt(6)
	ds_write2_b32 v16, v40, v41 offset1:1
	ds_write2_b32 v17, v42, v43 offset1:1
	s_waitcnt vmcnt(5)
	ds_write2_b32 v18, v44, v45 offset1:1
	ds_write2_b32 v20, v46, v47 offset1:1
	s_waitcnt vmcnt(4)
	ds_write2_b32 v33, v48, v49 offset1:1
	ds_write2_b32 v65, v50, v51 offset1:1
	s_waitcnt vmcnt(3)
	ds_write2_b32 v72, v52, v53 offset1:1
	ds_write2_b32 v73, v54, v55 offset1:1
	s_waitcnt vmcnt(2)
	ds_write2_b32 v74, v56, v57 offset1:1
	ds_write2_b32 v75, v58, v59 offset1:1
	s_waitcnt vmcnt(1)
	ds_write2_b32 v76, v60, v61 offset1:1
	ds_write2_b32 v77, v62, v63 offset1:1
	s_waitcnt vmcnt(0)
	ds_write2_b32 v78, v68, v69 offset1:1
	ds_write2_b32 v79, v70, v71 offset1:1
	s_waitcnt lgkmcnt(0)
	ds_read2_b32 v[212:213], v29 offset1:33
	ds_read2_b32 v[214:215], v29 offset0:66 offset1:99
	ds_read2_b32 v[216:217], v29 offset0:132 offset1:165
	ds_read2_b32 v[218:219], v29 offset0:198 offset1:231
	ds_read2_b32 v[220:221], v29 offset0:8 offset1:41
	ds_read2_b32 v[222:223], v29 offset0:74 offset1:107
	ds_read2_b32 v[224:225], v29 offset0:140 offset1:173
	ds_read2_b32 v[226:227], v29 offset0:206 offset1:239
	ds_read2_b32 v[228:229], v29 offset0:16 offset1:49
	ds_read2_b32 v[230:231], v29 offset0:82 offset1:115
	ds_read2_b32 v[232:233], v29 offset0:148 offset1:181
	ds_read2_b32 v[234:235], v29 offset0:214 offset1:247
	ds_read2_b32 v[236:237], v29 offset0:24 offset1:57
	ds_read2_b32 v[238:239], v29 offset0:90 offset1:123
	ds_read2_b32 v[240:241], v29 offset0:156 offset1:189
	ds_read2_b32 v[242:243], v29 offset0:222 offset1:255
	s_waitcnt lgkmcnt(0)
	v_cvt_pk_bf16_f32 v34, v212, v213
	s_waitcnt lgkmcnt(0)
	v_cvt_pk_bf16_f32 v35, v214, v215
	v_or_b32_e32 v18, s6, v9
	s_waitcnt lgkmcnt(0)
	v_cvt_pk_bf16_f32 v36, v216, v217
	v_mov_b32_e32 v41, v1
	v_lshlrev_b32_e32 v40, 11, v18
	v_lshl_add_u64 v[42:43], v[6:7], 0, s[10:11]
	s_waitcnt lgkmcnt(0)
	v_cvt_pk_bf16_f32 v37, v218, v219
	v_lshl_add_u64 v[40:41], v[42:43], 0, v[40:41]
	global_store_dwordx4 v[40:41], v[34:37], off
	v_or_b32_e32 v18, s6, v21
	v_mov_b32_e32 v41, v1
	s_waitcnt lgkmcnt(0)
	v_cvt_pk_bf16_f32 v34, v220, v221
	s_waitcnt lgkmcnt(0)
	v_cvt_pk_bf16_f32 v35, v222, v223
	s_waitcnt lgkmcnt(0)
	v_cvt_pk_bf16_f32 v36, v224, v225
	v_lshlrev_b32_e32 v40, 11, v18
	s_waitcnt lgkmcnt(0)
	v_cvt_pk_bf16_f32 v37, v226, v227
	v_lshl_add_u64 v[40:41], v[42:43], 0, v[40:41]
	global_store_dwordx4 v[40:41], v[34:37], off
	v_or_b32_e32 v18, s6, v22
	v_mov_b32_e32 v41, v1
	s_waitcnt lgkmcnt(0)
	v_cvt_pk_bf16_f32 v34, v228, v229
	s_waitcnt lgkmcnt(0)
	v_cvt_pk_bf16_f32 v35, v230, v231
	s_waitcnt lgkmcnt(0)
	v_cvt_pk_bf16_f32 v36, v232, v233
	v_lshlrev_b32_e32 v40, 11, v18
	s_waitcnt lgkmcnt(0)
	v_cvt_pk_bf16_f32 v37, v234, v235
	v_lshl_add_u64 v[40:41], v[42:43], 0, v[40:41]
	global_store_dwordx4 v[40:41], v[34:37], off
	v_or_b32_e32 v18, s6, v24
	v_mov_b32_e32 v41, v1
	s_waitcnt lgkmcnt(0)
	v_cvt_pk_bf16_f32 v34, v236, v237
	s_waitcnt lgkmcnt(0)
	v_cvt_pk_bf16_f32 v35, v238, v239
	s_waitcnt lgkmcnt(0)
	v_cvt_pk_bf16_f32 v36, v240, v241
	v_lshlrev_b32_e32 v40, 11, v18
	s_waitcnt lgkmcnt(0)
	v_cvt_pk_bf16_f32 v37, v242, v243
	v_lshl_add_u64 v[16:17], v[42:43], 0, v[40:41]
	global_store_dwordx4 v[16:17], v[34:37], off
	s_waitcnt lgkmcnt(0)

.LBB0_2620:
	v_mad_u64_u32 v[16:17], s[48:49], v18, s34, v[16:17]
	v_add_u32_e32 v18, 0x14a0, v33
	v_add_u32_e32 v33, 0x14a8, v33
	s_lshl_b32 s36, s36, 5
	s_lshl_b32 s10, s10, 1
	s_and_b32 s36, 0xffff, s36
	v_lshl_add_u64 v[42:43], v[10:11], 0, s[10:11]
	s_lshl_b32 s10, s36, 1
	s_and_b32 s36, s36, 0x60
	s_and_b32 s10, s10, 0x1f00
	s_or_b32 s10, s10, s36
	v_mov_b32_e32 v41, v1
	s_waitcnt vmcnt(0)
	v_pk_mul_f32 v[34:35], v[236:237], v[20:21] op_sel_hi:[1,0]
	v_pk_mul_f32 v[16:17], v[238:239], v[20:21] op_sel_hi:[1,0]
	ds_write2_b32 v18, v34, v35 offset1:1
	ds_write2_b32 v33, v16, v17 offset1:1
	s_waitcnt lgkmcnt(0)
	ds_read2_b32 v[212:213], v29 offset1:33
	ds_read2_b32 v[214:215], v29 offset0:66 offset1:99
	ds_read2_b32 v[216:217], v29 offset0:132 offset1:165
	ds_read2_b32 v[218:219], v29 offset0:198 offset1:231
	ds_read2_b32 v[220:221], v29 offset0:8 offset1:41
	ds_read2_b32 v[222:223], v29 offset0:74 offset1:107
	ds_read2_b32 v[224:225], v29 offset0:140 offset1:173
	ds_read2_b32 v[226:227], v29 offset0:206 offset1:239
	ds_read2_b32 v[228:229], v29 offset0:16 offset1:49
	ds_read2_b32 v[230:231], v29 offset0:82 offset1:115
	ds_read2_b32 v[232:233], v29 offset0:148 offset1:181
	ds_read2_b32 v[234:235], v29 offset0:214 offset1:247
	ds_read2_b32 v[236:237], v29 offset0:24 offset1:57
	ds_read2_b32 v[238:239], v29 offset0:90 offset1:123
	ds_read2_b32 v[240:241], v29 offset0:156 offset1:189
	ds_read2_b32 v[242:243], v29 offset0:222 offset1:255
	s_waitcnt lgkmcnt(0)
	v_cvt_pk_bf16_f32 v34, v212, v213
	s_waitcnt lgkmcnt(0)
	v_cvt_pk_bf16_f32 v35, v214, v215
	v_or_b32_e32 v18, s10, v9
	s_waitcnt lgkmcnt(0)
	v_cvt_pk_bf16_f32 v36, v216, v217
	v_lshlrev_b32_e32 v40, 11, v18
	s_waitcnt lgkmcnt(0)
	v_cvt_pk_bf16_f32 v37, v218, v219
	v_lshl_add_u64 v[40:41], v[42:43], 0, v[40:41]
	global_store_dwordx4 v[40:41], v[34:37], off
	v_or_b32_e32 v18, s10, v21
	v_mov_b32_e32 v41, v1
	s_waitcnt lgkmcnt(0)
	v_cvt_pk_bf16_f32 v34, v220, v221
	s_waitcnt lgkmcnt(0)
	v_cvt_pk_bf16_f32 v35, v222, v223
	s_waitcnt lgkmcnt(0)
	v_cvt_pk_bf16_f32 v36, v224, v225
	v_lshlrev_b32_e32 v40, 11, v18
	s_waitcnt lgkmcnt(0)
	v_cvt_pk_bf16_f32 v37, v226, v227
	v_lshl_add_u64 v[40:41], v[42:43], 0, v[40:41]
	global_store_dwordx4 v[40:41], v[34:37], off
	v_or_b32_e32 v18, s10, v22
	v_mov_b32_e32 v41, v1
	s_waitcnt lgkmcnt(0)
	v_cvt_pk_bf16_f32 v34, v228, v229
	s_waitcnt lgkmcnt(0)
	v_cvt_pk_bf16_f32 v35, v230, v231
	s_waitcnt lgkmcnt(0)
	v_cvt_pk_bf16_f32 v36, v232, v233
	v_lshlrev_b32_e32 v40, 11, v18
	s_waitcnt lgkmcnt(0)
	v_cvt_pk_bf16_f32 v37, v234, v235
	v_lshl_add_u64 v[40:41], v[42:43], 0, v[40:41]
	global_store_dwordx4 v[40:41], v[34:37], off
	v_or_b32_e32 v18, s10, v24
	v_mov_b32_e32 v41, v1
	s_waitcnt lgkmcnt(0)
	v_cvt_pk_bf16_f32 v34, v236, v237
	s_waitcnt lgkmcnt(0)
	v_cvt_pk_bf16_f32 v35, v238, v239
	s_waitcnt lgkmcnt(0)
	v_cvt_pk_bf16_f32 v36, v240, v241
	v_lshlrev_b32_e32 v40, 11, v18
	s_waitcnt lgkmcnt(0)
	v_cvt_pk_bf16_f32 v37, v242, v243
	v_lshl_add_u64 v[16:17], v[42:43], 0, v[40:41]
	global_store_dwordx4 v[16:17], v[34:37], off
	s_waitcnt lgkmcnt(0)

.LBB0_2638:
	v_mad_u64_u32 v[16:17], s[6:7], v18, s34, v[16:17]
	s_lshl_b32 s6, s36, 5
	s_and_b32 s6, 0xffff, s6
	s_lshl_b32 s7, s6, 1
	v_add_u32_e32 v18, 0x14a0, v33
	s_and_b32 s6, s6, 0x60
	s_and_b32 s7, s7, 0x1f00
	v_add_u32_e32 v33, 0x14a8, v33
	s_or_b32 s6, s7, s6
	s_lshl_b32 s10, s10, 1
	v_mov_b32_e32 v41, v1
	v_lshl_add_u64 v[42:43], v[10:11], 0, s[10:11]
	s_waitcnt vmcnt(0)
	v_pk_mul_f32 v[34:35], v[236:237], v[20:21] op_sel_hi:[1,0]
	v_pk_mul_f32 v[16:17], v[238:239], v[20:21] op_sel_hi:[1,0]
	ds_write2_b32 v18, v34, v35 offset1:1
	ds_write2_b32 v33, v16, v17 offset1:1
	s_waitcnt lgkmcnt(0)
	v_or_b32_e32 v18, s6, v9
	v_lshlrev_b32_e32 v40, 11, v18
	ds_read2_b32 v[212:213], v29 offset1:33
	ds_read2_b32 v[214:215], v29 offset0:66 offset1:99
	ds_read2_b32 v[216:217], v29 offset0:132 offset1:165
	ds_read2_b32 v[218:219], v29 offset0:198 offset1:231
	ds_read2_b32 v[220:221], v29 offset0:8 offset1:41
	ds_read2_b32 v[222:223], v29 offset0:74 offset1:107
	ds_read2_b32 v[224:225], v29 offset0:140 offset1:173
	ds_read2_b32 v[226:227], v29 offset0:206 offset1:239
	ds_read2_b32 v[228:229], v29 offset0:16 offset1:49
	ds_read2_b32 v[230:231], v29 offset0:82 offset1:115
	ds_read2_b32 v[232:233], v29 offset0:148 offset1:181
	ds_read2_b32 v[234:235], v29 offset0:214 offset1:247
	ds_read2_b32 v[236:237], v29 offset0:24 offset1:57
	ds_read2_b32 v[238:239], v29 offset0:90 offset1:123
	ds_read2_b32 v[240:241], v29 offset0:156 offset1:189
	ds_read2_b32 v[242:243], v29 offset0:222 offset1:255
	v_lshl_add_u64 v[40:41], v[42:43], 0, v[40:41]
	s_waitcnt lgkmcnt(0)
	v_cvt_pk_bf16_f32 v34, v212, v213
	v_add_co_u32_e32 v40, vcc, s35, v40
	s_waitcnt lgkmcnt(0)
	v_cvt_pk_bf16_f32 v35, v214, v215
	v_addc_co_u32_e32 v41, vcc, 0, v41, vcc
	v_or_b32_e32 v18, s6, v21
	s_waitcnt lgkmcnt(0)
	v_cvt_pk_bf16_f32 v36, v216, v217
	s_waitcnt lgkmcnt(0)
	v_cvt_pk_bf16_f32 v37, v218, v219
	global_store_dwordx4 v[40:41], v[34:37], off
	v_mov_b32_e32 v41, v1
	v_lshlrev_b32_e32 v40, 11, v18
	v_lshl_add_u64 v[40:41], v[42:43], 0, v[40:41]
	s_waitcnt lgkmcnt(0)
	v_cvt_pk_bf16_f32 v34, v220, v221
	v_add_co_u32_e32 v40, vcc, s35, v40
	s_waitcnt lgkmcnt(0)
	v_cvt_pk_bf16_f32 v35, v222, v223
	v_addc_co_u32_e32 v41, vcc, 0, v41, vcc
	v_or_b32_e32 v18, s6, v22
	s_waitcnt lgkmcnt(0)
	v_cvt_pk_bf16_f32 v36, v224, v225
	s_waitcnt lgkmcnt(0)
	v_cvt_pk_bf16_f32 v37, v226, v227
	global_store_dwordx4 v[40:41], v[34:37], off
	v_mov_b32_e32 v41, v1
	v_lshlrev_b32_e32 v40, 11, v18
	v_lshl_add_u64 v[40:41], v[42:43], 0, v[40:41]
	s_waitcnt lgkmcnt(0)
	v_cvt_pk_bf16_f32 v34, v228, v229
	v_add_co_u32_e32 v40, vcc, s35, v40
	s_waitcnt lgkmcnt(0)
	v_cvt_pk_bf16_f32 v35, v230, v231
	v_addc_co_u32_e32 v41, vcc, 0, v41, vcc
	v_or_b32_e32 v18, s6, v24
	s_waitcnt lgkmcnt(0)
	v_cvt_pk_bf16_f32 v36, v232, v233
	s_waitcnt lgkmcnt(0)
	v_cvt_pk_bf16_f32 v37, v234, v235
	global_store_dwordx4 v[40:41], v[34:37], off
	v_mov_b32_e32 v41, v1
	v_lshlrev_b32_e32 v40, 11, v18
	v_lshl_add_u64 v[40:41], v[42:43], 0, v[40:41]
	s_waitcnt lgkmcnt(0)
	v_cvt_pk_bf16_f32 v34, v236, v237
	v_add_co_u32_e32 v40, vcc, 0x40000, v40
	s_waitcnt lgkmcnt(0)
	v_cvt_pk_bf16_f32 v35, v238, v239
	v_addc_co_u32_e32 v41, vcc, 0, v41, vcc
	s_waitcnt lgkmcnt(0)
	v_cvt_pk_bf16_f32 v36, v240, v241
	s_waitcnt lgkmcnt(0)
	v_cvt_pk_bf16_f32 v37, v242, v243
	global_store_dwordx4 v[40:41], v[34:37], off
	s_waitcnt lgkmcnt(0)
.LBB0_2639:
	s_add_i32 s6, s2, 0xffffe900
	s_cmpk_gt_u32 s6, 0x57f
	v_add_u32_e32 v16, 0x420, v31
	v_add_u32_e32 v17, 0x428, v31
	v_add_u32_e32 v18, 0x840, v31
	v_add_u32_e32 v20, 0x848, v31
	v_add_u32_e32 v33, 0xc60, v31
	v_add_u32_e32 v34, 0xc68, v31
	v_add_u32_e32 v35, 0x1080, v31
	v_add_u32_e32 v36, 0x1088, v31
	v_add_u32_e32 v37, 0x14a0, v31
	v_add_u32_e32 v40, 0x14a8, v31
	v_add_u32_e32 v41, 0x18c0, v31
	v_add_u32_e32 v42, 0x18c8, v31
	v_add_u32_e32 v43, 0x1ce0, v31
	v_add_u32_e32 v44, 0x1ce8, v31
	s_cbranch_scc1 .LBB0_2641
	s_load_dwordx2 s[36:37], s[44:45], 0x138
	s_add_i32 s6, s26, 0xfffde200
	s_and_b32 s7, s6, 0xfc0
	s_lshl_b32 s6, s2, 5
	s_and_b32 s6, s6, 0x3e0
	s_lshl_b32 s10, s6, 2
	s_waitcnt lgkmcnt(0)
	s_add_u32 s36, s36, s10
	s_addc_u32 s37, s37, 0
	v_lshl_add_u64 v[46:47], s[36:37], 0, v[0:1]
	v_or_b32_e32 v45, s7, v9
	v_lshl_add_u64 v[62:63], v[46:47], 0, s[22:23]
	v_lshlrev_b32_e32 v46, 12, v45
	v_or_b32_e32 v45, s7, v21
	v_lshlrev_b32_e32 v48, 12, v45
	v_or_b32_e32 v45, s7, v22
	v_lshlrev_b32_e32 v54, 12, v45
	v_or_b32_e32 v45, s7, v24
	v_lshlrev_b32_e32 v56, 12, v45
	v_or_b32_e32 v45, s7, v25
	v_lshlrev_b32_e32 v68, 12, v45
	v_or_b32_e32 v45, s7, v26
	v_mov_b32_e32 v47, v1
	v_mov_b32_e32 v49, v1
	v_mov_b32_e32 v55, v1
	v_mov_b32_e32 v57, v1
	v_mov_b32_e32 v69, v1
	v_lshlrev_b32_e32 v70, 12, v45
	v_mov_b32_e32 v71, v1
	v_lshl_add_u64 v[46:47], v[62:63], 0, v[46:47]
	v_lshl_add_u64 v[50:51], v[62:63], 0, v[48:49]
	v_lshl_add_u64 v[54:55], v[62:63], 0, v[54:55]
	v_lshl_add_u64 v[58:59], v[62:63], 0, v[56:57]
	v_lshl_add_u64 v[68:69], v[62:63], 0, v[68:69]
	v_lshl_add_u64 v[72:73], v[62:63], 0, v[70:71]
	global_load_dwordx4 v[46:49], v[46:47], off
	s_nop 0
	global_load_dwordx4 v[50:53], v[50:51], off
	s_nop 0
	global_load_dwordx4 v[54:57], v[54:55], off
	s_nop 0
	global_load_dwordx4 v[58:61], v[58:59], off
	s_nop 0
	global_load_dwordx4 v[68:71], v[68:69], off
	s_nop 0
	global_load_dwordx4 v[72:75], v[72:73], off
	v_or_b32_e32 v45, s7, v27
	v_lshlrev_b32_e32 v76, 12, v45
	v_mov_b32_e32 v77, v1
	v_lshl_add_u64 v[76:77], v[62:63], 0, v[76:77]
	v_or_b32_e32 v45, s7, v28
	global_load_dwordx4 v[76:79], v[76:77], off
	v_lshlrev_b32_e32 v80, 12, v45
	v_mov_b32_e32 v81, v1
	v_lshl_add_u64 v[62:63], v[62:63], 0, v[80:81]
	global_load_dwordx4 v[80:83], v[62:63], off
	v_or_b32_e32 v45, s6, v9
	s_lshl_b32 s10, s7, 1
	s_waitcnt vmcnt(7)
	ds_write2_b32 v31, v46, v47 offset1:1
	ds_write2_b32 v31, v48, v49 offset0:2 offset1:3
	s_waitcnt vmcnt(6)
	ds_write2_b32 v16, v50, v51 offset1:1
	ds_write2_b32 v17, v52, v53 offset1:1
	s_waitcnt vmcnt(5)
	ds_write2_b32 v18, v54, v55 offset1:1
	ds_write2_b32 v20, v56, v57 offset1:1
	s_waitcnt vmcnt(4)
	ds_write2_b32 v33, v58, v59 offset1:1
	ds_write2_b32 v34, v60, v61 offset1:1
	s_waitcnt vmcnt(3)
	ds_write2_b32 v35, v68, v69 offset1:1
	ds_write2_b32 v36, v70, v71 offset1:1
	s_waitcnt vmcnt(2)
	ds_write2_b32 v37, v72, v73 offset1:1
	ds_write2_b32 v40, v74, v75 offset1:1
	s_waitcnt vmcnt(1)
	ds_write2_b32 v41, v76, v77 offset1:1
	ds_write2_b32 v42, v78, v79 offset1:1
	s_waitcnt vmcnt(0)
	ds_write2_b32 v43, v80, v81 offset1:1
	ds_write2_b32 v44, v82, v83 offset1:1
	s_waitcnt lgkmcnt(0)
	ds_read2_b32 v[212:213], v29 offset1:33
	ds_read2_b32 v[214:215], v29 offset0:66 offset1:99
	ds_read2_b32 v[216:217], v29 offset0:132 offset1:165
	ds_read2_b32 v[218:219], v29 offset0:198 offset1:231
	ds_read2_b32 v[220:221], v29 offset0:8 offset1:41
	ds_read2_b32 v[222:223], v29 offset0:74 offset1:107
	ds_read2_b32 v[224:225], v29 offset0:140 offset1:173
	ds_read2_b32 v[226:227], v29 offset0:206 offset1:239
	ds_read2_b32 v[228:229], v29 offset0:16 offset1:49
	ds_read2_b32 v[230:231], v29 offset0:82 offset1:115
	ds_read2_b32 v[232:233], v29 offset0:148 offset1:181
	ds_read2_b32 v[234:235], v29 offset0:214 offset1:247
	ds_read2_b32 v[236:237], v29 offset0:24 offset1:57
	ds_read2_b32 v[238:239], v29 offset0:90 offset1:123
	ds_read2_b32 v[240:241], v29 offset0:156 offset1:189
	ds_read2_b32 v[242:243], v29 offset0:222 offset1:255
	s_waitcnt lgkmcnt(0)
	v_cvt_pk_bf16_f32 v46, v212, v213
	s_waitcnt lgkmcnt(0)
	v_cvt_pk_bf16_f32 v47, v214, v215
	v_mov_b32_e32 v53, v1
	v_mul_u32_u24_e32 v52, 0x1600, v45
	v_lshl_add_u64 v[54:55], v[12:13], 0, s[10:11]
	s_waitcnt lgkmcnt(0)
	v_cvt_pk_bf16_f32 v48, v216, v217
	s_waitcnt lgkmcnt(0)
	v_cvt_pk_bf16_f32 v49, v218, v219
	v_lshl_add_u64 v[52:53], v[54:55], 0, v[52:53]
	global_store_dwordx4 v[52:53], v[46:49], off
	v_or_b32_e32 v45, s6, v21
	v_mov_b32_e32 v53, v1
	s_waitcnt lgkmcnt(0)
	v_cvt_pk_bf16_f32 v46, v220, v221
	s_waitcnt lgkmcnt(0)
	v_cvt_pk_bf16_f32 v47, v222, v223
	v_mul_u32_u24_e32 v52, 0x1600, v45
	s_waitcnt lgkmcnt(0)
	v_cvt_pk_bf16_f32 v48, v224, v225
	s_waitcnt lgkmcnt(0)
	v_cvt_pk_bf16_f32 v49, v226, v227
	v_lshl_add_u64 v[52:53], v[54:55], 0, v[52:53]
	global_store_dwordx4 v[52:53], v[46:49], off
	v_or_b32_e32 v45, s6, v22
	v_mov_b32_e32 v53, v1
	s_waitcnt lgkmcnt(0)
	v_cvt_pk_bf16_f32 v46, v228, v229
	s_waitcnt lgkmcnt(0)
	v_cvt_pk_bf16_f32 v47, v230, v231
	v_mul_u32_u24_e32 v52, 0x1600, v45
	s_waitcnt lgkmcnt(0)
	v_cvt_pk_bf16_f32 v48, v232, v233
	s_waitcnt lgkmcnt(0)
	v_cvt_pk_bf16_f32 v49, v234, v235
	v_lshl_add_u64 v[52:53], v[54:55], 0, v[52:53]
	global_store_dwordx4 v[52:53], v[46:49], off
	v_or_b32_e32 v45, s6, v24
	v_mov_b32_e32 v53, v1
	s_waitcnt lgkmcnt(0)
	v_cvt_pk_bf16_f32 v46, v236, v237
	s_waitcnt lgkmcnt(0)
	v_cvt_pk_bf16_f32 v47, v238, v239
	s_waitcnt lgkmcnt(0)
	v_cvt_pk_bf16_f32 v48, v240, v241
	v_mul_u32_u24_e32 v52, 0x1600, v45
	s_waitcnt lgkmcnt(0)
	v_cvt_pk_bf16_f32 v49, v242, v243
	v_lshl_add_u64 v[50:51], v[54:55], 0, v[52:53]
	global_store_dwordx4 v[50:51], v[46:49], off
	s_waitcnt lgkmcnt(0)
.LBB0_2641:
	s_and_b32 s6, s2, 0xffffffe0
	s_cmpk_lg_i32 s6, 0x1c80
	s_cbranch_scc1 .LBB0_2577
	s_load_dwordx2 s[36:37], s[44:45], 0x78
	s_lshl_b32 s6, s2, 5
	s_and_b32 s6, s6, 0xe0
	s_and_b32 s7, s28, 0xc0
	s_lshl_b32 s10, s6, 2
	s_waitcnt lgkmcnt(0)
	s_add_u32 s36, s36, s10
	s_addc_u32 s37, s37, 0
	v_lshl_add_u64 v[46:47], s[36:37], 0, v[0:1]
	v_or_b32_e32 v45, s7, v9
	v_lshl_add_u64 v[62:63], v[46:47], 0, s[24:25]
	v_lshlrev_b32_e32 v46, 10, v45
	v_or_b32_e32 v45, s7, v21
	v_lshlrev_b32_e32 v48, 10, v45
	v_or_b32_e32 v45, s7, v22
	v_lshlrev_b32_e32 v54, 10, v45
	v_or_b32_e32 v45, s7, v24
	v_lshlrev_b32_e32 v56, 10, v45
	v_or_b32_e32 v45, s7, v25
	v_lshlrev_b32_e32 v68, 10, v45
	v_or_b32_e32 v45, s7, v26
	v_mov_b32_e32 v47, v1
	v_mov_b32_e32 v49, v1
	v_mov_b32_e32 v55, v1
	v_mov_b32_e32 v57, v1
	v_mov_b32_e32 v69, v1
	v_lshlrev_b32_e32 v70, 10, v45
	v_mov_b32_e32 v71, v1
	v_lshl_add_u64 v[46:47], v[62:63], 0, v[46:47]
	v_lshl_add_u64 v[50:51], v[62:63], 0, v[48:49]
	v_lshl_add_u64 v[54:55], v[62:63], 0, v[54:55]
	v_lshl_add_u64 v[58:59], v[62:63], 0, v[56:57]
	v_lshl_add_u64 v[68:69], v[62:63], 0, v[68:69]
	v_lshl_add_u64 v[72:73], v[62:63], 0, v[70:71]
	global_load_dwordx4 v[46:49], v[46:47], off
	s_nop 0
	global_load_dwordx4 v[50:53], v[50:51], off
	s_nop 0
	global_load_dwordx4 v[54:57], v[54:55], off
	s_nop 0
	global_load_dwordx4 v[58:61], v[58:59], off
	s_nop 0
	global_load_dwordx4 v[68:71], v[68:69], off
	s_nop 0
	global_load_dwordx4 v[72:75], v[72:73], off
	v_or_b32_e32 v45, s7, v27
	v_lshlrev_b32_e32 v76, 10, v45
	v_mov_b32_e32 v77, v1
	v_lshl_add_u64 v[76:77], v[62:63], 0, v[76:77]
	v_or_b32_e32 v45, s7, v28
	global_load_dwordx4 v[76:79], v[76:77], off
	v_lshlrev_b32_e32 v80, 10, v45
	v_mov_b32_e32 v81, v1
	v_lshl_add_u64 v[62:63], v[62:63], 0, v[80:81]
	global_load_dwordx4 v[80:83], v[62:63], off
	s_lshl_b32 s10, s7, 1
	s_waitcnt vmcnt(7)
	ds_write2_b32 v31, v46, v47 offset1:1
	ds_write2_b32 v31, v48, v49 offset0:2 offset1:3
	s_waitcnt vmcnt(6)
	ds_write2_b32 v16, v50, v51 offset1:1
	ds_write2_b32 v17, v52, v53 offset1:1
	s_waitcnt vmcnt(5)
	ds_write2_b32 v18, v54, v55 offset1:1
	ds_write2_b32 v20, v56, v57 offset1:1
	s_waitcnt vmcnt(4)
	ds_write2_b32 v33, v58, v59 offset1:1
	ds_write2_b32 v34, v60, v61 offset1:1
	s_waitcnt vmcnt(3)
	ds_write2_b32 v35, v68, v69 offset1:1
	ds_write2_b32 v36, v70, v71 offset1:1
	s_waitcnt vmcnt(2)
	ds_write2_b32 v37, v72, v73 offset1:1
	ds_write2_b32 v40, v74, v75 offset1:1
	s_waitcnt vmcnt(1)
	ds_write2_b32 v41, v76, v77 offset1:1
	ds_write2_b32 v42, v78, v79 offset1:1
	s_waitcnt vmcnt(0)
	ds_write2_b32 v43, v80, v81 offset1:1
	ds_write2_b32 v44, v82, v83 offset1:1
	s_waitcnt lgkmcnt(0)
	ds_read2_b32 v[212:213], v29 offset1:33
	ds_read2_b32 v[214:215], v29 offset0:66 offset1:99
	ds_read2_b32 v[216:217], v29 offset0:132 offset1:165
	ds_read2_b32 v[218:219], v29 offset0:198 offset1:231
	ds_read2_b32 v[220:221], v29 offset0:8 offset1:41
	ds_read2_b32 v[222:223], v29 offset0:74 offset1:107
	ds_read2_b32 v[224:225], v29 offset0:140 offset1:173
	ds_read2_b32 v[226:227], v29 offset0:206 offset1:239
	ds_read2_b32 v[228:229], v29 offset0:16 offset1:49
	ds_read2_b32 v[230:231], v29 offset0:82 offset1:115
	ds_read2_b32 v[232:233], v29 offset0:148 offset1:181
	ds_read2_b32 v[234:235], v29 offset0:214 offset1:247
	ds_read2_b32 v[236:237], v29 offset0:24 offset1:57
	ds_read2_b32 v[238:239], v29 offset0:90 offset1:123
	ds_read2_b32 v[240:241], v29 offset0:156 offset1:189
	ds_read2_b32 v[242:243], v29 offset0:222 offset1:255
	s_waitcnt lgkmcnt(0)
	v_cvt_pk_bf16_f32 v34, v212, v213
	s_waitcnt lgkmcnt(0)
	v_cvt_pk_bf16_f32 v35, v214, v215
	v_or_b32_e32 v18, s6, v9
	s_waitcnt lgkmcnt(0)
	v_cvt_pk_bf16_f32 v36, v216, v217
	v_mov_b32_e32 v41, v1
	v_lshlrev_b32_e32 v40, 9, v18
	v_lshl_add_u64 v[42:43], v[14:15], 0, s[10:11]
	s_waitcnt lgkmcnt(0)
	v_cvt_pk_bf16_f32 v37, v218, v219
	v_lshl_add_u64 v[40:41], v[42:43], 0, v[40:41]
	global_store_dwordx4 v[40:41], v[34:37], off
	v_or_b32_e32 v18, s6, v21
	v_mov_b32_e32 v41, v1
	s_waitcnt lgkmcnt(0)
	v_cvt_pk_bf16_f32 v34, v220, v221
	s_waitcnt lgkmcnt(0)
	v_cvt_pk_bf16_f32 v35, v222, v223
	s_waitcnt lgkmcnt(0)
	v_cvt_pk_bf16_f32 v36, v224, v225
	v_lshlrev_b32_e32 v40, 9, v18
	s_waitcnt lgkmcnt(0)
	v_cvt_pk_bf16_f32 v37, v226, v227
	v_lshl_add_u64 v[40:41], v[42:43], 0, v[40:41]
	global_store_dwordx4 v[40:41], v[34:37], off
	v_or_b32_e32 v18, s6, v22
	v_mov_b32_e32 v41, v1
	s_waitcnt lgkmcnt(0)
	v_cvt_pk_bf16_f32 v34, v228, v229
	s_waitcnt lgkmcnt(0)
	v_cvt_pk_bf16_f32 v35, v230, v231
	s_waitcnt lgkmcnt(0)
	v_cvt_pk_bf16_f32 v36, v232, v233
	v_lshlrev_b32_e32 v40, 9, v18
	s_waitcnt lgkmcnt(0)
	v_cvt_pk_bf16_f32 v37, v234, v235
	v_lshl_add_u64 v[40:41], v[42:43], 0, v[40:41]
	global_store_dwordx4 v[40:41], v[34:37], off
	v_or_b32_e32 v18, s6, v24
	v_mov_b32_e32 v41, v1
	s_waitcnt lgkmcnt(0)
	v_cvt_pk_bf16_f32 v34, v236, v237
	s_waitcnt lgkmcnt(0)
	v_cvt_pk_bf16_f32 v35, v238, v239
	s_waitcnt lgkmcnt(0)
	v_cvt_pk_bf16_f32 v36, v240, v241
	v_lshlrev_b32_e32 v40, 9, v18
	s_waitcnt lgkmcnt(0)
	v_cvt_pk_bf16_f32 v37, v242, v243
	v_lshl_add_u64 v[16:17], v[42:43], 0, v[40:41]
	global_store_dwordx4 v[16:17], v[34:37], off
	s_waitcnt lgkmcnt(0)
	s_branch .LBB0_2577
